# adaLN modulation GEMV k loop rewritten: 4-deep nontemporal row prefetch with counted vmcnt, LDS operands of a step read up front (phase 0 and background queue copies)
# speedup vs baseline: 1.0724x; 1.0147x over previous
; __device__ __forceinline__ float4 ld_nt4(const float* p) { const f32x4v v = __builtin_nontemporal_load((const f32x4v*)p); return make_float4(v[0], v[1], v[2], v[3]); }
; DI void p0_mod_item(const Params& P, unsigned char* lds, int idx, const int tid) {
;     ...
;   const float* W = P.w_ada + ((size_t)l * 1024 + wave * 128) * NMOD + cch * 256 + lane * 4;
;   for (int k4 = 0; k4 < 32; ++k4) {
;     float4 w0 = ld_nt4(W + (size_t)(k4 * 4 + 0) * NMOD);
;     float4 w1 = ld_nt4(W + (size_t)(k4 * 4 + 1) * NMOD);
;     float4 w2 = ld_nt4(W + (size_t)(k4 * 4 + 2) * NMOD);
;     float4 w3 = ld_nt4(W + (size_t)(k4 * 4 + 3) * NMOD);
; #pragma unroll
;     for (int r = 0; r < 9; ++r) {
;       float4 s4 = *(const float4*)(sl + r * 1024 + wave * 128 + k4 * 4);
;       acc[r].x += s4.x * w0.x + s4.y * w1.x + s4.z * w2.x + s4.w * w3.x;
;       acc[r].y += s4.x * w0.y + s4.y * w1.y + s4.z * w2.y + s4.w * w3.y;
;       acc[r].z += s4.x * w0.z + s4.y * w1.z + s4.z * w2.z + s4.w * w3.z;
;       acc[r].w += s4.x * w0.w + s4.y * w1.w + s4.z * w2.w + s4.w * w3.w;
;     }
.LBB0_1081:
	v_mov_b32_e32 v150, v58
	v_mov_b32_e32 v151, v59
	v_mov_b32_e32 v152, v57
	s_mov_b32 s4, 0x9000
	s_mov_b32 s5, 0
	v_mov_b32_e32 v67, 0
	global_load_dwordx4 v[38:41], v[150:151], off nt
	v_lshl_add_u64 v[150:151], v[150:151], 0, s[4:5]
	global_load_dwordx4 v[42:45], v[150:151], off nt
	v_lshl_add_u64 v[150:151], v[150:151], 0, s[4:5]
	global_load_dwordx4 v[46:49], v[150:151], off nt
	v_lshl_add_u64 v[150:151], v[150:151], 0, s[4:5]
	global_load_dwordx4 v[50:53], v[150:151], off nt
	v_lshl_add_u64 v[150:151], v[150:151], 0, s[4:5]
	global_load_dwordx4 v[160:163], v[150:151], off nt
	v_lshl_add_u64 v[150:151], v[150:151], 0, s[4:5]
	global_load_dwordx4 v[164:167], v[150:151], off nt
	v_lshl_add_u64 v[150:151], v[150:151], 0, s[4:5]
	global_load_dwordx4 v[168:171], v[150:151], off nt
	v_lshl_add_u64 v[150:151], v[150:151], 0, s[4:5]
	global_load_dwordx4 v[172:175], v[150:151], off nt
	v_lshl_add_u64 v[150:151], v[150:151], 0, s[4:5]
	global_load_dwordx4 v[176:179], v[150:151], off nt
	v_lshl_add_u64 v[150:151], v[150:151], 0, s[4:5]
	global_load_dwordx4 v[180:183], v[150:151], off nt
	v_lshl_add_u64 v[150:151], v[150:151], 0, s[4:5]
	global_load_dwordx4 v[184:187], v[150:151], off nt
	v_lshl_add_u64 v[150:151], v[150:151], 0, s[4:5]
	global_load_dwordx4 v[188:191], v[150:151], off nt
	v_lshl_add_u64 v[150:151], v[150:151], 0, s[4:5]
	global_load_dwordx4 v[192:195], v[150:151], off nt
	v_lshl_add_u64 v[150:151], v[150:151], 0, s[4:5]
	global_load_dwordx4 v[196:199], v[150:151], off nt
	v_lshl_add_u64 v[150:151], v[150:151], 0, s[4:5]
	global_load_dwordx4 v[200:203], v[150:151], off nt
	v_lshl_add_u64 v[150:151], v[150:151], 0, s[4:5]
	global_load_dwordx4 v[204:207], v[150:151], off nt
	v_lshl_add_u64 v[150:151], v[150:151], 0, s[4:5]
	s_mov_b32 s100, 0
.Lmod_b_trip:
	ds_read_b128 v[114:117], v152
	ds_read_b128 v[118:121], v152 offset:4096
	ds_read_b128 v[122:125], v152 offset:8192
	ds_read_b128 v[126:129], v152 offset:12288
	ds_read_b128 v[130:133], v152 offset:16384
	ds_read_b128 v[134:137], v152 offset:20480
	ds_read_b128 v[138:141], v152 offset:24576
	ds_read_b128 v[142:145], v152 offset:28672
	ds_read_b128 v[146:149], v152 offset:32768
	s_waitcnt vmcnt(12)
	s_waitcnt lgkmcnt(8)
	v_mov_b32_e32 v66, v117
	v_pk_mul_f32 v[60:61], v[42:43], v[114:115] op_sel:[0,1]
	v_pk_mul_f32 v[62:63], v[44:45], v[114:115] op_sel:[0,1]
	v_pk_fma_f32 v[60:61], v[38:39], v[114:115], v[60:61] op_sel_hi:[1,0,1]
	v_pk_fma_f32 v[62:63], v[40:41], v[114:115], v[62:63] op_sel_hi:[1,0,1]
	v_pk_fma_f32 v[60:61], v[46:47], v[116:117], v[60:61] op_sel_hi:[1,0,1]
	v_pk_fma_f32 v[62:63], v[48:49], v[116:117], v[62:63] op_sel_hi:[1,0,1]
	v_pk_fma_f32 v[60:61], v[50:51], v[66:67], v[60:61] op_sel_hi:[1,0,1]
	v_pk_fma_f32 v[62:63], v[52:53], v[66:67], v[62:63] op_sel_hi:[1,0,1]
	v_pk_add_f32 v[22:23], v[22:23], v[60:61]
	v_pk_add_f32 v[24:25], v[24:25], v[62:63]
	s_waitcnt lgkmcnt(7)
	v_mov_b32_e32 v66, v121
	v_pk_mul_f32 v[60:61], v[42:43], v[118:119] op_sel:[0,1]
	v_pk_mul_f32 v[62:63], v[44:45], v[118:119] op_sel:[0,1]
	v_pk_fma_f32 v[60:61], v[38:39], v[118:119], v[60:61] op_sel_hi:[1,0,1]
	v_pk_fma_f32 v[62:63], v[40:41], v[118:119], v[62:63] op_sel_hi:[1,0,1]
	v_pk_fma_f32 v[60:61], v[46:47], v[120:121], v[60:61] op_sel_hi:[1,0,1]
	v_pk_fma_f32 v[62:63], v[48:49], v[120:121], v[62:63] op_sel_hi:[1,0,1]
	v_pk_fma_f32 v[60:61], v[50:51], v[66:67], v[60:61] op_sel_hi:[1,0,1]
	v_pk_fma_f32 v[62:63], v[52:53], v[66:67], v[62:63] op_sel_hi:[1,0,1]
	v_pk_add_f32 v[34:35], v[34:35], v[60:61]
	v_pk_add_f32 v[36:37], v[36:37], v[62:63]
	s_waitcnt lgkmcnt(6)
	v_mov_b32_e32 v66, v125
	v_pk_mul_f32 v[60:61], v[42:43], v[122:123] op_sel:[0,1]
	v_pk_mul_f32 v[62:63], v[44:45], v[122:123] op_sel:[0,1]
	v_pk_fma_f32 v[60:61], v[38:39], v[122:123], v[60:61] op_sel_hi:[1,0,1]
	v_pk_fma_f32 v[62:63], v[40:41], v[122:123], v[62:63] op_sel_hi:[1,0,1]
	v_pk_fma_f32 v[60:61], v[46:47], v[124:125], v[60:61] op_sel_hi:[1,0,1]
	v_pk_fma_f32 v[62:63], v[48:49], v[124:125], v[62:63] op_sel_hi:[1,0,1]
	v_pk_fma_f32 v[60:61], v[50:51], v[66:67], v[60:61] op_sel_hi:[1,0,1]
	v_pk_fma_f32 v[62:63], v[52:53], v[66:67], v[62:63] op_sel_hi:[1,0,1]
	v_pk_add_f32 v[30:31], v[30:31], v[60:61]
	v_pk_add_f32 v[32:33], v[32:33], v[62:63]
	s_waitcnt lgkmcnt(5)
	v_mov_b32_e32 v66, v129
	v_pk_mul_f32 v[60:61], v[42:43], v[126:127] op_sel:[0,1]
	v_pk_mul_f32 v[62:63], v[44:45], v[126:127] op_sel:[0,1]
	v_pk_fma_f32 v[60:61], v[38:39], v[126:127], v[60:61] op_sel_hi:[1,0,1]
	v_pk_fma_f32 v[62:63], v[40:41], v[126:127], v[62:63] op_sel_hi:[1,0,1]
	v_pk_fma_f32 v[60:61], v[46:47], v[128:129], v[60:61] op_sel_hi:[1,0,1]
	v_pk_fma_f32 v[62:63], v[48:49], v[128:129], v[62:63] op_sel_hi:[1,0,1]
	v_pk_fma_f32 v[60:61], v[50:51], v[66:67], v[60:61] op_sel_hi:[1,0,1]
	v_pk_fma_f32 v[62:63], v[52:53], v[66:67], v[62:63] op_sel_hi:[1,0,1]
	v_pk_add_f32 v[26:27], v[26:27], v[60:61]
	v_pk_add_f32 v[28:29], v[28:29], v[62:63]
	s_waitcnt lgkmcnt(4)
	v_mov_b32_e32 v66, v133
	v_pk_mul_f32 v[60:61], v[42:43], v[130:131] op_sel:[0,1]
	v_pk_mul_f32 v[62:63], v[44:45], v[130:131] op_sel:[0,1]
	v_pk_fma_f32 v[60:61], v[38:39], v[130:131], v[60:61] op_sel_hi:[1,0,1]
	v_pk_fma_f32 v[62:63], v[40:41], v[130:131], v[62:63] op_sel_hi:[1,0,1]
	v_pk_fma_f32 v[60:61], v[46:47], v[132:133], v[60:61] op_sel_hi:[1,0,1]
	v_pk_fma_f32 v[62:63], v[48:49], v[132:133], v[62:63] op_sel_hi:[1,0,1]
	v_pk_fma_f32 v[60:61], v[50:51], v[66:67], v[60:61] op_sel_hi:[1,0,1]
	v_pk_fma_f32 v[62:63], v[52:53], v[66:67], v[62:63] op_sel_hi:[1,0,1]
	v_pk_add_f32 v[18:19], v[18:19], v[60:61]
	v_pk_add_f32 v[20:21], v[20:21], v[62:63]
	s_waitcnt lgkmcnt(3)
; __device__ __forceinline__ float4 ld_nt4(const float* p) { const f32x4v v = __builtin_nontemporal_load((const f32x4v*)p); return make_float4(v[0], v[1], v[2], v[3]); }
; DI void p0_mod_item(const Params& P, unsigned char* lds, int idx, const int tid) {
;     ...
;   for (int k4 = 0; k4 < 32; ++k4) {
;     float4 w0 = ld_nt4(W + (size_t)(k4 * 4 + 0) * NMOD);
;     float4 w1 = ld_nt4(W + (size_t)(k4 * 4 + 1) * NMOD);
;     float4 w2 = ld_nt4(W + (size_t)(k4 * 4 + 2) * NMOD);
;     float4 w3 = ld_nt4(W + (size_t)(k4 * 4 + 3) * NMOD);
; #pragma unroll
;     for (int r = 0; r < 9; ++r) {
;       float4 s4 = *(const float4*)(sl + r * 1024 + wave * 128 + k4 * 4);
;       acc[r].x += s4.x * w0.x + s4.y * w1.x + s4.z * w2.x + s4.w * w3.x;
;       acc[r].y += s4.x * w0.y + s4.y * w1.y + s4.z * w2.y + s4.w * w3.y;
;       acc[r].z += s4.x * w0.z + s4.y * w1.z + s4.z * w2.z + s4.w * w3.z;
;       acc[r].w += s4.x * w0.w + s4.y * w1.w + s4.z * w2.w + s4.w * w3.w;
;     }
	v_mov_b32_e32 v66, v137
	v_pk_mul_f32 v[60:61], v[42:43], v[134:135] op_sel:[0,1]
	v_pk_mul_f32 v[62:63], v[44:45], v[134:135] op_sel:[0,1]
	v_pk_fma_f32 v[60:61], v[38:39], v[134:135], v[60:61] op_sel_hi:[1,0,1]
	v_pk_fma_f32 v[62:63], v[40:41], v[134:135], v[62:63] op_sel_hi:[1,0,1]
	v_pk_fma_f32 v[60:61], v[46:47], v[136:137], v[60:61] op_sel_hi:[1,0,1]
	v_pk_fma_f32 v[62:63], v[48:49], v[136:137], v[62:63] op_sel_hi:[1,0,1]
	v_pk_fma_f32 v[60:61], v[50:51], v[66:67], v[60:61] op_sel_hi:[1,0,1]
	v_pk_fma_f32 v[62:63], v[52:53], v[66:67], v[62:63] op_sel_hi:[1,0,1]
	v_pk_add_f32 v[14:15], v[14:15], v[60:61]
	v_pk_add_f32 v[16:17], v[16:17], v[62:63]
	s_waitcnt lgkmcnt(2)
	v_mov_b32_e32 v66, v141
	v_pk_mul_f32 v[60:61], v[42:43], v[138:139] op_sel:[0,1]
	v_pk_mul_f32 v[62:63], v[44:45], v[138:139] op_sel:[0,1]
	v_pk_fma_f32 v[60:61], v[38:39], v[138:139], v[60:61] op_sel_hi:[1,0,1]
	v_pk_fma_f32 v[62:63], v[40:41], v[138:139], v[62:63] op_sel_hi:[1,0,1]
	v_pk_fma_f32 v[60:61], v[46:47], v[140:141], v[60:61] op_sel_hi:[1,0,1]
	v_pk_fma_f32 v[62:63], v[48:49], v[140:141], v[62:63] op_sel_hi:[1,0,1]
	v_pk_fma_f32 v[60:61], v[50:51], v[66:67], v[60:61] op_sel_hi:[1,0,1]
	v_pk_fma_f32 v[62:63], v[52:53], v[66:67], v[62:63] op_sel_hi:[1,0,1]
	v_pk_add_f32 v[10:11], v[10:11], v[60:61]
	v_pk_add_f32 v[12:13], v[12:13], v[62:63]
	s_waitcnt lgkmcnt(1)
	v_mov_b32_e32 v66, v145
	v_pk_mul_f32 v[60:61], v[42:43], v[142:143] op_sel:[0,1]
	v_pk_mul_f32 v[62:63], v[44:45], v[142:143] op_sel:[0,1]
	v_pk_fma_f32 v[60:61], v[38:39], v[142:143], v[60:61] op_sel_hi:[1,0,1]
	v_pk_fma_f32 v[62:63], v[40:41], v[142:143], v[62:63] op_sel_hi:[1,0,1]
	v_pk_fma_f32 v[60:61], v[46:47], v[144:145], v[60:61] op_sel_hi:[1,0,1]
	v_pk_fma_f32 v[62:63], v[48:49], v[144:145], v[62:63] op_sel_hi:[1,0,1]
	v_pk_fma_f32 v[60:61], v[50:51], v[66:67], v[60:61] op_sel_hi:[1,0,1]
	v_pk_fma_f32 v[62:63], v[52:53], v[66:67], v[62:63] op_sel_hi:[1,0,1]
	v_pk_add_f32 v[6:7], v[6:7], v[60:61]
	v_pk_add_f32 v[8:9], v[8:9], v[62:63]
	s_waitcnt lgkmcnt(0)
	v_mov_b32_e32 v66, v149
	v_pk_mul_f32 v[60:61], v[42:43], v[146:147] op_sel:[0,1]
	v_pk_mul_f32 v[62:63], v[44:45], v[146:147] op_sel:[0,1]
	v_pk_fma_f32 v[60:61], v[38:39], v[146:147], v[60:61] op_sel_hi:[1,0,1]
	v_pk_fma_f32 v[62:63], v[40:41], v[146:147], v[62:63] op_sel_hi:[1,0,1]
	v_pk_fma_f32 v[60:61], v[46:47], v[148:149], v[60:61] op_sel_hi:[1,0,1]
	v_pk_fma_f32 v[62:63], v[48:49], v[148:149], v[62:63] op_sel_hi:[1,0,1]
	v_pk_fma_f32 v[60:61], v[50:51], v[66:67], v[60:61] op_sel_hi:[1,0,1]
	v_pk_fma_f32 v[62:63], v[52:53], v[66:67], v[62:63] op_sel_hi:[1,0,1]
	v_pk_add_f32 v[2:3], v[2:3], v[60:61]
	v_pk_add_f32 v[4:5], v[4:5], v[62:63]
	global_load_dwordx4 v[38:41], v[150:151], off nt
	v_lshl_add_u64 v[150:151], v[150:151], 0, s[4:5]
	global_load_dwordx4 v[42:45], v[150:151], off nt
	v_lshl_add_u64 v[150:151], v[150:151], 0, s[4:5]
	global_load_dwordx4 v[46:49], v[150:151], off nt
	v_lshl_add_u64 v[150:151], v[150:151], 0, s[4:5]
	global_load_dwordx4 v[50:53], v[150:151], off nt
	v_lshl_add_u64 v[150:151], v[150:151], 0, s[4:5]
	ds_read_b128 v[114:117], v152 offset:16
	ds_read_b128 v[118:121], v152 offset:4112
	ds_read_b128 v[122:125], v152 offset:8208
	ds_read_b128 v[126:129], v152 offset:12304
	ds_read_b128 v[130:133], v152 offset:16400
	ds_read_b128 v[134:137], v152 offset:20496
	ds_read_b128 v[138:141], v152 offset:24592
	ds_read_b128 v[142:145], v152 offset:28688
	ds_read_b128 v[146:149], v152 offset:32784
	s_waitcnt vmcnt(12)
	s_waitcnt lgkmcnt(8)
	v_mov_b32_e32 v66, v117
	v_pk_mul_f32 v[60:61], v[164:165], v[114:115] op_sel:[0,1]
	v_pk_mul_f32 v[62:63], v[166:167], v[114:115] op_sel:[0,1]
	v_pk_fma_f32 v[60:61], v[160:161], v[114:115], v[60:61] op_sel_hi:[1,0,1]
	v_pk_fma_f32 v[62:63], v[162:163], v[114:115], v[62:63] op_sel_hi:[1,0,1]
	v_pk_fma_f32 v[60:61], v[168:169], v[116:117], v[60:61] op_sel_hi:[1,0,1]
	v_pk_fma_f32 v[62:63], v[170:171], v[116:117], v[62:63] op_sel_hi:[1,0,1]
	v_pk_fma_f32 v[60:61], v[172:173], v[66:67], v[60:61] op_sel_hi:[1,0,1]
	v_pk_fma_f32 v[62:63], v[174:175], v[66:67], v[62:63] op_sel_hi:[1,0,1]
	v_pk_add_f32 v[22:23], v[22:23], v[60:61]
	v_pk_add_f32 v[24:25], v[24:25], v[62:63]
	s_waitcnt lgkmcnt(7)
	v_mov_b32_e32 v66, v121
	v_pk_mul_f32 v[60:61], v[164:165], v[118:119] op_sel:[0,1]
	v_pk_mul_f32 v[62:63], v[166:167], v[118:119] op_sel:[0,1]
	v_pk_fma_f32 v[60:61], v[160:161], v[118:119], v[60:61] op_sel_hi:[1,0,1]
	v_pk_fma_f32 v[62:63], v[162:163], v[118:119], v[62:63] op_sel_hi:[1,0,1]
	v_pk_fma_f32 v[60:61], v[168:169], v[120:121], v[60:61] op_sel_hi:[1,0,1]
	v_pk_fma_f32 v[62:63], v[170:171], v[120:121], v[62:63] op_sel_hi:[1,0,1]
	v_pk_fma_f32 v[60:61], v[172:173], v[66:67], v[60:61] op_sel_hi:[1,0,1]
	v_pk_fma_f32 v[62:63], v[174:175], v[66:67], v[62:63] op_sel_hi:[1,0,1]
	v_pk_add_f32 v[34:35], v[34:35], v[60:61]
	v_pk_add_f32 v[36:37], v[36:37], v[62:63]
	s_waitcnt lgkmcnt(6)
	v_mov_b32_e32 v66, v125
	v_pk_mul_f32 v[60:61], v[164:165], v[122:123] op_sel:[0,1]
	v_pk_mul_f32 v[62:63], v[166:167], v[122:123] op_sel:[0,1]
	v_pk_fma_f32 v[60:61], v[160:161], v[122:123], v[60:61] op_sel_hi:[1,0,1]
	v_pk_fma_f32 v[62:63], v[162:163], v[122:123], v[62:63] op_sel_hi:[1,0,1]
	v_pk_fma_f32 v[60:61], v[168:169], v[124:125], v[60:61] op_sel_hi:[1,0,1]
	v_pk_fma_f32 v[62:63], v[170:171], v[124:125], v[62:63] op_sel_hi:[1,0,1]
	v_pk_fma_f32 v[60:61], v[172:173], v[66:67], v[60:61] op_sel_hi:[1,0,1]
	v_pk_fma_f32 v[62:63], v[174:175], v[66:67], v[62:63] op_sel_hi:[1,0,1]
	v_pk_add_f32 v[30:31], v[30:31], v[60:61]
	v_pk_add_f32 v[32:33], v[32:33], v[62:63]
	s_waitcnt lgkmcnt(5)
; __device__ __forceinline__ float4 ld_nt4(const float* p) { const f32x4v v = __builtin_nontemporal_load((const f32x4v*)p); return make_float4(v[0], v[1], v[2], v[3]); }
; DI void p0_mod_item(const Params& P, unsigned char* lds, int idx, const int tid) {
;     ...
;   for (int k4 = 0; k4 < 32; ++k4) {
;     float4 w0 = ld_nt4(W + (size_t)(k4 * 4 + 0) * NMOD);
;     float4 w1 = ld_nt4(W + (size_t)(k4 * 4 + 1) * NMOD);
;     float4 w2 = ld_nt4(W + (size_t)(k4 * 4 + 2) * NMOD);
;     float4 w3 = ld_nt4(W + (size_t)(k4 * 4 + 3) * NMOD);
; #pragma unroll
;     for (int r = 0; r < 9; ++r) {
;       float4 s4 = *(const float4*)(sl + r * 1024 + wave * 128 + k4 * 4);
;       acc[r].x += s4.x * w0.x + s4.y * w1.x + s4.z * w2.x + s4.w * w3.x;
;       acc[r].y += s4.x * w0.y + s4.y * w1.y + s4.z * w2.y + s4.w * w3.y;
;       acc[r].z += s4.x * w0.z + s4.y * w1.z + s4.z * w2.z + s4.w * w3.z;
;       acc[r].w += s4.x * w0.w + s4.y * w1.w + s4.z * w2.w + s4.w * w3.w;
;     }
	v_mov_b32_e32 v66, v129
	v_pk_mul_f32 v[60:61], v[164:165], v[126:127] op_sel:[0,1]
	v_pk_mul_f32 v[62:63], v[166:167], v[126:127] op_sel:[0,1]
	v_pk_fma_f32 v[60:61], v[160:161], v[126:127], v[60:61] op_sel_hi:[1,0,1]
	v_pk_fma_f32 v[62:63], v[162:163], v[126:127], v[62:63] op_sel_hi:[1,0,1]
	v_pk_fma_f32 v[60:61], v[168:169], v[128:129], v[60:61] op_sel_hi:[1,0,1]
	v_pk_fma_f32 v[62:63], v[170:171], v[128:129], v[62:63] op_sel_hi:[1,0,1]
	v_pk_fma_f32 v[60:61], v[172:173], v[66:67], v[60:61] op_sel_hi:[1,0,1]
	v_pk_fma_f32 v[62:63], v[174:175], v[66:67], v[62:63] op_sel_hi:[1,0,1]
	v_pk_add_f32 v[26:27], v[26:27], v[60:61]
	v_pk_add_f32 v[28:29], v[28:29], v[62:63]
	s_waitcnt lgkmcnt(4)
	v_mov_b32_e32 v66, v133
	v_pk_mul_f32 v[60:61], v[164:165], v[130:131] op_sel:[0,1]
	v_pk_mul_f32 v[62:63], v[166:167], v[130:131] op_sel:[0,1]
	v_pk_fma_f32 v[60:61], v[160:161], v[130:131], v[60:61] op_sel_hi:[1,0,1]
	v_pk_fma_f32 v[62:63], v[162:163], v[130:131], v[62:63] op_sel_hi:[1,0,1]
	v_pk_fma_f32 v[60:61], v[168:169], v[132:133], v[60:61] op_sel_hi:[1,0,1]
	v_pk_fma_f32 v[62:63], v[170:171], v[132:133], v[62:63] op_sel_hi:[1,0,1]
	v_pk_fma_f32 v[60:61], v[172:173], v[66:67], v[60:61] op_sel_hi:[1,0,1]
	v_pk_fma_f32 v[62:63], v[174:175], v[66:67], v[62:63] op_sel_hi:[1,0,1]
	v_pk_add_f32 v[18:19], v[18:19], v[60:61]
	v_pk_add_f32 v[20:21], v[20:21], v[62:63]
	s_waitcnt lgkmcnt(3)
	v_mov_b32_e32 v66, v137
	v_pk_mul_f32 v[60:61], v[164:165], v[134:135] op_sel:[0,1]
	v_pk_mul_f32 v[62:63], v[166:167], v[134:135] op_sel:[0,1]
	v_pk_fma_f32 v[60:61], v[160:161], v[134:135], v[60:61] op_sel_hi:[1,0,1]
	v_pk_fma_f32 v[62:63], v[162:163], v[134:135], v[62:63] op_sel_hi:[1,0,1]
	v_pk_fma_f32 v[60:61], v[168:169], v[136:137], v[60:61] op_sel_hi:[1,0,1]
	v_pk_fma_f32 v[62:63], v[170:171], v[136:137], v[62:63] op_sel_hi:[1,0,1]
	v_pk_fma_f32 v[60:61], v[172:173], v[66:67], v[60:61] op_sel_hi:[1,0,1]
	v_pk_fma_f32 v[62:63], v[174:175], v[66:67], v[62:63] op_sel_hi:[1,0,1]
	v_pk_add_f32 v[14:15], v[14:15], v[60:61]
	v_pk_add_f32 v[16:17], v[16:17], v[62:63]
	s_waitcnt lgkmcnt(2)
	v_mov_b32_e32 v66, v141
	v_pk_mul_f32 v[60:61], v[164:165], v[138:139] op_sel:[0,1]
	v_pk_mul_f32 v[62:63], v[166:167], v[138:139] op_sel:[0,1]
	v_pk_fma_f32 v[60:61], v[160:161], v[138:139], v[60:61] op_sel_hi:[1,0,1]
	v_pk_fma_f32 v[62:63], v[162:163], v[138:139], v[62:63] op_sel_hi:[1,0,1]
	v_pk_fma_f32 v[60:61], v[168:169], v[140:141], v[60:61] op_sel_hi:[1,0,1]
	v_pk_fma_f32 v[62:63], v[170:171], v[140:141], v[62:63] op_sel_hi:[1,0,1]
	v_pk_fma_f32 v[60:61], v[172:173], v[66:67], v[60:61] op_sel_hi:[1,0,1]
	v_pk_fma_f32 v[62:63], v[174:175], v[66:67], v[62:63] op_sel_hi:[1,0,1]
	v_pk_add_f32 v[10:11], v[10:11], v[60:61]
	v_pk_add_f32 v[12:13], v[12:13], v[62:63]
	s_waitcnt lgkmcnt(1)
	v_mov_b32_e32 v66, v145
	v_pk_mul_f32 v[60:61], v[164:165], v[142:143] op_sel:[0,1]
	v_pk_mul_f32 v[62:63], v[166:167], v[142:143] op_sel:[0,1]
	v_pk_fma_f32 v[60:61], v[160:161], v[142:143], v[60:61] op_sel_hi:[1,0,1]
	v_pk_fma_f32 v[62:63], v[162:163], v[142:143], v[62:63] op_sel_hi:[1,0,1]
	v_pk_fma_f32 v[60:61], v[168:169], v[144:145], v[60:61] op_sel_hi:[1,0,1]
	v_pk_fma_f32 v[62:63], v[170:171], v[144:145], v[62:63] op_sel_hi:[1,0,1]
	v_pk_fma_f32 v[60:61], v[172:173], v[66:67], v[60:61] op_sel_hi:[1,0,1]
	v_pk_fma_f32 v[62:63], v[174:175], v[66:67], v[62:63] op_sel_hi:[1,0,1]
	v_pk_add_f32 v[6:7], v[6:7], v[60:61]
	v_pk_add_f32 v[8:9], v[8:9], v[62:63]
	s_waitcnt lgkmcnt(0)
	v_mov_b32_e32 v66, v149
	v_pk_mul_f32 v[60:61], v[164:165], v[146:147] op_sel:[0,1]
	v_pk_mul_f32 v[62:63], v[166:167], v[146:147] op_sel:[0,1]
	v_pk_fma_f32 v[60:61], v[160:161], v[146:147], v[60:61] op_sel_hi:[1,0,1]
	v_pk_fma_f32 v[62:63], v[162:163], v[146:147], v[62:63] op_sel_hi:[1,0,1]
	v_pk_fma_f32 v[60:61], v[168:169], v[148:149], v[60:61] op_sel_hi:[1,0,1]
	v_pk_fma_f32 v[62:63], v[170:171], v[148:149], v[62:63] op_sel_hi:[1,0,1]
	v_pk_fma_f32 v[60:61], v[172:173], v[66:67], v[60:61] op_sel_hi:[1,0,1]
	v_pk_fma_f32 v[62:63], v[174:175], v[66:67], v[62:63] op_sel_hi:[1,0,1]
	v_pk_add_f32 v[2:3], v[2:3], v[60:61]
	v_pk_add_f32 v[4:5], v[4:5], v[62:63]
	global_load_dwordx4 v[160:163], v[150:151], off nt
	v_lshl_add_u64 v[150:151], v[150:151], 0, s[4:5]
	global_load_dwordx4 v[164:167], v[150:151], off nt
	v_lshl_add_u64 v[150:151], v[150:151], 0, s[4:5]
	global_load_dwordx4 v[168:171], v[150:151], off nt
	v_lshl_add_u64 v[150:151], v[150:151], 0, s[4:5]
	global_load_dwordx4 v[172:175], v[150:151], off nt
	v_lshl_add_u64 v[150:151], v[150:151], 0, s[4:5]
	ds_read_b128 v[114:117], v152 offset:32
	ds_read_b128 v[118:121], v152 offset:4128
	ds_read_b128 v[122:125], v152 offset:8224
	ds_read_b128 v[126:129], v152 offset:12320
	ds_read_b128 v[130:133], v152 offset:16416
	ds_read_b128 v[134:137], v152 offset:20512
	ds_read_b128 v[138:141], v152 offset:24608
	ds_read_b128 v[142:145], v152 offset:28704
	ds_read_b128 v[146:149], v152 offset:32800
	s_waitcnt vmcnt(12)
	s_waitcnt lgkmcnt(8)
	v_mov_b32_e32 v66, v117
	v_pk_mul_f32 v[60:61], v[180:181], v[114:115] op_sel:[0,1]
	v_pk_mul_f32 v[62:63], v[182:183], v[114:115] op_sel:[0,1]
	v_pk_fma_f32 v[60:61], v[176:177], v[114:115], v[60:61] op_sel_hi:[1,0,1]
	v_pk_fma_f32 v[62:63], v[178:179], v[114:115], v[62:63] op_sel_hi:[1,0,1]
	v_pk_fma_f32 v[60:61], v[184:185], v[116:117], v[60:61] op_sel_hi:[1,0,1]
	v_pk_fma_f32 v[62:63], v[186:187], v[116:117], v[62:63] op_sel_hi:[1,0,1]
	v_pk_fma_f32 v[60:61], v[188:189], v[66:67], v[60:61] op_sel_hi:[1,0,1]
	v_pk_fma_f32 v[62:63], v[190:191], v[66:67], v[62:63] op_sel_hi:[1,0,1]
	v_pk_add_f32 v[22:23], v[22:23], v[60:61]
	v_pk_add_f32 v[24:25], v[24:25], v[62:63]
	s_waitcnt lgkmcnt(7)
; __device__ __forceinline__ float4 ld_nt4(const float* p) { const f32x4v v = __builtin_nontemporal_load((const f32x4v*)p); return make_float4(v[0], v[1], v[2], v[3]); }
; DI void p0_mod_item(const Params& P, unsigned char* lds, int idx, const int tid) {
;     ...
;   for (int k4 = 0; k4 < 32; ++k4) {
;     float4 w0 = ld_nt4(W + (size_t)(k4 * 4 + 0) * NMOD);
;     float4 w1 = ld_nt4(W + (size_t)(k4 * 4 + 1) * NMOD);
;     float4 w2 = ld_nt4(W + (size_t)(k4 * 4 + 2) * NMOD);
;     float4 w3 = ld_nt4(W + (size_t)(k4 * 4 + 3) * NMOD);
; #pragma unroll
;     for (int r = 0; r < 9; ++r) {
;       float4 s4 = *(const float4*)(sl + r * 1024 + wave * 128 + k4 * 4);
;       acc[r].x += s4.x * w0.x + s4.y * w1.x + s4.z * w2.x + s4.w * w3.x;
;       acc[r].y += s4.x * w0.y + s4.y * w1.y + s4.z * w2.y + s4.w * w3.y;
;       acc[r].z += s4.x * w0.z + s4.y * w1.z + s4.z * w2.z + s4.w * w3.z;
;       acc[r].w += s4.x * w0.w + s4.y * w1.w + s4.z * w2.w + s4.w * w3.w;
;     }
	v_mov_b32_e32 v66, v121
	v_pk_mul_f32 v[60:61], v[180:181], v[118:119] op_sel:[0,1]
	v_pk_mul_f32 v[62:63], v[182:183], v[118:119] op_sel:[0,1]
	v_pk_fma_f32 v[60:61], v[176:177], v[118:119], v[60:61] op_sel_hi:[1,0,1]
	v_pk_fma_f32 v[62:63], v[178:179], v[118:119], v[62:63] op_sel_hi:[1,0,1]
	v_pk_fma_f32 v[60:61], v[184:185], v[120:121], v[60:61] op_sel_hi:[1,0,1]
	v_pk_fma_f32 v[62:63], v[186:187], v[120:121], v[62:63] op_sel_hi:[1,0,1]
	v_pk_fma_f32 v[60:61], v[188:189], v[66:67], v[60:61] op_sel_hi:[1,0,1]
	v_pk_fma_f32 v[62:63], v[190:191], v[66:67], v[62:63] op_sel_hi:[1,0,1]
	v_pk_add_f32 v[34:35], v[34:35], v[60:61]
	v_pk_add_f32 v[36:37], v[36:37], v[62:63]
	s_waitcnt lgkmcnt(6)
	v_mov_b32_e32 v66, v125
	v_pk_mul_f32 v[60:61], v[180:181], v[122:123] op_sel:[0,1]
	v_pk_mul_f32 v[62:63], v[182:183], v[122:123] op_sel:[0,1]
	v_pk_fma_f32 v[60:61], v[176:177], v[122:123], v[60:61] op_sel_hi:[1,0,1]
	v_pk_fma_f32 v[62:63], v[178:179], v[122:123], v[62:63] op_sel_hi:[1,0,1]
	v_pk_fma_f32 v[60:61], v[184:185], v[124:125], v[60:61] op_sel_hi:[1,0,1]
	v_pk_fma_f32 v[62:63], v[186:187], v[124:125], v[62:63] op_sel_hi:[1,0,1]
	v_pk_fma_f32 v[60:61], v[188:189], v[66:67], v[60:61] op_sel_hi:[1,0,1]
	v_pk_fma_f32 v[62:63], v[190:191], v[66:67], v[62:63] op_sel_hi:[1,0,1]
	v_pk_add_f32 v[30:31], v[30:31], v[60:61]
	v_pk_add_f32 v[32:33], v[32:33], v[62:63]
	s_waitcnt lgkmcnt(5)
	v_mov_b32_e32 v66, v129
	v_pk_mul_f32 v[60:61], v[180:181], v[126:127] op_sel:[0,1]
	v_pk_mul_f32 v[62:63], v[182:183], v[126:127] op_sel:[0,1]
	v_pk_fma_f32 v[60:61], v[176:177], v[126:127], v[60:61] op_sel_hi:[1,0,1]
	v_pk_fma_f32 v[62:63], v[178:179], v[126:127], v[62:63] op_sel_hi:[1,0,1]
	v_pk_fma_f32 v[60:61], v[184:185], v[128:129], v[60:61] op_sel_hi:[1,0,1]
	v_pk_fma_f32 v[62:63], v[186:187], v[128:129], v[62:63] op_sel_hi:[1,0,1]
	v_pk_fma_f32 v[60:61], v[188:189], v[66:67], v[60:61] op_sel_hi:[1,0,1]
	v_pk_fma_f32 v[62:63], v[190:191], v[66:67], v[62:63] op_sel_hi:[1,0,1]
	v_pk_add_f32 v[26:27], v[26:27], v[60:61]
	v_pk_add_f32 v[28:29], v[28:29], v[62:63]
	s_waitcnt lgkmcnt(4)
	v_mov_b32_e32 v66, v133
	v_pk_mul_f32 v[60:61], v[180:181], v[130:131] op_sel:[0,1]
	v_pk_mul_f32 v[62:63], v[182:183], v[130:131] op_sel:[0,1]
	v_pk_fma_f32 v[60:61], v[176:177], v[130:131], v[60:61] op_sel_hi:[1,0,1]
	v_pk_fma_f32 v[62:63], v[178:179], v[130:131], v[62:63] op_sel_hi:[1,0,1]
	v_pk_fma_f32 v[60:61], v[184:185], v[132:133], v[60:61] op_sel_hi:[1,0,1]
	v_pk_fma_f32 v[62:63], v[186:187], v[132:133], v[62:63] op_sel_hi:[1,0,1]
	v_pk_fma_f32 v[60:61], v[188:189], v[66:67], v[60:61] op_sel_hi:[1,0,1]
	v_pk_fma_f32 v[62:63], v[190:191], v[66:67], v[62:63] op_sel_hi:[1,0,1]
	v_pk_add_f32 v[18:19], v[18:19], v[60:61]
	v_pk_add_f32 v[20:21], v[20:21], v[62:63]
	s_waitcnt lgkmcnt(3)
	v_mov_b32_e32 v66, v137
	v_pk_mul_f32 v[60:61], v[180:181], v[134:135] op_sel:[0,1]
	v_pk_mul_f32 v[62:63], v[182:183], v[134:135] op_sel:[0,1]
	v_pk_fma_f32 v[60:61], v[176:177], v[134:135], v[60:61] op_sel_hi:[1,0,1]
	v_pk_fma_f32 v[62:63], v[178:179], v[134:135], v[62:63] op_sel_hi:[1,0,1]
	v_pk_fma_f32 v[60:61], v[184:185], v[136:137], v[60:61] op_sel_hi:[1,0,1]
	v_pk_fma_f32 v[62:63], v[186:187], v[136:137], v[62:63] op_sel_hi:[1,0,1]
	v_pk_fma_f32 v[60:61], v[188:189], v[66:67], v[60:61] op_sel_hi:[1,0,1]
	v_pk_fma_f32 v[62:63], v[190:191], v[66:67], v[62:63] op_sel_hi:[1,0,1]
	v_pk_add_f32 v[14:15], v[14:15], v[60:61]
	v_pk_add_f32 v[16:17], v[16:17], v[62:63]
	s_waitcnt lgkmcnt(2)
	v_mov_b32_e32 v66, v141
	v_pk_mul_f32 v[60:61], v[180:181], v[138:139] op_sel:[0,1]
	v_pk_mul_f32 v[62:63], v[182:183], v[138:139] op_sel:[0,1]
	v_pk_fma_f32 v[60:61], v[176:177], v[138:139], v[60:61] op_sel_hi:[1,0,1]
	v_pk_fma_f32 v[62:63], v[178:179], v[138:139], v[62:63] op_sel_hi:[1,0,1]
	v_pk_fma_f32 v[60:61], v[184:185], v[140:141], v[60:61] op_sel_hi:[1,0,1]
	v_pk_fma_f32 v[62:63], v[186:187], v[140:141], v[62:63] op_sel_hi:[1,0,1]
	v_pk_fma_f32 v[60:61], v[188:189], v[66:67], v[60:61] op_sel_hi:[1,0,1]
	v_pk_fma_f32 v[62:63], v[190:191], v[66:67], v[62:63] op_sel_hi:[1,0,1]
	v_pk_add_f32 v[10:11], v[10:11], v[60:61]
	v_pk_add_f32 v[12:13], v[12:13], v[62:63]
	s_waitcnt lgkmcnt(1)
	v_mov_b32_e32 v66, v145
	v_pk_mul_f32 v[60:61], v[180:181], v[142:143] op_sel:[0,1]
	v_pk_mul_f32 v[62:63], v[182:183], v[142:143] op_sel:[0,1]
	v_pk_fma_f32 v[60:61], v[176:177], v[142:143], v[60:61] op_sel_hi:[1,0,1]
	v_pk_fma_f32 v[62:63], v[178:179], v[142:143], v[62:63] op_sel_hi:[1,0,1]
	v_pk_fma_f32 v[60:61], v[184:185], v[144:145], v[60:61] op_sel_hi:[1,0,1]
	v_pk_fma_f32 v[62:63], v[186:187], v[144:145], v[62:63] op_sel_hi:[1,0,1]
	v_pk_fma_f32 v[60:61], v[188:189], v[66:67], v[60:61] op_sel_hi:[1,0,1]
	v_pk_fma_f32 v[62:63], v[190:191], v[66:67], v[62:63] op_sel_hi:[1,0,1]
	v_pk_add_f32 v[6:7], v[6:7], v[60:61]
	v_pk_add_f32 v[8:9], v[8:9], v[62:63]
	s_waitcnt lgkmcnt(0)
	v_mov_b32_e32 v66, v149
	v_pk_mul_f32 v[60:61], v[180:181], v[146:147] op_sel:[0,1]
	v_pk_mul_f32 v[62:63], v[182:183], v[146:147] op_sel:[0,1]
	v_pk_fma_f32 v[60:61], v[176:177], v[146:147], v[60:61] op_sel_hi:[1,0,1]
	v_pk_fma_f32 v[62:63], v[178:179], v[146:147], v[62:63] op_sel_hi:[1,0,1]
	v_pk_fma_f32 v[60:61], v[184:185], v[148:149], v[60:61] op_sel_hi:[1,0,1]
	v_pk_fma_f32 v[62:63], v[186:187], v[148:149], v[62:63] op_sel_hi:[1,0,1]
	v_pk_fma_f32 v[60:61], v[188:189], v[66:67], v[60:61] op_sel_hi:[1,0,1]
	v_pk_fma_f32 v[62:63], v[190:191], v[66:67], v[62:63] op_sel_hi:[1,0,1]
	v_pk_add_f32 v[2:3], v[2:3], v[60:61]
	v_pk_add_f32 v[4:5], v[4:5], v[62:63]
	global_load_dwordx4 v[176:179], v[150:151], off nt
	v_lshl_add_u64 v[150:151], v[150:151], 0, s[4:5]
	global_load_dwordx4 v[180:183], v[150:151], off nt
	v_lshl_add_u64 v[150:151], v[150:151], 0, s[4:5]
	global_load_dwordx4 v[184:187], v[150:151], off nt
	v_lshl_add_u64 v[150:151], v[150:151], 0, s[4:5]
	global_load_dwordx4 v[188:191], v[150:151], off nt
	v_lshl_add_u64 v[150:151], v[150:151], 0, s[4:5]
	ds_read_b128 v[114:117], v152 offset:48
	ds_read_b128 v[118:121], v152 offset:4144
	ds_read_b128 v[122:125], v152 offset:8240
	ds_read_b128 v[126:129], v152 offset:12336
	ds_read_b128 v[130:133], v152 offset:16432
	ds_read_b128 v[134:137], v152 offset:20528
	ds_read_b128 v[138:141], v152 offset:24624
	ds_read_b128 v[142:145], v152 offset:28720
	ds_read_b128 v[146:149], v152 offset:32816
	s_waitcnt vmcnt(12)
; __device__ __forceinline__ float4 ld_nt4(const float* p) { const f32x4v v = __builtin_nontemporal_load((const f32x4v*)p); return make_float4(v[0], v[1], v[2], v[3]); }
; DI void p0_mod_item(const Params& P, unsigned char* lds, int idx, const int tid) {
;     ...
;   for (int k4 = 0; k4 < 32; ++k4) {
;     float4 w0 = ld_nt4(W + (size_t)(k4 * 4 + 0) * NMOD);
;     float4 w1 = ld_nt4(W + (size_t)(k4 * 4 + 1) * NMOD);
;     float4 w2 = ld_nt4(W + (size_t)(k4 * 4 + 2) * NMOD);
;     float4 w3 = ld_nt4(W + (size_t)(k4 * 4 + 3) * NMOD);
; #pragma unroll
;     for (int r = 0; r < 9; ++r) {
;       float4 s4 = *(const float4*)(sl + r * 1024 + wave * 128 + k4 * 4);
;       acc[r].x += s4.x * w0.x + s4.y * w1.x + s4.z * w2.x + s4.w * w3.x;
;       acc[r].y += s4.x * w0.y + s4.y * w1.y + s4.z * w2.y + s4.w * w3.y;
;       acc[r].z += s4.x * w0.z + s4.y * w1.z + s4.z * w2.z + s4.w * w3.z;
;       acc[r].w += s4.x * w0.w + s4.y * w1.w + s4.z * w2.w + s4.w * w3.w;
;     }
	s_waitcnt lgkmcnt(8)
	v_mov_b32_e32 v66, v117
	v_pk_mul_f32 v[60:61], v[196:197], v[114:115] op_sel:[0,1]
	v_pk_mul_f32 v[62:63], v[198:199], v[114:115] op_sel:[0,1]
	v_pk_fma_f32 v[60:61], v[192:193], v[114:115], v[60:61] op_sel_hi:[1,0,1]
	v_pk_fma_f32 v[62:63], v[194:195], v[114:115], v[62:63] op_sel_hi:[1,0,1]
	v_pk_fma_f32 v[60:61], v[200:201], v[116:117], v[60:61] op_sel_hi:[1,0,1]
	v_pk_fma_f32 v[62:63], v[202:203], v[116:117], v[62:63] op_sel_hi:[1,0,1]
	v_pk_fma_f32 v[60:61], v[204:205], v[66:67], v[60:61] op_sel_hi:[1,0,1]
	v_pk_fma_f32 v[62:63], v[206:207], v[66:67], v[62:63] op_sel_hi:[1,0,1]
	v_pk_add_f32 v[22:23], v[22:23], v[60:61]
	v_pk_add_f32 v[24:25], v[24:25], v[62:63]
	s_waitcnt lgkmcnt(7)
	v_mov_b32_e32 v66, v121
	v_pk_mul_f32 v[60:61], v[196:197], v[118:119] op_sel:[0,1]
	v_pk_mul_f32 v[62:63], v[198:199], v[118:119] op_sel:[0,1]
	v_pk_fma_f32 v[60:61], v[192:193], v[118:119], v[60:61] op_sel_hi:[1,0,1]
	v_pk_fma_f32 v[62:63], v[194:195], v[118:119], v[62:63] op_sel_hi:[1,0,1]
	v_pk_fma_f32 v[60:61], v[200:201], v[120:121], v[60:61] op_sel_hi:[1,0,1]
	v_pk_fma_f32 v[62:63], v[202:203], v[120:121], v[62:63] op_sel_hi:[1,0,1]
	v_pk_fma_f32 v[60:61], v[204:205], v[66:67], v[60:61] op_sel_hi:[1,0,1]
	v_pk_fma_f32 v[62:63], v[206:207], v[66:67], v[62:63] op_sel_hi:[1,0,1]
	v_pk_add_f32 v[34:35], v[34:35], v[60:61]
	v_pk_add_f32 v[36:37], v[36:37], v[62:63]
	s_waitcnt lgkmcnt(6)
	v_mov_b32_e32 v66, v125
	v_pk_mul_f32 v[60:61], v[196:197], v[122:123] op_sel:[0,1]
	v_pk_mul_f32 v[62:63], v[198:199], v[122:123] op_sel:[0,1]
	v_pk_fma_f32 v[60:61], v[192:193], v[122:123], v[60:61] op_sel_hi:[1,0,1]
	v_pk_fma_f32 v[62:63], v[194:195], v[122:123], v[62:63] op_sel_hi:[1,0,1]
	v_pk_fma_f32 v[60:61], v[200:201], v[124:125], v[60:61] op_sel_hi:[1,0,1]
	v_pk_fma_f32 v[62:63], v[202:203], v[124:125], v[62:63] op_sel_hi:[1,0,1]
	v_pk_fma_f32 v[60:61], v[204:205], v[66:67], v[60:61] op_sel_hi:[1,0,1]
	v_pk_fma_f32 v[62:63], v[206:207], v[66:67], v[62:63] op_sel_hi:[1,0,1]
	v_pk_add_f32 v[30:31], v[30:31], v[60:61]
	v_pk_add_f32 v[32:33], v[32:33], v[62:63]
	s_waitcnt lgkmcnt(5)
	v_mov_b32_e32 v66, v129
	v_pk_mul_f32 v[60:61], v[196:197], v[126:127] op_sel:[0,1]
	v_pk_mul_f32 v[62:63], v[198:199], v[126:127] op_sel:[0,1]
	v_pk_fma_f32 v[60:61], v[192:193], v[126:127], v[60:61] op_sel_hi:[1,0,1]
	v_pk_fma_f32 v[62:63], v[194:195], v[126:127], v[62:63] op_sel_hi:[1,0,1]
	v_pk_fma_f32 v[60:61], v[200:201], v[128:129], v[60:61] op_sel_hi:[1,0,1]
	v_pk_fma_f32 v[62:63], v[202:203], v[128:129], v[62:63] op_sel_hi:[1,0,1]
	v_pk_fma_f32 v[60:61], v[204:205], v[66:67], v[60:61] op_sel_hi:[1,0,1]
	v_pk_fma_f32 v[62:63], v[206:207], v[66:67], v[62:63] op_sel_hi:[1,0,1]
	v_pk_add_f32 v[26:27], v[26:27], v[60:61]
	v_pk_add_f32 v[28:29], v[28:29], v[62:63]
	s_waitcnt lgkmcnt(4)
	v_mov_b32_e32 v66, v133
	v_pk_mul_f32 v[60:61], v[196:197], v[130:131] op_sel:[0,1]
	v_pk_mul_f32 v[62:63], v[198:199], v[130:131] op_sel:[0,1]
	v_pk_fma_f32 v[60:61], v[192:193], v[130:131], v[60:61] op_sel_hi:[1,0,1]
	v_pk_fma_f32 v[62:63], v[194:195], v[130:131], v[62:63] op_sel_hi:[1,0,1]
	v_pk_fma_f32 v[60:61], v[200:201], v[132:133], v[60:61] op_sel_hi:[1,0,1]
	v_pk_fma_f32 v[62:63], v[202:203], v[132:133], v[62:63] op_sel_hi:[1,0,1]
	v_pk_fma_f32 v[60:61], v[204:205], v[66:67], v[60:61] op_sel_hi:[1,0,1]
	v_pk_fma_f32 v[62:63], v[206:207], v[66:67], v[62:63] op_sel_hi:[1,0,1]
	v_pk_add_f32 v[18:19], v[18:19], v[60:61]
	v_pk_add_f32 v[20:21], v[20:21], v[62:63]
	s_waitcnt lgkmcnt(3)
	v_mov_b32_e32 v66, v137
	v_pk_mul_f32 v[60:61], v[196:197], v[134:135] op_sel:[0,1]
	v_pk_mul_f32 v[62:63], v[198:199], v[134:135] op_sel:[0,1]
	v_pk_fma_f32 v[60:61], v[192:193], v[134:135], v[60:61] op_sel_hi:[1,0,1]
	v_pk_fma_f32 v[62:63], v[194:195], v[134:135], v[62:63] op_sel_hi:[1,0,1]
	v_pk_fma_f32 v[60:61], v[200:201], v[136:137], v[60:61] op_sel_hi:[1,0,1]
	v_pk_fma_f32 v[62:63], v[202:203], v[136:137], v[62:63] op_sel_hi:[1,0,1]
	v_pk_fma_f32 v[60:61], v[204:205], v[66:67], v[60:61] op_sel_hi:[1,0,1]
	v_pk_fma_f32 v[62:63], v[206:207], v[66:67], v[62:63] op_sel_hi:[1,0,1]
	v_pk_add_f32 v[14:15], v[14:15], v[60:61]
	v_pk_add_f32 v[16:17], v[16:17], v[62:63]
	s_waitcnt lgkmcnt(2)
	v_mov_b32_e32 v66, v141
	v_pk_mul_f32 v[60:61], v[196:197], v[138:139] op_sel:[0,1]
	v_pk_mul_f32 v[62:63], v[198:199], v[138:139] op_sel:[0,1]
	v_pk_fma_f32 v[60:61], v[192:193], v[138:139], v[60:61] op_sel_hi:[1,0,1]
	v_pk_fma_f32 v[62:63], v[194:195], v[138:139], v[62:63] op_sel_hi:[1,0,1]
	v_pk_fma_f32 v[60:61], v[200:201], v[140:141], v[60:61] op_sel_hi:[1,0,1]
	v_pk_fma_f32 v[62:63], v[202:203], v[140:141], v[62:63] op_sel_hi:[1,0,1]
	v_pk_fma_f32 v[60:61], v[204:205], v[66:67], v[60:61] op_sel_hi:[1,0,1]
	v_pk_fma_f32 v[62:63], v[206:207], v[66:67], v[62:63] op_sel_hi:[1,0,1]
	v_pk_add_f32 v[10:11], v[10:11], v[60:61]
	v_pk_add_f32 v[12:13], v[12:13], v[62:63]
	s_waitcnt lgkmcnt(1)
	v_mov_b32_e32 v66, v145
	v_pk_mul_f32 v[60:61], v[196:197], v[142:143] op_sel:[0,1]
	v_pk_mul_f32 v[62:63], v[198:199], v[142:143] op_sel:[0,1]
	v_pk_fma_f32 v[60:61], v[192:193], v[142:143], v[60:61] op_sel_hi:[1,0,1]
	v_pk_fma_f32 v[62:63], v[194:195], v[142:143], v[62:63] op_sel_hi:[1,0,1]
	v_pk_fma_f32 v[60:61], v[200:201], v[144:145], v[60:61] op_sel_hi:[1,0,1]
	v_pk_fma_f32 v[62:63], v[202:203], v[144:145], v[62:63] op_sel_hi:[1,0,1]
	v_pk_fma_f32 v[60:61], v[204:205], v[66:67], v[60:61] op_sel_hi:[1,0,1]
	v_pk_fma_f32 v[62:63], v[206:207], v[66:67], v[62:63] op_sel_hi:[1,0,1]
	v_pk_add_f32 v[6:7], v[6:7], v[60:61]
	v_pk_add_f32 v[8:9], v[8:9], v[62:63]
	s_waitcnt lgkmcnt(0)
	v_mov_b32_e32 v66, v149
	v_pk_mul_f32 v[60:61], v[196:197], v[146:147] op_sel:[0,1]
	v_pk_mul_f32 v[62:63], v[198:199], v[146:147] op_sel:[0,1]
	v_pk_fma_f32 v[60:61], v[192:193], v[146:147], v[60:61] op_sel_hi:[1,0,1]
	v_pk_fma_f32 v[62:63], v[194:195], v[146:147], v[62:63] op_sel_hi:[1,0,1]
	v_pk_fma_f32 v[60:61], v[200:201], v[148:149], v[60:61] op_sel_hi:[1,0,1]
	v_pk_fma_f32 v[62:63], v[202:203], v[148:149], v[62:63] op_sel_hi:[1,0,1]
	v_pk_fma_f32 v[60:61], v[204:205], v[66:67], v[60:61] op_sel_hi:[1,0,1]
	v_pk_fma_f32 v[62:63], v[206:207], v[66:67], v[62:63] op_sel_hi:[1,0,1]
	v_pk_add_f32 v[2:3], v[2:3], v[60:61]
	v_pk_add_f32 v[4:5], v[4:5], v[62:63]
	global_load_dwordx4 v[192:195], v[150:151], off nt
	v_lshl_add_u64 v[150:151], v[150:151], 0, s[4:5]
	global_load_dwordx4 v[196:199], v[150:151], off nt
	v_lshl_add_u64 v[150:151], v[150:151], 0, s[4:5]
	global_load_dwordx4 v[200:203], v[150:151], off nt
	v_lshl_add_u64 v[150:151], v[150:151], 0, s[4:5]
	global_load_dwordx4 v[204:207], v[150:151], off nt
	v_lshl_add_u64 v[150:151], v[150:151], 0, s[4:5]
	v_add_u32_e32 v152, 64, v152
	s_add_i32 s100, s100, 1
	s_cmp_lt_u32 s100, 7
	s_cbranch_scc1 .Lmod_b_trip
; __device__ __forceinline__ float4 ld_nt4(const float* p) { const f32x4v v = __builtin_nontemporal_load((const f32x4v*)p); return make_float4(v[0], v[1], v[2], v[3]); }
; DI void p0_mod_item(const Params& P, unsigned char* lds, int idx, const int tid) {
;     ...
;   for (int k4 = 0; k4 < 32; ++k4) {
;     float4 w0 = ld_nt4(W + (size_t)(k4 * 4 + 0) * NMOD);
;     float4 w1 = ld_nt4(W + (size_t)(k4 * 4 + 1) * NMOD);
;     float4 w2 = ld_nt4(W + (size_t)(k4 * 4 + 2) * NMOD);
;     float4 w3 = ld_nt4(W + (size_t)(k4 * 4 + 3) * NMOD);
; #pragma unroll
;     for (int r = 0; r < 9; ++r) {
;       float4 s4 = *(const float4*)(sl + r * 1024 + wave * 128 + k4 * 4);
;       acc[r].x += s4.x * w0.x + s4.y * w1.x + s4.z * w2.x + s4.w * w3.x;
;       acc[r].y += s4.x * w0.y + s4.y * w1.y + s4.z * w2.y + s4.w * w3.y;
;       acc[r].z += s4.x * w0.z + s4.y * w1.z + s4.z * w2.z + s4.w * w3.z;
;       acc[r].w += s4.x * w0.w + s4.y * w1.w + s4.z * w2.w + s4.w * w3.w;
;     }
	ds_read_b128 v[114:117], v152
	ds_read_b128 v[118:121], v152 offset:4096
	ds_read_b128 v[122:125], v152 offset:8192
	ds_read_b128 v[126:129], v152 offset:12288
	ds_read_b128 v[130:133], v152 offset:16384
	ds_read_b128 v[134:137], v152 offset:20480
	ds_read_b128 v[138:141], v152 offset:24576
	ds_read_b128 v[142:145], v152 offset:28672
	ds_read_b128 v[146:149], v152 offset:32768
	s_waitcnt vmcnt(12)
	s_waitcnt lgkmcnt(8)
	v_mov_b32_e32 v66, v117
	v_pk_mul_f32 v[60:61], v[42:43], v[114:115] op_sel:[0,1]
	v_pk_mul_f32 v[62:63], v[44:45], v[114:115] op_sel:[0,1]
	v_pk_fma_f32 v[60:61], v[38:39], v[114:115], v[60:61] op_sel_hi:[1,0,1]
	v_pk_fma_f32 v[62:63], v[40:41], v[114:115], v[62:63] op_sel_hi:[1,0,1]
	v_pk_fma_f32 v[60:61], v[46:47], v[116:117], v[60:61] op_sel_hi:[1,0,1]
	v_pk_fma_f32 v[62:63], v[48:49], v[116:117], v[62:63] op_sel_hi:[1,0,1]
	v_pk_fma_f32 v[60:61], v[50:51], v[66:67], v[60:61] op_sel_hi:[1,0,1]
	v_pk_fma_f32 v[62:63], v[52:53], v[66:67], v[62:63] op_sel_hi:[1,0,1]
	v_pk_add_f32 v[22:23], v[22:23], v[60:61]
	v_pk_add_f32 v[24:25], v[24:25], v[62:63]
	s_waitcnt lgkmcnt(7)
	v_mov_b32_e32 v66, v121
	v_pk_mul_f32 v[60:61], v[42:43], v[118:119] op_sel:[0,1]
	v_pk_mul_f32 v[62:63], v[44:45], v[118:119] op_sel:[0,1]
	v_pk_fma_f32 v[60:61], v[38:39], v[118:119], v[60:61] op_sel_hi:[1,0,1]
	v_pk_fma_f32 v[62:63], v[40:41], v[118:119], v[62:63] op_sel_hi:[1,0,1]
	v_pk_fma_f32 v[60:61], v[46:47], v[120:121], v[60:61] op_sel_hi:[1,0,1]
	v_pk_fma_f32 v[62:63], v[48:49], v[120:121], v[62:63] op_sel_hi:[1,0,1]
	v_pk_fma_f32 v[60:61], v[50:51], v[66:67], v[60:61] op_sel_hi:[1,0,1]
	v_pk_fma_f32 v[62:63], v[52:53], v[66:67], v[62:63] op_sel_hi:[1,0,1]
	v_pk_add_f32 v[34:35], v[34:35], v[60:61]
	v_pk_add_f32 v[36:37], v[36:37], v[62:63]
	s_waitcnt lgkmcnt(6)
	v_mov_b32_e32 v66, v125
	v_pk_mul_f32 v[60:61], v[42:43], v[122:123] op_sel:[0,1]
	v_pk_mul_f32 v[62:63], v[44:45], v[122:123] op_sel:[0,1]
	v_pk_fma_f32 v[60:61], v[38:39], v[122:123], v[60:61] op_sel_hi:[1,0,1]
	v_pk_fma_f32 v[62:63], v[40:41], v[122:123], v[62:63] op_sel_hi:[1,0,1]
	v_pk_fma_f32 v[60:61], v[46:47], v[124:125], v[60:61] op_sel_hi:[1,0,1]
	v_pk_fma_f32 v[62:63], v[48:49], v[124:125], v[62:63] op_sel_hi:[1,0,1]
	v_pk_fma_f32 v[60:61], v[50:51], v[66:67], v[60:61] op_sel_hi:[1,0,1]
	v_pk_fma_f32 v[62:63], v[52:53], v[66:67], v[62:63] op_sel_hi:[1,0,1]
	v_pk_add_f32 v[30:31], v[30:31], v[60:61]
	v_pk_add_f32 v[32:33], v[32:33], v[62:63]
	s_waitcnt lgkmcnt(5)
	v_mov_b32_e32 v66, v129
	v_pk_mul_f32 v[60:61], v[42:43], v[126:127] op_sel:[0,1]
	v_pk_mul_f32 v[62:63], v[44:45], v[126:127] op_sel:[0,1]
	v_pk_fma_f32 v[60:61], v[38:39], v[126:127], v[60:61] op_sel_hi:[1,0,1]
	v_pk_fma_f32 v[62:63], v[40:41], v[126:127], v[62:63] op_sel_hi:[1,0,1]
	v_pk_fma_f32 v[60:61], v[46:47], v[128:129], v[60:61] op_sel_hi:[1,0,1]
	v_pk_fma_f32 v[62:63], v[48:49], v[128:129], v[62:63] op_sel_hi:[1,0,1]
	v_pk_fma_f32 v[60:61], v[50:51], v[66:67], v[60:61] op_sel_hi:[1,0,1]
	v_pk_fma_f32 v[62:63], v[52:53], v[66:67], v[62:63] op_sel_hi:[1,0,1]
	v_pk_add_f32 v[26:27], v[26:27], v[60:61]
	v_pk_add_f32 v[28:29], v[28:29], v[62:63]
	s_waitcnt lgkmcnt(4)
	v_mov_b32_e32 v66, v133
	v_pk_mul_f32 v[60:61], v[42:43], v[130:131] op_sel:[0,1]
	v_pk_mul_f32 v[62:63], v[44:45], v[130:131] op_sel:[0,1]
	v_pk_fma_f32 v[60:61], v[38:39], v[130:131], v[60:61] op_sel_hi:[1,0,1]
	v_pk_fma_f32 v[62:63], v[40:41], v[130:131], v[62:63] op_sel_hi:[1,0,1]
	v_pk_fma_f32 v[60:61], v[46:47], v[132:133], v[60:61] op_sel_hi:[1,0,1]
	v_pk_fma_f32 v[62:63], v[48:49], v[132:133], v[62:63] op_sel_hi:[1,0,1]
	v_pk_fma_f32 v[60:61], v[50:51], v[66:67], v[60:61] op_sel_hi:[1,0,1]
	v_pk_fma_f32 v[62:63], v[52:53], v[66:67], v[62:63] op_sel_hi:[1,0,1]
	v_pk_add_f32 v[18:19], v[18:19], v[60:61]
	v_pk_add_f32 v[20:21], v[20:21], v[62:63]
	s_waitcnt lgkmcnt(3)
	v_mov_b32_e32 v66, v137
	v_pk_mul_f32 v[60:61], v[42:43], v[134:135] op_sel:[0,1]
	v_pk_mul_f32 v[62:63], v[44:45], v[134:135] op_sel:[0,1]
	v_pk_fma_f32 v[60:61], v[38:39], v[134:135], v[60:61] op_sel_hi:[1,0,1]
	v_pk_fma_f32 v[62:63], v[40:41], v[134:135], v[62:63] op_sel_hi:[1,0,1]
	v_pk_fma_f32 v[60:61], v[46:47], v[136:137], v[60:61] op_sel_hi:[1,0,1]
	v_pk_fma_f32 v[62:63], v[48:49], v[136:137], v[62:63] op_sel_hi:[1,0,1]
	v_pk_fma_f32 v[60:61], v[50:51], v[66:67], v[60:61] op_sel_hi:[1,0,1]
	v_pk_fma_f32 v[62:63], v[52:53], v[66:67], v[62:63] op_sel_hi:[1,0,1]
	v_pk_add_f32 v[14:15], v[14:15], v[60:61]
	v_pk_add_f32 v[16:17], v[16:17], v[62:63]
	s_waitcnt lgkmcnt(2)
	v_mov_b32_e32 v66, v141
	v_pk_mul_f32 v[60:61], v[42:43], v[138:139] op_sel:[0,1]
	v_pk_mul_f32 v[62:63], v[44:45], v[138:139] op_sel:[0,1]
	v_pk_fma_f32 v[60:61], v[38:39], v[138:139], v[60:61] op_sel_hi:[1,0,1]
	v_pk_fma_f32 v[62:63], v[40:41], v[138:139], v[62:63] op_sel_hi:[1,0,1]
	v_pk_fma_f32 v[60:61], v[46:47], v[140:141], v[60:61] op_sel_hi:[1,0,1]
	v_pk_fma_f32 v[62:63], v[48:49], v[140:141], v[62:63] op_sel_hi:[1,0,1]
	v_pk_fma_f32 v[60:61], v[50:51], v[66:67], v[60:61] op_sel_hi:[1,0,1]
	v_pk_fma_f32 v[62:63], v[52:53], v[66:67], v[62:63] op_sel_hi:[1,0,1]
	v_pk_add_f32 v[10:11], v[10:11], v[60:61]
	v_pk_add_f32 v[12:13], v[12:13], v[62:63]
	s_waitcnt lgkmcnt(1)
	v_mov_b32_e32 v66, v145
	v_pk_mul_f32 v[60:61], v[42:43], v[142:143] op_sel:[0,1]
	v_pk_mul_f32 v[62:63], v[44:45], v[142:143] op_sel:[0,1]
	v_pk_fma_f32 v[60:61], v[38:39], v[142:143], v[60:61] op_sel_hi:[1,0,1]
	v_pk_fma_f32 v[62:63], v[40:41], v[142:143], v[62:63] op_sel_hi:[1,0,1]
	v_pk_fma_f32 v[60:61], v[46:47], v[144:145], v[60:61] op_sel_hi:[1,0,1]
	v_pk_fma_f32 v[62:63], v[48:49], v[144:145], v[62:63] op_sel_hi:[1,0,1]
	v_pk_fma_f32 v[60:61], v[50:51], v[66:67], v[60:61] op_sel_hi:[1,0,1]
	v_pk_fma_f32 v[62:63], v[52:53], v[66:67], v[62:63] op_sel_hi:[1,0,1]
	v_pk_add_f32 v[6:7], v[6:7], v[60:61]
	v_pk_add_f32 v[8:9], v[8:9], v[62:63]
	s_waitcnt lgkmcnt(0)
; __device__ __forceinline__ float4 ld_nt4(const float* p) { const f32x4v v = __builtin_nontemporal_load((const f32x4v*)p); return make_float4(v[0], v[1], v[2], v[3]); }
; DI void p0_mod_item(const Params& P, unsigned char* lds, int idx, const int tid) {
;     ...
;   for (int k4 = 0; k4 < 32; ++k4) {
;     float4 w0 = ld_nt4(W + (size_t)(k4 * 4 + 0) * NMOD);
;     float4 w1 = ld_nt4(W + (size_t)(k4 * 4 + 1) * NMOD);
;     float4 w2 = ld_nt4(W + (size_t)(k4 * 4 + 2) * NMOD);
;     float4 w3 = ld_nt4(W + (size_t)(k4 * 4 + 3) * NMOD);
; #pragma unroll
;     for (int r = 0; r < 9; ++r) {
;       float4 s4 = *(const float4*)(sl + r * 1024 + wave * 128 + k4 * 4);
;       acc[r].x += s4.x * w0.x + s4.y * w1.x + s4.z * w2.x + s4.w * w3.x;
;       acc[r].y += s4.x * w0.y + s4.y * w1.y + s4.z * w2.y + s4.w * w3.y;
;       acc[r].z += s4.x * w0.z + s4.y * w1.z + s4.z * w2.z + s4.w * w3.z;
;       acc[r].w += s4.x * w0.w + s4.y * w1.w + s4.z * w2.w + s4.w * w3.w;
;     }
	v_mov_b32_e32 v66, v149
	v_pk_mul_f32 v[60:61], v[42:43], v[146:147] op_sel:[0,1]
	v_pk_mul_f32 v[62:63], v[44:45], v[146:147] op_sel:[0,1]
	v_pk_fma_f32 v[60:61], v[38:39], v[146:147], v[60:61] op_sel_hi:[1,0,1]
	v_pk_fma_f32 v[62:63], v[40:41], v[146:147], v[62:63] op_sel_hi:[1,0,1]
	v_pk_fma_f32 v[60:61], v[46:47], v[148:149], v[60:61] op_sel_hi:[1,0,1]
	v_pk_fma_f32 v[62:63], v[48:49], v[148:149], v[62:63] op_sel_hi:[1,0,1]
	v_pk_fma_f32 v[60:61], v[50:51], v[66:67], v[60:61] op_sel_hi:[1,0,1]
	v_pk_fma_f32 v[62:63], v[52:53], v[66:67], v[62:63] op_sel_hi:[1,0,1]
	v_pk_add_f32 v[2:3], v[2:3], v[60:61]
	v_pk_add_f32 v[4:5], v[4:5], v[62:63]
	ds_read_b128 v[114:117], v152 offset:16
	ds_read_b128 v[118:121], v152 offset:4112
	ds_read_b128 v[122:125], v152 offset:8208
	ds_read_b128 v[126:129], v152 offset:12304
	ds_read_b128 v[130:133], v152 offset:16400
	ds_read_b128 v[134:137], v152 offset:20496
	ds_read_b128 v[138:141], v152 offset:24592
	ds_read_b128 v[142:145], v152 offset:28688
	ds_read_b128 v[146:149], v152 offset:32784
	s_waitcnt vmcnt(8)
	s_waitcnt lgkmcnt(8)
	v_mov_b32_e32 v66, v117
	v_pk_mul_f32 v[60:61], v[164:165], v[114:115] op_sel:[0,1]
	v_pk_mul_f32 v[62:63], v[166:167], v[114:115] op_sel:[0,1]
	v_pk_fma_f32 v[60:61], v[160:161], v[114:115], v[60:61] op_sel_hi:[1,0,1]
	v_pk_fma_f32 v[62:63], v[162:163], v[114:115], v[62:63] op_sel_hi:[1,0,1]
	v_pk_fma_f32 v[60:61], v[168:169], v[116:117], v[60:61] op_sel_hi:[1,0,1]
	v_pk_fma_f32 v[62:63], v[170:171], v[116:117], v[62:63] op_sel_hi:[1,0,1]
	v_pk_fma_f32 v[60:61], v[172:173], v[66:67], v[60:61] op_sel_hi:[1,0,1]
	v_pk_fma_f32 v[62:63], v[174:175], v[66:67], v[62:63] op_sel_hi:[1,0,1]
	v_pk_add_f32 v[22:23], v[22:23], v[60:61]
	v_pk_add_f32 v[24:25], v[24:25], v[62:63]
	s_waitcnt lgkmcnt(7)
	v_mov_b32_e32 v66, v121
	v_pk_mul_f32 v[60:61], v[164:165], v[118:119] op_sel:[0,1]
	v_pk_mul_f32 v[62:63], v[166:167], v[118:119] op_sel:[0,1]
	v_pk_fma_f32 v[60:61], v[160:161], v[118:119], v[60:61] op_sel_hi:[1,0,1]
	v_pk_fma_f32 v[62:63], v[162:163], v[118:119], v[62:63] op_sel_hi:[1,0,1]
	v_pk_fma_f32 v[60:61], v[168:169], v[120:121], v[60:61] op_sel_hi:[1,0,1]
	v_pk_fma_f32 v[62:63], v[170:171], v[120:121], v[62:63] op_sel_hi:[1,0,1]
	v_pk_fma_f32 v[60:61], v[172:173], v[66:67], v[60:61] op_sel_hi:[1,0,1]
	v_pk_fma_f32 v[62:63], v[174:175], v[66:67], v[62:63] op_sel_hi:[1,0,1]
	v_pk_add_f32 v[34:35], v[34:35], v[60:61]
	v_pk_add_f32 v[36:37], v[36:37], v[62:63]
	s_waitcnt lgkmcnt(6)
	v_mov_b32_e32 v66, v125
	v_pk_mul_f32 v[60:61], v[164:165], v[122:123] op_sel:[0,1]
	v_pk_mul_f32 v[62:63], v[166:167], v[122:123] op_sel:[0,1]
	v_pk_fma_f32 v[60:61], v[160:161], v[122:123], v[60:61] op_sel_hi:[1,0,1]
	v_pk_fma_f32 v[62:63], v[162:163], v[122:123], v[62:63] op_sel_hi:[1,0,1]
	v_pk_fma_f32 v[60:61], v[168:169], v[124:125], v[60:61] op_sel_hi:[1,0,1]
	v_pk_fma_f32 v[62:63], v[170:171], v[124:125], v[62:63] op_sel_hi:[1,0,1]
	v_pk_fma_f32 v[60:61], v[172:173], v[66:67], v[60:61] op_sel_hi:[1,0,1]
	v_pk_fma_f32 v[62:63], v[174:175], v[66:67], v[62:63] op_sel_hi:[1,0,1]
	v_pk_add_f32 v[30:31], v[30:31], v[60:61]
	v_pk_add_f32 v[32:33], v[32:33], v[62:63]
	s_waitcnt lgkmcnt(5)
	v_mov_b32_e32 v66, v129
	v_pk_mul_f32 v[60:61], v[164:165], v[126:127] op_sel:[0,1]
	v_pk_mul_f32 v[62:63], v[166:167], v[126:127] op_sel:[0,1]
	v_pk_fma_f32 v[60:61], v[160:161], v[126:127], v[60:61] op_sel_hi:[1,0,1]
	v_pk_fma_f32 v[62:63], v[162:163], v[126:127], v[62:63] op_sel_hi:[1,0,1]
	v_pk_fma_f32 v[60:61], v[168:169], v[128:129], v[60:61] op_sel_hi:[1,0,1]
	v_pk_fma_f32 v[62:63], v[170:171], v[128:129], v[62:63] op_sel_hi:[1,0,1]
	v_pk_fma_f32 v[60:61], v[172:173], v[66:67], v[60:61] op_sel_hi:[1,0,1]
	v_pk_fma_f32 v[62:63], v[174:175], v[66:67], v[62:63] op_sel_hi:[1,0,1]
	v_pk_add_f32 v[26:27], v[26:27], v[60:61]
	v_pk_add_f32 v[28:29], v[28:29], v[62:63]
	s_waitcnt lgkmcnt(4)
	v_mov_b32_e32 v66, v133
	v_pk_mul_f32 v[60:61], v[164:165], v[130:131] op_sel:[0,1]
	v_pk_mul_f32 v[62:63], v[166:167], v[130:131] op_sel:[0,1]
	v_pk_fma_f32 v[60:61], v[160:161], v[130:131], v[60:61] op_sel_hi:[1,0,1]
	v_pk_fma_f32 v[62:63], v[162:163], v[130:131], v[62:63] op_sel_hi:[1,0,1]
	v_pk_fma_f32 v[60:61], v[168:169], v[132:133], v[60:61] op_sel_hi:[1,0,1]
	v_pk_fma_f32 v[62:63], v[170:171], v[132:133], v[62:63] op_sel_hi:[1,0,1]
	v_pk_fma_f32 v[60:61], v[172:173], v[66:67], v[60:61] op_sel_hi:[1,0,1]
	v_pk_fma_f32 v[62:63], v[174:175], v[66:67], v[62:63] op_sel_hi:[1,0,1]
	v_pk_add_f32 v[18:19], v[18:19], v[60:61]
	v_pk_add_f32 v[20:21], v[20:21], v[62:63]
	s_waitcnt lgkmcnt(3)
	v_mov_b32_e32 v66, v137
	v_pk_mul_f32 v[60:61], v[164:165], v[134:135] op_sel:[0,1]
	v_pk_mul_f32 v[62:63], v[166:167], v[134:135] op_sel:[0,1]
	v_pk_fma_f32 v[60:61], v[160:161], v[134:135], v[60:61] op_sel_hi:[1,0,1]
	v_pk_fma_f32 v[62:63], v[162:163], v[134:135], v[62:63] op_sel_hi:[1,0,1]
	v_pk_fma_f32 v[60:61], v[168:169], v[136:137], v[60:61] op_sel_hi:[1,0,1]
	v_pk_fma_f32 v[62:63], v[170:171], v[136:137], v[62:63] op_sel_hi:[1,0,1]
	v_pk_fma_f32 v[60:61], v[172:173], v[66:67], v[60:61] op_sel_hi:[1,0,1]
	v_pk_fma_f32 v[62:63], v[174:175], v[66:67], v[62:63] op_sel_hi:[1,0,1]
	v_pk_add_f32 v[14:15], v[14:15], v[60:61]
	v_pk_add_f32 v[16:17], v[16:17], v[62:63]
	s_waitcnt lgkmcnt(2)
	v_mov_b32_e32 v66, v141
	v_pk_mul_f32 v[60:61], v[164:165], v[138:139] op_sel:[0,1]
	v_pk_mul_f32 v[62:63], v[166:167], v[138:139] op_sel:[0,1]
	v_pk_fma_f32 v[60:61], v[160:161], v[138:139], v[60:61] op_sel_hi:[1,0,1]
	v_pk_fma_f32 v[62:63], v[162:163], v[138:139], v[62:63] op_sel_hi:[1,0,1]
	v_pk_fma_f32 v[60:61], v[168:169], v[140:141], v[60:61] op_sel_hi:[1,0,1]
	v_pk_fma_f32 v[62:63], v[170:171], v[140:141], v[62:63] op_sel_hi:[1,0,1]
	v_pk_fma_f32 v[60:61], v[172:173], v[66:67], v[60:61] op_sel_hi:[1,0,1]
	v_pk_fma_f32 v[62:63], v[174:175], v[66:67], v[62:63] op_sel_hi:[1,0,1]
	v_pk_add_f32 v[10:11], v[10:11], v[60:61]
	v_pk_add_f32 v[12:13], v[12:13], v[62:63]
	s_waitcnt lgkmcnt(1)
; __device__ __forceinline__ float4 ld_nt4(const float* p) { const f32x4v v = __builtin_nontemporal_load((const f32x4v*)p); return make_float4(v[0], v[1], v[2], v[3]); }
; DI void p0_mod_item(const Params& P, unsigned char* lds, int idx, const int tid) {
;     ...
;   for (int k4 = 0; k4 < 32; ++k4) {
;     float4 w0 = ld_nt4(W + (size_t)(k4 * 4 + 0) * NMOD);
;     float4 w1 = ld_nt4(W + (size_t)(k4 * 4 + 1) * NMOD);
;     float4 w2 = ld_nt4(W + (size_t)(k4 * 4 + 2) * NMOD);
;     float4 w3 = ld_nt4(W + (size_t)(k4 * 4 + 3) * NMOD);
; #pragma unroll
;     for (int r = 0; r < 9; ++r) {
;       float4 s4 = *(const float4*)(sl + r * 1024 + wave * 128 + k4 * 4);
;       acc[r].x += s4.x * w0.x + s4.y * w1.x + s4.z * w2.x + s4.w * w3.x;
;       acc[r].y += s4.x * w0.y + s4.y * w1.y + s4.z * w2.y + s4.w * w3.y;
;       acc[r].z += s4.x * w0.z + s4.y * w1.z + s4.z * w2.z + s4.w * w3.z;
;       acc[r].w += s4.x * w0.w + s4.y * w1.w + s4.z * w2.w + s4.w * w3.w;
;     }
	v_mov_b32_e32 v66, v145
	v_pk_mul_f32 v[60:61], v[164:165], v[142:143] op_sel:[0,1]
	v_pk_mul_f32 v[62:63], v[166:167], v[142:143] op_sel:[0,1]
	v_pk_fma_f32 v[60:61], v[160:161], v[142:143], v[60:61] op_sel_hi:[1,0,1]
	v_pk_fma_f32 v[62:63], v[162:163], v[142:143], v[62:63] op_sel_hi:[1,0,1]
	v_pk_fma_f32 v[60:61], v[168:169], v[144:145], v[60:61] op_sel_hi:[1,0,1]
	v_pk_fma_f32 v[62:63], v[170:171], v[144:145], v[62:63] op_sel_hi:[1,0,1]
	v_pk_fma_f32 v[60:61], v[172:173], v[66:67], v[60:61] op_sel_hi:[1,0,1]
	v_pk_fma_f32 v[62:63], v[174:175], v[66:67], v[62:63] op_sel_hi:[1,0,1]
	v_pk_add_f32 v[6:7], v[6:7], v[60:61]
	v_pk_add_f32 v[8:9], v[8:9], v[62:63]
	s_waitcnt lgkmcnt(0)
	v_mov_b32_e32 v66, v149
	v_pk_mul_f32 v[60:61], v[164:165], v[146:147] op_sel:[0,1]
	v_pk_mul_f32 v[62:63], v[166:167], v[146:147] op_sel:[0,1]
	v_pk_fma_f32 v[60:61], v[160:161], v[146:147], v[60:61] op_sel_hi:[1,0,1]
	v_pk_fma_f32 v[62:63], v[162:163], v[146:147], v[62:63] op_sel_hi:[1,0,1]
	v_pk_fma_f32 v[60:61], v[168:169], v[148:149], v[60:61] op_sel_hi:[1,0,1]
	v_pk_fma_f32 v[62:63], v[170:171], v[148:149], v[62:63] op_sel_hi:[1,0,1]
	v_pk_fma_f32 v[60:61], v[172:173], v[66:67], v[60:61] op_sel_hi:[1,0,1]
	v_pk_fma_f32 v[62:63], v[174:175], v[66:67], v[62:63] op_sel_hi:[1,0,1]
	v_pk_add_f32 v[2:3], v[2:3], v[60:61]
	v_pk_add_f32 v[4:5], v[4:5], v[62:63]
	ds_read_b128 v[114:117], v152 offset:32
	ds_read_b128 v[118:121], v152 offset:4128
	ds_read_b128 v[122:125], v152 offset:8224
	ds_read_b128 v[126:129], v152 offset:12320
	ds_read_b128 v[130:133], v152 offset:16416
	ds_read_b128 v[134:137], v152 offset:20512
	ds_read_b128 v[138:141], v152 offset:24608
	ds_read_b128 v[142:145], v152 offset:28704
	ds_read_b128 v[146:149], v152 offset:32800
	s_waitcnt vmcnt(4)
	s_waitcnt lgkmcnt(8)
	v_mov_b32_e32 v66, v117
	v_pk_mul_f32 v[60:61], v[180:181], v[114:115] op_sel:[0,1]
	v_pk_mul_f32 v[62:63], v[182:183], v[114:115] op_sel:[0,1]
	v_pk_fma_f32 v[60:61], v[176:177], v[114:115], v[60:61] op_sel_hi:[1,0,1]
	v_pk_fma_f32 v[62:63], v[178:179], v[114:115], v[62:63] op_sel_hi:[1,0,1]
	v_pk_fma_f32 v[60:61], v[184:185], v[116:117], v[60:61] op_sel_hi:[1,0,1]
	v_pk_fma_f32 v[62:63], v[186:187], v[116:117], v[62:63] op_sel_hi:[1,0,1]
	v_pk_fma_f32 v[60:61], v[188:189], v[66:67], v[60:61] op_sel_hi:[1,0,1]
	v_pk_fma_f32 v[62:63], v[190:191], v[66:67], v[62:63] op_sel_hi:[1,0,1]
	v_pk_add_f32 v[22:23], v[22:23], v[60:61]
	v_pk_add_f32 v[24:25], v[24:25], v[62:63]
	s_waitcnt lgkmcnt(7)
	v_mov_b32_e32 v66, v121
	v_pk_mul_f32 v[60:61], v[180:181], v[118:119] op_sel:[0,1]
	v_pk_mul_f32 v[62:63], v[182:183], v[118:119] op_sel:[0,1]
	v_pk_fma_f32 v[60:61], v[176:177], v[118:119], v[60:61] op_sel_hi:[1,0,1]
	v_pk_fma_f32 v[62:63], v[178:179], v[118:119], v[62:63] op_sel_hi:[1,0,1]
	v_pk_fma_f32 v[60:61], v[184:185], v[120:121], v[60:61] op_sel_hi:[1,0,1]
	v_pk_fma_f32 v[62:63], v[186:187], v[120:121], v[62:63] op_sel_hi:[1,0,1]
	v_pk_fma_f32 v[60:61], v[188:189], v[66:67], v[60:61] op_sel_hi:[1,0,1]
	v_pk_fma_f32 v[62:63], v[190:191], v[66:67], v[62:63] op_sel_hi:[1,0,1]
	v_pk_add_f32 v[34:35], v[34:35], v[60:61]
	v_pk_add_f32 v[36:37], v[36:37], v[62:63]
	s_waitcnt lgkmcnt(6)
	v_mov_b32_e32 v66, v125
	v_pk_mul_f32 v[60:61], v[180:181], v[122:123] op_sel:[0,1]
	v_pk_mul_f32 v[62:63], v[182:183], v[122:123] op_sel:[0,1]
	v_pk_fma_f32 v[60:61], v[176:177], v[122:123], v[60:61] op_sel_hi:[1,0,1]
	v_pk_fma_f32 v[62:63], v[178:179], v[122:123], v[62:63] op_sel_hi:[1,0,1]
	v_pk_fma_f32 v[60:61], v[184:185], v[124:125], v[60:61] op_sel_hi:[1,0,1]
	v_pk_fma_f32 v[62:63], v[186:187], v[124:125], v[62:63] op_sel_hi:[1,0,1]
	v_pk_fma_f32 v[60:61], v[188:189], v[66:67], v[60:61] op_sel_hi:[1,0,1]
	v_pk_fma_f32 v[62:63], v[190:191], v[66:67], v[62:63] op_sel_hi:[1,0,1]
	v_pk_add_f32 v[30:31], v[30:31], v[60:61]
	v_pk_add_f32 v[32:33], v[32:33], v[62:63]
	s_waitcnt lgkmcnt(5)
	v_mov_b32_e32 v66, v129
	v_pk_mul_f32 v[60:61], v[180:181], v[126:127] op_sel:[0,1]
	v_pk_mul_f32 v[62:63], v[182:183], v[126:127] op_sel:[0,1]
	v_pk_fma_f32 v[60:61], v[176:177], v[126:127], v[60:61] op_sel_hi:[1,0,1]
	v_pk_fma_f32 v[62:63], v[178:179], v[126:127], v[62:63] op_sel_hi:[1,0,1]
	v_pk_fma_f32 v[60:61], v[184:185], v[128:129], v[60:61] op_sel_hi:[1,0,1]
	v_pk_fma_f32 v[62:63], v[186:187], v[128:129], v[62:63] op_sel_hi:[1,0,1]
	v_pk_fma_f32 v[60:61], v[188:189], v[66:67], v[60:61] op_sel_hi:[1,0,1]
	v_pk_fma_f32 v[62:63], v[190:191], v[66:67], v[62:63] op_sel_hi:[1,0,1]
	v_pk_add_f32 v[26:27], v[26:27], v[60:61]
	v_pk_add_f32 v[28:29], v[28:29], v[62:63]
	s_waitcnt lgkmcnt(4)
	v_mov_b32_e32 v66, v133
	v_pk_mul_f32 v[60:61], v[180:181], v[130:131] op_sel:[0,1]
	v_pk_mul_f32 v[62:63], v[182:183], v[130:131] op_sel:[0,1]
	v_pk_fma_f32 v[60:61], v[176:177], v[130:131], v[60:61] op_sel_hi:[1,0,1]
	v_pk_fma_f32 v[62:63], v[178:179], v[130:131], v[62:63] op_sel_hi:[1,0,1]
	v_pk_fma_f32 v[60:61], v[184:185], v[132:133], v[60:61] op_sel_hi:[1,0,1]
	v_pk_fma_f32 v[62:63], v[186:187], v[132:133], v[62:63] op_sel_hi:[1,0,1]
	v_pk_fma_f32 v[60:61], v[188:189], v[66:67], v[60:61] op_sel_hi:[1,0,1]
	v_pk_fma_f32 v[62:63], v[190:191], v[66:67], v[62:63] op_sel_hi:[1,0,1]
	v_pk_add_f32 v[18:19], v[18:19], v[60:61]
	v_pk_add_f32 v[20:21], v[20:21], v[62:63]
	s_waitcnt lgkmcnt(3)
	v_mov_b32_e32 v66, v137
	v_pk_mul_f32 v[60:61], v[180:181], v[134:135] op_sel:[0,1]
	v_pk_mul_f32 v[62:63], v[182:183], v[134:135] op_sel:[0,1]
	v_pk_fma_f32 v[60:61], v[176:177], v[134:135], v[60:61] op_sel_hi:[1,0,1]
	v_pk_fma_f32 v[62:63], v[178:179], v[134:135], v[62:63] op_sel_hi:[1,0,1]
	v_pk_fma_f32 v[60:61], v[184:185], v[136:137], v[60:61] op_sel_hi:[1,0,1]
	v_pk_fma_f32 v[62:63], v[186:187], v[136:137], v[62:63] op_sel_hi:[1,0,1]
	v_pk_fma_f32 v[60:61], v[188:189], v[66:67], v[60:61] op_sel_hi:[1,0,1]
	v_pk_fma_f32 v[62:63], v[190:191], v[66:67], v[62:63] op_sel_hi:[1,0,1]
	v_pk_add_f32 v[14:15], v[14:15], v[60:61]
	v_pk_add_f32 v[16:17], v[16:17], v[62:63]
	s_waitcnt lgkmcnt(2)
; __device__ __forceinline__ float4 ld_nt4(const float* p) { const f32x4v v = __builtin_nontemporal_load((const f32x4v*)p); return make_float4(v[0], v[1], v[2], v[3]); }
; DI void p0_mod_item(const Params& P, unsigned char* lds, int idx, const int tid) {
;     ...
;   for (int k4 = 0; k4 < 32; ++k4) {
;     float4 w0 = ld_nt4(W + (size_t)(k4 * 4 + 0) * NMOD);
;     float4 w1 = ld_nt4(W + (size_t)(k4 * 4 + 1) * NMOD);
;     float4 w2 = ld_nt4(W + (size_t)(k4 * 4 + 2) * NMOD);
;     float4 w3 = ld_nt4(W + (size_t)(k4 * 4 + 3) * NMOD);
; #pragma unroll
;     for (int r = 0; r < 9; ++r) {
;       float4 s4 = *(const float4*)(sl + r * 1024 + wave * 128 + k4 * 4);
;       acc[r].x += s4.x * w0.x + s4.y * w1.x + s4.z * w2.x + s4.w * w3.x;
;       acc[r].y += s4.x * w0.y + s4.y * w1.y + s4.z * w2.y + s4.w * w3.y;
;       acc[r].z += s4.x * w0.z + s4.y * w1.z + s4.z * w2.z + s4.w * w3.z;
;       acc[r].w += s4.x * w0.w + s4.y * w1.w + s4.z * w2.w + s4.w * w3.w;
;     }
;   }
	v_mov_b32_e32 v66, v141
	v_pk_mul_f32 v[60:61], v[180:181], v[138:139] op_sel:[0,1]
	v_pk_mul_f32 v[62:63], v[182:183], v[138:139] op_sel:[0,1]
	v_pk_fma_f32 v[60:61], v[176:177], v[138:139], v[60:61] op_sel_hi:[1,0,1]
	v_pk_fma_f32 v[62:63], v[178:179], v[138:139], v[62:63] op_sel_hi:[1,0,1]
	v_pk_fma_f32 v[60:61], v[184:185], v[140:141], v[60:61] op_sel_hi:[1,0,1]
	v_pk_fma_f32 v[62:63], v[186:187], v[140:141], v[62:63] op_sel_hi:[1,0,1]
	v_pk_fma_f32 v[60:61], v[188:189], v[66:67], v[60:61] op_sel_hi:[1,0,1]
	v_pk_fma_f32 v[62:63], v[190:191], v[66:67], v[62:63] op_sel_hi:[1,0,1]
	v_pk_add_f32 v[10:11], v[10:11], v[60:61]
	v_pk_add_f32 v[12:13], v[12:13], v[62:63]
	s_waitcnt lgkmcnt(1)
	v_mov_b32_e32 v66, v145
	v_pk_mul_f32 v[60:61], v[180:181], v[142:143] op_sel:[0,1]
	v_pk_mul_f32 v[62:63], v[182:183], v[142:143] op_sel:[0,1]
	v_pk_fma_f32 v[60:61], v[176:177], v[142:143], v[60:61] op_sel_hi:[1,0,1]
	v_pk_fma_f32 v[62:63], v[178:179], v[142:143], v[62:63] op_sel_hi:[1,0,1]
	v_pk_fma_f32 v[60:61], v[184:185], v[144:145], v[60:61] op_sel_hi:[1,0,1]
	v_pk_fma_f32 v[62:63], v[186:187], v[144:145], v[62:63] op_sel_hi:[1,0,1]
	v_pk_fma_f32 v[60:61], v[188:189], v[66:67], v[60:61] op_sel_hi:[1,0,1]
	v_pk_fma_f32 v[62:63], v[190:191], v[66:67], v[62:63] op_sel_hi:[1,0,1]
	v_pk_add_f32 v[6:7], v[6:7], v[60:61]
	v_pk_add_f32 v[8:9], v[8:9], v[62:63]
	s_waitcnt lgkmcnt(0)
	v_mov_b32_e32 v66, v149
	v_pk_mul_f32 v[60:61], v[180:181], v[146:147] op_sel:[0,1]
	v_pk_mul_f32 v[62:63], v[182:183], v[146:147] op_sel:[0,1]
	v_pk_fma_f32 v[60:61], v[176:177], v[146:147], v[60:61] op_sel_hi:[1,0,1]
	v_pk_fma_f32 v[62:63], v[178:179], v[146:147], v[62:63] op_sel_hi:[1,0,1]
	v_pk_fma_f32 v[60:61], v[184:185], v[148:149], v[60:61] op_sel_hi:[1,0,1]
	v_pk_fma_f32 v[62:63], v[186:187], v[148:149], v[62:63] op_sel_hi:[1,0,1]
	v_pk_fma_f32 v[60:61], v[188:189], v[66:67], v[60:61] op_sel_hi:[1,0,1]
	v_pk_fma_f32 v[62:63], v[190:191], v[66:67], v[62:63] op_sel_hi:[1,0,1]
	v_pk_add_f32 v[2:3], v[2:3], v[60:61]
	v_pk_add_f32 v[4:5], v[4:5], v[62:63]
	ds_read_b128 v[114:117], v152 offset:48
	ds_read_b128 v[118:121], v152 offset:4144
	ds_read_b128 v[122:125], v152 offset:8240
	ds_read_b128 v[126:129], v152 offset:12336
	ds_read_b128 v[130:133], v152 offset:16432
	ds_read_b128 v[134:137], v152 offset:20528
	ds_read_b128 v[138:141], v152 offset:24624
	ds_read_b128 v[142:145], v152 offset:28720
	ds_read_b128 v[146:149], v152 offset:32816
	s_waitcnt vmcnt(0)
	s_waitcnt lgkmcnt(8)
	v_mov_b32_e32 v66, v117
	v_pk_mul_f32 v[60:61], v[196:197], v[114:115] op_sel:[0,1]
	v_pk_mul_f32 v[62:63], v[198:199], v[114:115] op_sel:[0,1]
	v_pk_fma_f32 v[60:61], v[192:193], v[114:115], v[60:61] op_sel_hi:[1,0,1]
	v_pk_fma_f32 v[62:63], v[194:195], v[114:115], v[62:63] op_sel_hi:[1,0,1]
	v_pk_fma_f32 v[60:61], v[200:201], v[116:117], v[60:61] op_sel_hi:[1,0,1]
	v_pk_fma_f32 v[62:63], v[202:203], v[116:117], v[62:63] op_sel_hi:[1,0,1]
	v_pk_fma_f32 v[60:61], v[204:205], v[66:67], v[60:61] op_sel_hi:[1,0,1]
	v_pk_fma_f32 v[62:63], v[206:207], v[66:67], v[62:63] op_sel_hi:[1,0,1]
	v_pk_add_f32 v[22:23], v[22:23], v[60:61]
	v_pk_add_f32 v[24:25], v[24:25], v[62:63]
	s_waitcnt lgkmcnt(7)
	v_mov_b32_e32 v66, v121
	v_pk_mul_f32 v[60:61], v[196:197], v[118:119] op_sel:[0,1]
	v_pk_mul_f32 v[62:63], v[198:199], v[118:119] op_sel:[0,1]
	v_pk_fma_f32 v[60:61], v[192:193], v[118:119], v[60:61] op_sel_hi:[1,0,1]
	v_pk_fma_f32 v[62:63], v[194:195], v[118:119], v[62:63] op_sel_hi:[1,0,1]
	v_pk_fma_f32 v[60:61], v[200:201], v[120:121], v[60:61] op_sel_hi:[1,0,1]
	v_pk_fma_f32 v[62:63], v[202:203], v[120:121], v[62:63] op_sel_hi:[1,0,1]
	v_pk_fma_f32 v[60:61], v[204:205], v[66:67], v[60:61] op_sel_hi:[1,0,1]
	v_pk_fma_f32 v[62:63], v[206:207], v[66:67], v[62:63] op_sel_hi:[1,0,1]
	v_pk_add_f32 v[34:35], v[34:35], v[60:61]
	v_pk_add_f32 v[36:37], v[36:37], v[62:63]
	s_waitcnt lgkmcnt(6)
	v_mov_b32_e32 v66, v125
	v_pk_mul_f32 v[60:61], v[196:197], v[122:123] op_sel:[0,1]
	v_pk_mul_f32 v[62:63], v[198:199], v[122:123] op_sel:[0,1]
	v_pk_fma_f32 v[60:61], v[192:193], v[122:123], v[60:61] op_sel_hi:[1,0,1]
	v_pk_fma_f32 v[62:63], v[194:195], v[122:123], v[62:63] op_sel_hi:[1,0,1]
	v_pk_fma_f32 v[60:61], v[200:201], v[124:125], v[60:61] op_sel_hi:[1,0,1]
	v_pk_fma_f32 v[62:63], v[202:203], v[124:125], v[62:63] op_sel_hi:[1,0,1]
	v_pk_fma_f32 v[60:61], v[204:205], v[66:67], v[60:61] op_sel_hi:[1,0,1]
	v_pk_fma_f32 v[62:63], v[206:207], v[66:67], v[62:63] op_sel_hi:[1,0,1]
	v_pk_add_f32 v[30:31], v[30:31], v[60:61]
	v_pk_add_f32 v[32:33], v[32:33], v[62:63]
	s_waitcnt lgkmcnt(5)
	v_mov_b32_e32 v66, v129
	v_pk_mul_f32 v[60:61], v[196:197], v[126:127] op_sel:[0,1]
	v_pk_mul_f32 v[62:63], v[198:199], v[126:127] op_sel:[0,1]
	v_pk_fma_f32 v[60:61], v[192:193], v[126:127], v[60:61] op_sel_hi:[1,0,1]
	v_pk_fma_f32 v[62:63], v[194:195], v[126:127], v[62:63] op_sel_hi:[1,0,1]
	v_pk_fma_f32 v[60:61], v[200:201], v[128:129], v[60:61] op_sel_hi:[1,0,1]
	v_pk_fma_f32 v[62:63], v[202:203], v[128:129], v[62:63] op_sel_hi:[1,0,1]
	v_pk_fma_f32 v[60:61], v[204:205], v[66:67], v[60:61] op_sel_hi:[1,0,1]
	v_pk_fma_f32 v[62:63], v[206:207], v[66:67], v[62:63] op_sel_hi:[1,0,1]
	v_pk_add_f32 v[26:27], v[26:27], v[60:61]
	v_pk_add_f32 v[28:29], v[28:29], v[62:63]
	s_waitcnt lgkmcnt(4)
; DI void p0_mod_item(const Params& P, unsigned char* lds, int idx, const int tid) {
;     ...
;     for (int r = 0; r < 9; ++r) {
;       float4 s4 = *(const float4*)(sl + r * 1024 + wave * 128 + k4 * 4);
;       acc[r].x += s4.x * w0.x + s4.y * w1.x + s4.z * w2.x + s4.w * w3.x;
;       acc[r].y += s4.x * w0.y + s4.y * w1.y + s4.z * w2.y + s4.w * w3.y;
;       acc[r].z += s4.x * w0.z + s4.y * w1.z + s4.z * w2.z + s4.w * w3.z;
;       acc[r].w += s4.x * w0.w + s4.y * w1.w + s4.z * w2.w + s4.w * w3.w;
;     }
;   }
; #pragma unroll
;   for (int r = 0; r < 9; ++r) *(float4*)(red + (wave * 9 + r) * 256 + lane * 4) = acc[r];
;   __syncthreads();
;   float* mod = (float*)(P.ws + WS_MOD);
;   for (int o = tid; o < 2304; o += 512) {
;     int r = o >> 8, cc = o & 255;
;     float sacc = P.b_ada[l * NMOD + cch * 256 + cc];
; #pragma unroll
;     for (int w = 0; w < 8; ++w) sacc += red[(w * 9 + r) * 256 + cc];
;     mod[((size_t)l * 9 + r) * NMOD + cch * 256 + cc] = sacc;
	v_mov_b32_e32 v66, v133
	v_pk_mul_f32 v[60:61], v[196:197], v[130:131] op_sel:[0,1]
	v_pk_mul_f32 v[62:63], v[198:199], v[130:131] op_sel:[0,1]
	v_pk_fma_f32 v[60:61], v[192:193], v[130:131], v[60:61] op_sel_hi:[1,0,1]
	v_pk_fma_f32 v[62:63], v[194:195], v[130:131], v[62:63] op_sel_hi:[1,0,1]
	v_pk_fma_f32 v[60:61], v[200:201], v[132:133], v[60:61] op_sel_hi:[1,0,1]
	v_pk_fma_f32 v[62:63], v[202:203], v[132:133], v[62:63] op_sel_hi:[1,0,1]
	v_pk_fma_f32 v[60:61], v[204:205], v[66:67], v[60:61] op_sel_hi:[1,0,1]
	v_pk_fma_f32 v[62:63], v[206:207], v[66:67], v[62:63] op_sel_hi:[1,0,1]
	v_pk_add_f32 v[18:19], v[18:19], v[60:61]
	v_pk_add_f32 v[20:21], v[20:21], v[62:63]
	s_waitcnt lgkmcnt(3)
	v_mov_b32_e32 v66, v137
	v_pk_mul_f32 v[60:61], v[196:197], v[134:135] op_sel:[0,1]
	v_pk_mul_f32 v[62:63], v[198:199], v[134:135] op_sel:[0,1]
	v_pk_fma_f32 v[60:61], v[192:193], v[134:135], v[60:61] op_sel_hi:[1,0,1]
	v_pk_fma_f32 v[62:63], v[194:195], v[134:135], v[62:63] op_sel_hi:[1,0,1]
	v_pk_fma_f32 v[60:61], v[200:201], v[136:137], v[60:61] op_sel_hi:[1,0,1]
	v_pk_fma_f32 v[62:63], v[202:203], v[136:137], v[62:63] op_sel_hi:[1,0,1]
	v_pk_fma_f32 v[60:61], v[204:205], v[66:67], v[60:61] op_sel_hi:[1,0,1]
	v_pk_fma_f32 v[62:63], v[206:207], v[66:67], v[62:63] op_sel_hi:[1,0,1]
	v_pk_add_f32 v[14:15], v[14:15], v[60:61]
	v_pk_add_f32 v[16:17], v[16:17], v[62:63]
	s_waitcnt lgkmcnt(2)
	v_mov_b32_e32 v66, v141
	v_pk_mul_f32 v[60:61], v[196:197], v[138:139] op_sel:[0,1]
	v_pk_mul_f32 v[62:63], v[198:199], v[138:139] op_sel:[0,1]
	v_pk_fma_f32 v[60:61], v[192:193], v[138:139], v[60:61] op_sel_hi:[1,0,1]
	v_pk_fma_f32 v[62:63], v[194:195], v[138:139], v[62:63] op_sel_hi:[1,0,1]
	v_pk_fma_f32 v[60:61], v[200:201], v[140:141], v[60:61] op_sel_hi:[1,0,1]
	v_pk_fma_f32 v[62:63], v[202:203], v[140:141], v[62:63] op_sel_hi:[1,0,1]
	v_pk_fma_f32 v[60:61], v[204:205], v[66:67], v[60:61] op_sel_hi:[1,0,1]
	v_pk_fma_f32 v[62:63], v[206:207], v[66:67], v[62:63] op_sel_hi:[1,0,1]
	v_pk_add_f32 v[10:11], v[10:11], v[60:61]
	v_pk_add_f32 v[12:13], v[12:13], v[62:63]
	s_waitcnt lgkmcnt(1)
	v_mov_b32_e32 v66, v145
	v_pk_mul_f32 v[60:61], v[196:197], v[142:143] op_sel:[0,1]
	v_pk_mul_f32 v[62:63], v[198:199], v[142:143] op_sel:[0,1]
	v_pk_fma_f32 v[60:61], v[192:193], v[142:143], v[60:61] op_sel_hi:[1,0,1]
	v_pk_fma_f32 v[62:63], v[194:195], v[142:143], v[62:63] op_sel_hi:[1,0,1]
	v_pk_fma_f32 v[60:61], v[200:201], v[144:145], v[60:61] op_sel_hi:[1,0,1]
	v_pk_fma_f32 v[62:63], v[202:203], v[144:145], v[62:63] op_sel_hi:[1,0,1]
	v_pk_fma_f32 v[60:61], v[204:205], v[66:67], v[60:61] op_sel_hi:[1,0,1]
	v_pk_fma_f32 v[62:63], v[206:207], v[66:67], v[62:63] op_sel_hi:[1,0,1]
	v_pk_add_f32 v[6:7], v[6:7], v[60:61]
	v_pk_add_f32 v[8:9], v[8:9], v[62:63]
	s_waitcnt lgkmcnt(0)
	v_mov_b32_e32 v66, v149
	v_pk_mul_f32 v[60:61], v[196:197], v[146:147] op_sel:[0,1]
	v_pk_mul_f32 v[62:63], v[198:199], v[146:147] op_sel:[0,1]
	v_pk_fma_f32 v[60:61], v[192:193], v[146:147], v[60:61] op_sel_hi:[1,0,1]
	v_pk_fma_f32 v[62:63], v[194:195], v[146:147], v[62:63] op_sel_hi:[1,0,1]
	v_pk_fma_f32 v[60:61], v[200:201], v[148:149], v[60:61] op_sel_hi:[1,0,1]
	v_pk_fma_f32 v[62:63], v[202:203], v[148:149], v[62:63] op_sel_hi:[1,0,1]
	v_pk_fma_f32 v[60:61], v[204:205], v[66:67], v[60:61] op_sel_hi:[1,0,1]
	v_pk_fma_f32 v[62:63], v[206:207], v[66:67], v[62:63] op_sel_hi:[1,0,1]
	v_pk_add_f32 v[2:3], v[2:3], v[60:61]
	v_pk_add_f32 v[4:5], v[4:5], v[62:63]
	v_lshlrev_b32_e32 v38, 4, v56
	s_movk_i32 s1, 0x2400
	v_and_b32_e32 v38, 0x3f0, v38
	v_mul_lo_u32 v0, v0, s1
	s_movk_i32 s1, 0x900
	v_add3_u32 v0, 0, v38, v0
	v_cmp_gt_i32_e32 vcc, s1, v56
	ds_write_b128 v0, v[22:25] offset:36864
	ds_write_b128 v0, v[34:37] offset:37888
	ds_write_b128 v0, v[30:33] offset:38912
	ds_write_b128 v0, v[26:29] offset:39936
	ds_write_b128 v0, v[18:21] offset:40960
	ds_write_b128 v0, v[14:17] offset:41984
	ds_write_b128 v0, v[10:13] offset:43008
	ds_write_b128 v0, v[6:9] offset:44032
	ds_write_b128 v0, v[2:5] offset:45056
	s_waitcnt lgkmcnt(0)
	s_barrier
	s_and_saveexec_b64 s[4:5], vcc
	s_movk_i32 s11, 0x6ff
	s_cbranch_execz .LBB0_1085
	v_readlane_b32 s1, v254, 57
	s_add_u32 s2, s1, s2
	v_readlane_b32 s1, v254, 58
	s_addc_u32 s3, s1, s3
	s_mul_i32 s1, s6, 0x2400
	s_add_i32 s7, s0, s1
	v_or_b32_sdwa v2, s7, v56 dst_sel:DWORD dst_unused:UNUSED_PAD src0_sel:DWORD src1_sel:BYTE_0
	v_mov_b32_e32 v0, 2
	v_ashrrev_i32_e32 v3, 31, v2
	v_lshlrev_b32_sdwa v0, v0, v56 dst_sel:DWORD dst_unused:UNUSED_PAD src0_sel:DWORD src1_sel:BYTE_0
	s_mul_hi_i32 s1, s6, 9
	s_mul_i32 s0, s6, 9
	v_lshl_add_u64 v[2:3], v[2:3], 2, s[82:83]
	v_add_u32_e32 v6, 0, v0
	v_lshl_add_u64 v[4:5], s[2:3], 0, v[0:1]
	s_mov_b64 s[2:3], 0
	v_mov_b32_e32 v0, v56

; __device__ __forceinline__ float4 ld_nt4(const float* p) { const f32x4v v = __builtin_nontemporal_load((const f32x4v*)p); return make_float4(v[0], v[1], v[2], v[3]); }
; DI void p0_mod_item(const Params& P, unsigned char* lds, int idx, const int tid) {
;     ...
;   const float* W = P.w_ada + ((size_t)l * 1024 + wave * 128) * NMOD + cch * 256 + lane * 4;
;   for (int k4 = 0; k4 < 32; ++k4) {
;     float4 w0 = ld_nt4(W + (size_t)(k4 * 4 + 0) * NMOD);
;     float4 w1 = ld_nt4(W + (size_t)(k4 * 4 + 1) * NMOD);
;     float4 w2 = ld_nt4(W + (size_t)(k4 * 4 + 2) * NMOD);
;     float4 w3 = ld_nt4(W + (size_t)(k4 * 4 + 3) * NMOD);
; #pragma unroll
;     for (int r = 0; r < 9; ++r) {
;       float4 s4 = *(const float4*)(sl + r * 1024 + wave * 128 + k4 * 4);
;       acc[r].x += s4.x * w0.x + s4.y * w1.x + s4.z * w2.x + s4.w * w3.x;
;       acc[r].y += s4.x * w0.y + s4.y * w1.y + s4.z * w2.y + s4.w * w3.y;
;       acc[r].z += s4.x * w0.z + s4.y * w1.z + s4.z * w2.z + s4.w * w3.z;
;       acc[r].w += s4.x * w0.w + s4.y * w1.w + s4.z * w2.w + s4.w * w3.w;
;     }
;   }
.LBB0_1238:
	v_mov_b32_e32 v150, v64
	v_mov_b32_e32 v151, v65
	v_mov_b32_e32 v152, v0
	s_mov_b32 s0, 0x9000
	s_mov_b32 s1, 0
	v_mov_b32_e32 v113, 0
	global_load_dwordx4 v[38:41], v[150:151], off nt
	v_lshl_add_u64 v[150:151], v[150:151], 0, s[0:1]
	global_load_dwordx4 v[42:45], v[150:151], off nt
	v_lshl_add_u64 v[150:151], v[150:151], 0, s[0:1]
	global_load_dwordx4 v[46:49], v[150:151], off nt
	v_lshl_add_u64 v[150:151], v[150:151], 0, s[0:1]
	global_load_dwordx4 v[50:53], v[150:151], off nt
	v_lshl_add_u64 v[150:151], v[150:151], 0, s[0:1]
	global_load_dwordx4 v[160:163], v[150:151], off nt
	v_lshl_add_u64 v[150:151], v[150:151], 0, s[0:1]
	global_load_dwordx4 v[164:167], v[150:151], off nt
	v_lshl_add_u64 v[150:151], v[150:151], 0, s[0:1]
	global_load_dwordx4 v[168:171], v[150:151], off nt
	v_lshl_add_u64 v[150:151], v[150:151], 0, s[0:1]
	global_load_dwordx4 v[172:175], v[150:151], off nt
	v_lshl_add_u64 v[150:151], v[150:151], 0, s[0:1]
	global_load_dwordx4 v[176:179], v[150:151], off nt
	v_lshl_add_u64 v[150:151], v[150:151], 0, s[0:1]
	global_load_dwordx4 v[180:183], v[150:151], off nt
	v_lshl_add_u64 v[150:151], v[150:151], 0, s[0:1]
	global_load_dwordx4 v[184:187], v[150:151], off nt
	v_lshl_add_u64 v[150:151], v[150:151], 0, s[0:1]
	global_load_dwordx4 v[188:191], v[150:151], off nt
	v_lshl_add_u64 v[150:151], v[150:151], 0, s[0:1]
	global_load_dwordx4 v[192:195], v[150:151], off nt
	v_lshl_add_u64 v[150:151], v[150:151], 0, s[0:1]
	global_load_dwordx4 v[196:199], v[150:151], off nt
	v_lshl_add_u64 v[150:151], v[150:151], 0, s[0:1]
	global_load_dwordx4 v[200:203], v[150:151], off nt
	v_lshl_add_u64 v[150:151], v[150:151], 0, s[0:1]
	global_load_dwordx4 v[204:207], v[150:151], off nt
	v_lshl_add_u64 v[150:151], v[150:151], 0, s[0:1]
	s_mov_b32 s100, 0
.Lmod_a_trip:
	ds_read_b128 v[114:117], v152
	ds_read_b128 v[118:121], v152 offset:4096
	ds_read_b128 v[122:125], v152 offset:8192
	ds_read_b128 v[126:129], v152 offset:12288
	ds_read_b128 v[130:133], v152 offset:16384
	ds_read_b128 v[134:137], v152 offset:20480
	ds_read_b128 v[138:141], v152 offset:24576
	ds_read_b128 v[142:145], v152 offset:28672
	ds_read_b128 v[146:149], v152 offset:32768
	s_waitcnt vmcnt(12)
	s_waitcnt lgkmcnt(8)
	v_mov_b32_e32 v112, v117
	v_pk_mul_f32 v[106:107], v[42:43], v[114:115] op_sel:[0,1]
	v_pk_mul_f32 v[108:109], v[44:45], v[114:115] op_sel:[0,1]
	v_pk_fma_f32 v[106:107], v[38:39], v[114:115], v[106:107] op_sel_hi:[1,0,1]
	v_pk_fma_f32 v[108:109], v[40:41], v[114:115], v[108:109] op_sel_hi:[1,0,1]
	v_pk_fma_f32 v[106:107], v[46:47], v[116:117], v[106:107] op_sel_hi:[1,0,1]
	v_pk_fma_f32 v[108:109], v[48:49], v[116:117], v[108:109] op_sel_hi:[1,0,1]
	v_pk_fma_f32 v[106:107], v[50:51], v[112:113], v[106:107] op_sel_hi:[1,0,1]
	v_pk_fma_f32 v[108:109], v[52:53], v[112:113], v[108:109] op_sel_hi:[1,0,1]
	v_pk_add_f32 v[22:23], v[22:23], v[106:107]
	v_pk_add_f32 v[24:25], v[24:25], v[108:109]
	s_waitcnt lgkmcnt(7)
	v_mov_b32_e32 v112, v121
	v_pk_mul_f32 v[106:107], v[42:43], v[118:119] op_sel:[0,1]
	v_pk_mul_f32 v[108:109], v[44:45], v[118:119] op_sel:[0,1]
	v_pk_fma_f32 v[106:107], v[38:39], v[118:119], v[106:107] op_sel_hi:[1,0,1]
	v_pk_fma_f32 v[108:109], v[40:41], v[118:119], v[108:109] op_sel_hi:[1,0,1]
	v_pk_fma_f32 v[106:107], v[46:47], v[120:121], v[106:107] op_sel_hi:[1,0,1]
	v_pk_fma_f32 v[108:109], v[48:49], v[120:121], v[108:109] op_sel_hi:[1,0,1]
	v_pk_fma_f32 v[106:107], v[50:51], v[112:113], v[106:107] op_sel_hi:[1,0,1]
	v_pk_fma_f32 v[108:109], v[52:53], v[112:113], v[108:109] op_sel_hi:[1,0,1]
	v_pk_add_f32 v[34:35], v[34:35], v[106:107]
	v_pk_add_f32 v[36:37], v[36:37], v[108:109]
	s_waitcnt lgkmcnt(6)
	v_mov_b32_e32 v112, v125
	v_pk_mul_f32 v[106:107], v[42:43], v[122:123] op_sel:[0,1]
	v_pk_mul_f32 v[108:109], v[44:45], v[122:123] op_sel:[0,1]
	v_pk_fma_f32 v[106:107], v[38:39], v[122:123], v[106:107] op_sel_hi:[1,0,1]
	v_pk_fma_f32 v[108:109], v[40:41], v[122:123], v[108:109] op_sel_hi:[1,0,1]
	v_pk_fma_f32 v[106:107], v[46:47], v[124:125], v[106:107] op_sel_hi:[1,0,1]
	v_pk_fma_f32 v[108:109], v[48:49], v[124:125], v[108:109] op_sel_hi:[1,0,1]
	v_pk_fma_f32 v[106:107], v[50:51], v[112:113], v[106:107] op_sel_hi:[1,0,1]
	v_pk_fma_f32 v[108:109], v[52:53], v[112:113], v[108:109] op_sel_hi:[1,0,1]
	v_pk_add_f32 v[30:31], v[30:31], v[106:107]
	v_pk_add_f32 v[32:33], v[32:33], v[108:109]
	s_waitcnt lgkmcnt(5)
	v_mov_b32_e32 v112, v129
	v_pk_mul_f32 v[106:107], v[42:43], v[126:127] op_sel:[0,1]
	v_pk_mul_f32 v[108:109], v[44:45], v[126:127] op_sel:[0,1]
	v_pk_fma_f32 v[106:107], v[38:39], v[126:127], v[106:107] op_sel_hi:[1,0,1]
	v_pk_fma_f32 v[108:109], v[40:41], v[126:127], v[108:109] op_sel_hi:[1,0,1]
	v_pk_fma_f32 v[106:107], v[46:47], v[128:129], v[106:107] op_sel_hi:[1,0,1]
	v_pk_fma_f32 v[108:109], v[48:49], v[128:129], v[108:109] op_sel_hi:[1,0,1]
	v_pk_fma_f32 v[106:107], v[50:51], v[112:113], v[106:107] op_sel_hi:[1,0,1]
	v_pk_fma_f32 v[108:109], v[52:53], v[112:113], v[108:109] op_sel_hi:[1,0,1]
	v_pk_add_f32 v[26:27], v[26:27], v[106:107]
	v_pk_add_f32 v[28:29], v[28:29], v[108:109]
	s_waitcnt lgkmcnt(4)
	v_mov_b32_e32 v112, v133
	v_pk_mul_f32 v[106:107], v[42:43], v[130:131] op_sel:[0,1]
	v_pk_mul_f32 v[108:109], v[44:45], v[130:131] op_sel:[0,1]
	v_pk_fma_f32 v[106:107], v[38:39], v[130:131], v[106:107] op_sel_hi:[1,0,1]
	v_pk_fma_f32 v[108:109], v[40:41], v[130:131], v[108:109] op_sel_hi:[1,0,1]
	v_pk_fma_f32 v[106:107], v[46:47], v[132:133], v[106:107] op_sel_hi:[1,0,1]
	v_pk_fma_f32 v[108:109], v[48:49], v[132:133], v[108:109] op_sel_hi:[1,0,1]
	v_pk_fma_f32 v[106:107], v[50:51], v[112:113], v[106:107] op_sel_hi:[1,0,1]
	v_pk_fma_f32 v[108:109], v[52:53], v[112:113], v[108:109] op_sel_hi:[1,0,1]
	v_pk_add_f32 v[18:19], v[18:19], v[106:107]
	v_pk_add_f32 v[20:21], v[20:21], v[108:109]
	s_waitcnt lgkmcnt(3)
; __device__ __forceinline__ float4 ld_nt4(const float* p) { const f32x4v v = __builtin_nontemporal_load((const f32x4v*)p); return make_float4(v[0], v[1], v[2], v[3]); }
; DI void p0_mod_item(const Params& P, unsigned char* lds, int idx, const int tid) {
;     ...
;   for (int k4 = 0; k4 < 32; ++k4) {
;     float4 w0 = ld_nt4(W + (size_t)(k4 * 4 + 0) * NMOD);
;     float4 w1 = ld_nt4(W + (size_t)(k4 * 4 + 1) * NMOD);
;     float4 w2 = ld_nt4(W + (size_t)(k4 * 4 + 2) * NMOD);
;     float4 w3 = ld_nt4(W + (size_t)(k4 * 4 + 3) * NMOD);
; #pragma unroll
;     for (int r = 0; r < 9; ++r) {
;       float4 s4 = *(const float4*)(sl + r * 1024 + wave * 128 + k4 * 4);
;       acc[r].x += s4.x * w0.x + s4.y * w1.x + s4.z * w2.x + s4.w * w3.x;
;       acc[r].y += s4.x * w0.y + s4.y * w1.y + s4.z * w2.y + s4.w * w3.y;
;       acc[r].z += s4.x * w0.z + s4.y * w1.z + s4.z * w2.z + s4.w * w3.z;
;       acc[r].w += s4.x * w0.w + s4.y * w1.w + s4.z * w2.w + s4.w * w3.w;
;     }
;   }
	v_mov_b32_e32 v112, v137
	v_pk_mul_f32 v[106:107], v[42:43], v[134:135] op_sel:[0,1]
	v_pk_mul_f32 v[108:109], v[44:45], v[134:135] op_sel:[0,1]
	v_pk_fma_f32 v[106:107], v[38:39], v[134:135], v[106:107] op_sel_hi:[1,0,1]
	v_pk_fma_f32 v[108:109], v[40:41], v[134:135], v[108:109] op_sel_hi:[1,0,1]
	v_pk_fma_f32 v[106:107], v[46:47], v[136:137], v[106:107] op_sel_hi:[1,0,1]
	v_pk_fma_f32 v[108:109], v[48:49], v[136:137], v[108:109] op_sel_hi:[1,0,1]
	v_pk_fma_f32 v[106:107], v[50:51], v[112:113], v[106:107] op_sel_hi:[1,0,1]
	v_pk_fma_f32 v[108:109], v[52:53], v[112:113], v[108:109] op_sel_hi:[1,0,1]
	v_pk_add_f32 v[14:15], v[14:15], v[106:107]
	v_pk_add_f32 v[16:17], v[16:17], v[108:109]
	s_waitcnt lgkmcnt(2)
	v_mov_b32_e32 v112, v141
	v_pk_mul_f32 v[106:107], v[42:43], v[138:139] op_sel:[0,1]
	v_pk_mul_f32 v[108:109], v[44:45], v[138:139] op_sel:[0,1]
	v_pk_fma_f32 v[106:107], v[38:39], v[138:139], v[106:107] op_sel_hi:[1,0,1]
	v_pk_fma_f32 v[108:109], v[40:41], v[138:139], v[108:109] op_sel_hi:[1,0,1]
	v_pk_fma_f32 v[106:107], v[46:47], v[140:141], v[106:107] op_sel_hi:[1,0,1]
	v_pk_fma_f32 v[108:109], v[48:49], v[140:141], v[108:109] op_sel_hi:[1,0,1]
	v_pk_fma_f32 v[106:107], v[50:51], v[112:113], v[106:107] op_sel_hi:[1,0,1]
	v_pk_fma_f32 v[108:109], v[52:53], v[112:113], v[108:109] op_sel_hi:[1,0,1]
	v_pk_add_f32 v[10:11], v[10:11], v[106:107]
	v_pk_add_f32 v[12:13], v[12:13], v[108:109]
	s_waitcnt lgkmcnt(1)
	v_mov_b32_e32 v112, v145
	v_pk_mul_f32 v[106:107], v[42:43], v[142:143] op_sel:[0,1]
	v_pk_mul_f32 v[108:109], v[44:45], v[142:143] op_sel:[0,1]
	v_pk_fma_f32 v[106:107], v[38:39], v[142:143], v[106:107] op_sel_hi:[1,0,1]
	v_pk_fma_f32 v[108:109], v[40:41], v[142:143], v[108:109] op_sel_hi:[1,0,1]
	v_pk_fma_f32 v[106:107], v[46:47], v[144:145], v[106:107] op_sel_hi:[1,0,1]
	v_pk_fma_f32 v[108:109], v[48:49], v[144:145], v[108:109] op_sel_hi:[1,0,1]
	v_pk_fma_f32 v[106:107], v[50:51], v[112:113], v[106:107] op_sel_hi:[1,0,1]
	v_pk_fma_f32 v[108:109], v[52:53], v[112:113], v[108:109] op_sel_hi:[1,0,1]
	v_pk_add_f32 v[6:7], v[6:7], v[106:107]
	v_pk_add_f32 v[8:9], v[8:9], v[108:109]
	s_waitcnt lgkmcnt(0)
	v_mov_b32_e32 v112, v149
	v_pk_mul_f32 v[106:107], v[42:43], v[146:147] op_sel:[0,1]
	v_pk_mul_f32 v[108:109], v[44:45], v[146:147] op_sel:[0,1]
	v_pk_fma_f32 v[106:107], v[38:39], v[146:147], v[106:107] op_sel_hi:[1,0,1]
	v_pk_fma_f32 v[108:109], v[40:41], v[146:147], v[108:109] op_sel_hi:[1,0,1]
	v_pk_fma_f32 v[106:107], v[46:47], v[148:149], v[106:107] op_sel_hi:[1,0,1]
	v_pk_fma_f32 v[108:109], v[48:49], v[148:149], v[108:109] op_sel_hi:[1,0,1]
	v_pk_fma_f32 v[106:107], v[50:51], v[112:113], v[106:107] op_sel_hi:[1,0,1]
	v_pk_fma_f32 v[108:109], v[52:53], v[112:113], v[108:109] op_sel_hi:[1,0,1]
	v_pk_add_f32 v[2:3], v[2:3], v[106:107]
	v_pk_add_f32 v[4:5], v[4:5], v[108:109]
	global_load_dwordx4 v[38:41], v[150:151], off nt
	v_lshl_add_u64 v[150:151], v[150:151], 0, s[0:1]
	global_load_dwordx4 v[42:45], v[150:151], off nt
	v_lshl_add_u64 v[150:151], v[150:151], 0, s[0:1]
	global_load_dwordx4 v[46:49], v[150:151], off nt
	v_lshl_add_u64 v[150:151], v[150:151], 0, s[0:1]
	global_load_dwordx4 v[50:53], v[150:151], off nt
	v_lshl_add_u64 v[150:151], v[150:151], 0, s[0:1]
	ds_read_b128 v[114:117], v152 offset:16
	ds_read_b128 v[118:121], v152 offset:4112
	ds_read_b128 v[122:125], v152 offset:8208
	ds_read_b128 v[126:129], v152 offset:12304
	ds_read_b128 v[130:133], v152 offset:16400
	ds_read_b128 v[134:137], v152 offset:20496
	ds_read_b128 v[138:141], v152 offset:24592
	ds_read_b128 v[142:145], v152 offset:28688
	ds_read_b128 v[146:149], v152 offset:32784
	s_waitcnt vmcnt(12)
	s_waitcnt lgkmcnt(8)
	v_mov_b32_e32 v112, v117
	v_pk_mul_f32 v[106:107], v[164:165], v[114:115] op_sel:[0,1]
	v_pk_mul_f32 v[108:109], v[166:167], v[114:115] op_sel:[0,1]
	v_pk_fma_f32 v[106:107], v[160:161], v[114:115], v[106:107] op_sel_hi:[1,0,1]
	v_pk_fma_f32 v[108:109], v[162:163], v[114:115], v[108:109] op_sel_hi:[1,0,1]
	v_pk_fma_f32 v[106:107], v[168:169], v[116:117], v[106:107] op_sel_hi:[1,0,1]
	v_pk_fma_f32 v[108:109], v[170:171], v[116:117], v[108:109] op_sel_hi:[1,0,1]
	v_pk_fma_f32 v[106:107], v[172:173], v[112:113], v[106:107] op_sel_hi:[1,0,1]
	v_pk_fma_f32 v[108:109], v[174:175], v[112:113], v[108:109] op_sel_hi:[1,0,1]
	v_pk_add_f32 v[22:23], v[22:23], v[106:107]
	v_pk_add_f32 v[24:25], v[24:25], v[108:109]
	s_waitcnt lgkmcnt(7)
	v_mov_b32_e32 v112, v121
	v_pk_mul_f32 v[106:107], v[164:165], v[118:119] op_sel:[0,1]
	v_pk_mul_f32 v[108:109], v[166:167], v[118:119] op_sel:[0,1]
	v_pk_fma_f32 v[106:107], v[160:161], v[118:119], v[106:107] op_sel_hi:[1,0,1]
	v_pk_fma_f32 v[108:109], v[162:163], v[118:119], v[108:109] op_sel_hi:[1,0,1]
	v_pk_fma_f32 v[106:107], v[168:169], v[120:121], v[106:107] op_sel_hi:[1,0,1]
	v_pk_fma_f32 v[108:109], v[170:171], v[120:121], v[108:109] op_sel_hi:[1,0,1]
	v_pk_fma_f32 v[106:107], v[172:173], v[112:113], v[106:107] op_sel_hi:[1,0,1]
	v_pk_fma_f32 v[108:109], v[174:175], v[112:113], v[108:109] op_sel_hi:[1,0,1]
	v_pk_add_f32 v[34:35], v[34:35], v[106:107]
	v_pk_add_f32 v[36:37], v[36:37], v[108:109]
	s_waitcnt lgkmcnt(6)
	v_mov_b32_e32 v112, v125
	v_pk_mul_f32 v[106:107], v[164:165], v[122:123] op_sel:[0,1]
	v_pk_mul_f32 v[108:109], v[166:167], v[122:123] op_sel:[0,1]
	v_pk_fma_f32 v[106:107], v[160:161], v[122:123], v[106:107] op_sel_hi:[1,0,1]
	v_pk_fma_f32 v[108:109], v[162:163], v[122:123], v[108:109] op_sel_hi:[1,0,1]
	v_pk_fma_f32 v[106:107], v[168:169], v[124:125], v[106:107] op_sel_hi:[1,0,1]
	v_pk_fma_f32 v[108:109], v[170:171], v[124:125], v[108:109] op_sel_hi:[1,0,1]
	v_pk_fma_f32 v[106:107], v[172:173], v[112:113], v[106:107] op_sel_hi:[1,0,1]
	v_pk_fma_f32 v[108:109], v[174:175], v[112:113], v[108:109] op_sel_hi:[1,0,1]
	v_pk_add_f32 v[30:31], v[30:31], v[106:107]
	v_pk_add_f32 v[32:33], v[32:33], v[108:109]
	s_waitcnt lgkmcnt(5)
; __device__ __forceinline__ float4 ld_nt4(const float* p) { const f32x4v v = __builtin_nontemporal_load((const f32x4v*)p); return make_float4(v[0], v[1], v[2], v[3]); }
; DI void p0_mod_item(const Params& P, unsigned char* lds, int idx, const int tid) {
;     ...
;   for (int k4 = 0; k4 < 32; ++k4) {
;     float4 w0 = ld_nt4(W + (size_t)(k4 * 4 + 0) * NMOD);
;     float4 w1 = ld_nt4(W + (size_t)(k4 * 4 + 1) * NMOD);
;     float4 w2 = ld_nt4(W + (size_t)(k4 * 4 + 2) * NMOD);
;     float4 w3 = ld_nt4(W + (size_t)(k4 * 4 + 3) * NMOD);
; #pragma unroll
;     for (int r = 0; r < 9; ++r) {
;       float4 s4 = *(const float4*)(sl + r * 1024 + wave * 128 + k4 * 4);
;       acc[r].x += s4.x * w0.x + s4.y * w1.x + s4.z * w2.x + s4.w * w3.x;
;       acc[r].y += s4.x * w0.y + s4.y * w1.y + s4.z * w2.y + s4.w * w3.y;
;       acc[r].z += s4.x * w0.z + s4.y * w1.z + s4.z * w2.z + s4.w * w3.z;
;       acc[r].w += s4.x * w0.w + s4.y * w1.w + s4.z * w2.w + s4.w * w3.w;
;     }
;   }
	v_mov_b32_e32 v112, v129
	v_pk_mul_f32 v[106:107], v[164:165], v[126:127] op_sel:[0,1]
	v_pk_mul_f32 v[108:109], v[166:167], v[126:127] op_sel:[0,1]
	v_pk_fma_f32 v[106:107], v[160:161], v[126:127], v[106:107] op_sel_hi:[1,0,1]
	v_pk_fma_f32 v[108:109], v[162:163], v[126:127], v[108:109] op_sel_hi:[1,0,1]
	v_pk_fma_f32 v[106:107], v[168:169], v[128:129], v[106:107] op_sel_hi:[1,0,1]
	v_pk_fma_f32 v[108:109], v[170:171], v[128:129], v[108:109] op_sel_hi:[1,0,1]
	v_pk_fma_f32 v[106:107], v[172:173], v[112:113], v[106:107] op_sel_hi:[1,0,1]
	v_pk_fma_f32 v[108:109], v[174:175], v[112:113], v[108:109] op_sel_hi:[1,0,1]
	v_pk_add_f32 v[26:27], v[26:27], v[106:107]
	v_pk_add_f32 v[28:29], v[28:29], v[108:109]
	s_waitcnt lgkmcnt(4)
	v_mov_b32_e32 v112, v133
	v_pk_mul_f32 v[106:107], v[164:165], v[130:131] op_sel:[0,1]
	v_pk_mul_f32 v[108:109], v[166:167], v[130:131] op_sel:[0,1]
	v_pk_fma_f32 v[106:107], v[160:161], v[130:131], v[106:107] op_sel_hi:[1,0,1]
	v_pk_fma_f32 v[108:109], v[162:163], v[130:131], v[108:109] op_sel_hi:[1,0,1]
	v_pk_fma_f32 v[106:107], v[168:169], v[132:133], v[106:107] op_sel_hi:[1,0,1]
	v_pk_fma_f32 v[108:109], v[170:171], v[132:133], v[108:109] op_sel_hi:[1,0,1]
	v_pk_fma_f32 v[106:107], v[172:173], v[112:113], v[106:107] op_sel_hi:[1,0,1]
	v_pk_fma_f32 v[108:109], v[174:175], v[112:113], v[108:109] op_sel_hi:[1,0,1]
	v_pk_add_f32 v[18:19], v[18:19], v[106:107]
	v_pk_add_f32 v[20:21], v[20:21], v[108:109]
	s_waitcnt lgkmcnt(3)
	v_mov_b32_e32 v112, v137
	v_pk_mul_f32 v[106:107], v[164:165], v[134:135] op_sel:[0,1]
	v_pk_mul_f32 v[108:109], v[166:167], v[134:135] op_sel:[0,1]
	v_pk_fma_f32 v[106:107], v[160:161], v[134:135], v[106:107] op_sel_hi:[1,0,1]
	v_pk_fma_f32 v[108:109], v[162:163], v[134:135], v[108:109] op_sel_hi:[1,0,1]
	v_pk_fma_f32 v[106:107], v[168:169], v[136:137], v[106:107] op_sel_hi:[1,0,1]
	v_pk_fma_f32 v[108:109], v[170:171], v[136:137], v[108:109] op_sel_hi:[1,0,1]
	v_pk_fma_f32 v[106:107], v[172:173], v[112:113], v[106:107] op_sel_hi:[1,0,1]
	v_pk_fma_f32 v[108:109], v[174:175], v[112:113], v[108:109] op_sel_hi:[1,0,1]
	v_pk_add_f32 v[14:15], v[14:15], v[106:107]
	v_pk_add_f32 v[16:17], v[16:17], v[108:109]
	s_waitcnt lgkmcnt(2)
	v_mov_b32_e32 v112, v141
	v_pk_mul_f32 v[106:107], v[164:165], v[138:139] op_sel:[0,1]
	v_pk_mul_f32 v[108:109], v[166:167], v[138:139] op_sel:[0,1]
	v_pk_fma_f32 v[106:107], v[160:161], v[138:139], v[106:107] op_sel_hi:[1,0,1]
	v_pk_fma_f32 v[108:109], v[162:163], v[138:139], v[108:109] op_sel_hi:[1,0,1]
	v_pk_fma_f32 v[106:107], v[168:169], v[140:141], v[106:107] op_sel_hi:[1,0,1]
	v_pk_fma_f32 v[108:109], v[170:171], v[140:141], v[108:109] op_sel_hi:[1,0,1]
	v_pk_fma_f32 v[106:107], v[172:173], v[112:113], v[106:107] op_sel_hi:[1,0,1]
	v_pk_fma_f32 v[108:109], v[174:175], v[112:113], v[108:109] op_sel_hi:[1,0,1]
	v_pk_add_f32 v[10:11], v[10:11], v[106:107]
	v_pk_add_f32 v[12:13], v[12:13], v[108:109]
	s_waitcnt lgkmcnt(1)
	v_mov_b32_e32 v112, v145
	v_pk_mul_f32 v[106:107], v[164:165], v[142:143] op_sel:[0,1]
	v_pk_mul_f32 v[108:109], v[166:167], v[142:143] op_sel:[0,1]
	v_pk_fma_f32 v[106:107], v[160:161], v[142:143], v[106:107] op_sel_hi:[1,0,1]
	v_pk_fma_f32 v[108:109], v[162:163], v[142:143], v[108:109] op_sel_hi:[1,0,1]
	v_pk_fma_f32 v[106:107], v[168:169], v[144:145], v[106:107] op_sel_hi:[1,0,1]
	v_pk_fma_f32 v[108:109], v[170:171], v[144:145], v[108:109] op_sel_hi:[1,0,1]
	v_pk_fma_f32 v[106:107], v[172:173], v[112:113], v[106:107] op_sel_hi:[1,0,1]
	v_pk_fma_f32 v[108:109], v[174:175], v[112:113], v[108:109] op_sel_hi:[1,0,1]
	v_pk_add_f32 v[6:7], v[6:7], v[106:107]
	v_pk_add_f32 v[8:9], v[8:9], v[108:109]
	s_waitcnt lgkmcnt(0)
	v_mov_b32_e32 v112, v149
	v_pk_mul_f32 v[106:107], v[164:165], v[146:147] op_sel:[0,1]
	v_pk_mul_f32 v[108:109], v[166:167], v[146:147] op_sel:[0,1]
	v_pk_fma_f32 v[106:107], v[160:161], v[146:147], v[106:107] op_sel_hi:[1,0,1]
	v_pk_fma_f32 v[108:109], v[162:163], v[146:147], v[108:109] op_sel_hi:[1,0,1]
	v_pk_fma_f32 v[106:107], v[168:169], v[148:149], v[106:107] op_sel_hi:[1,0,1]
	v_pk_fma_f32 v[108:109], v[170:171], v[148:149], v[108:109] op_sel_hi:[1,0,1]
	v_pk_fma_f32 v[106:107], v[172:173], v[112:113], v[106:107] op_sel_hi:[1,0,1]
	v_pk_fma_f32 v[108:109], v[174:175], v[112:113], v[108:109] op_sel_hi:[1,0,1]
	v_pk_add_f32 v[2:3], v[2:3], v[106:107]
	v_pk_add_f32 v[4:5], v[4:5], v[108:109]
	global_load_dwordx4 v[160:163], v[150:151], off nt
	v_lshl_add_u64 v[150:151], v[150:151], 0, s[0:1]
	global_load_dwordx4 v[164:167], v[150:151], off nt
	v_lshl_add_u64 v[150:151], v[150:151], 0, s[0:1]
	global_load_dwordx4 v[168:171], v[150:151], off nt
	v_lshl_add_u64 v[150:151], v[150:151], 0, s[0:1]
	global_load_dwordx4 v[172:175], v[150:151], off nt
	v_lshl_add_u64 v[150:151], v[150:151], 0, s[0:1]
	ds_read_b128 v[114:117], v152 offset:32
	ds_read_b128 v[118:121], v152 offset:4128
	ds_read_b128 v[122:125], v152 offset:8224
	ds_read_b128 v[126:129], v152 offset:12320
	ds_read_b128 v[130:133], v152 offset:16416
	ds_read_b128 v[134:137], v152 offset:20512
	ds_read_b128 v[138:141], v152 offset:24608
	ds_read_b128 v[142:145], v152 offset:28704
	ds_read_b128 v[146:149], v152 offset:32800
	s_waitcnt vmcnt(12)
	s_waitcnt lgkmcnt(8)
	v_mov_b32_e32 v112, v117
	v_pk_mul_f32 v[106:107], v[180:181], v[114:115] op_sel:[0,1]
	v_pk_mul_f32 v[108:109], v[182:183], v[114:115] op_sel:[0,1]
	v_pk_fma_f32 v[106:107], v[176:177], v[114:115], v[106:107] op_sel_hi:[1,0,1]
	v_pk_fma_f32 v[108:109], v[178:179], v[114:115], v[108:109] op_sel_hi:[1,0,1]
	v_pk_fma_f32 v[106:107], v[184:185], v[116:117], v[106:107] op_sel_hi:[1,0,1]
	v_pk_fma_f32 v[108:109], v[186:187], v[116:117], v[108:109] op_sel_hi:[1,0,1]
	v_pk_fma_f32 v[106:107], v[188:189], v[112:113], v[106:107] op_sel_hi:[1,0,1]
	v_pk_fma_f32 v[108:109], v[190:191], v[112:113], v[108:109] op_sel_hi:[1,0,1]
	v_pk_add_f32 v[22:23], v[22:23], v[106:107]
	v_pk_add_f32 v[24:25], v[24:25], v[108:109]
	s_waitcnt lgkmcnt(7)
; __device__ __forceinline__ float4 ld_nt4(const float* p) { const f32x4v v = __builtin_nontemporal_load((const f32x4v*)p); return make_float4(v[0], v[1], v[2], v[3]); }
; DI void p0_mod_item(const Params& P, unsigned char* lds, int idx, const int tid) {
;     ...
;   for (int k4 = 0; k4 < 32; ++k4) {
;     float4 w0 = ld_nt4(W + (size_t)(k4 * 4 + 0) * NMOD);
;     float4 w1 = ld_nt4(W + (size_t)(k4 * 4 + 1) * NMOD);
;     float4 w2 = ld_nt4(W + (size_t)(k4 * 4 + 2) * NMOD);
;     float4 w3 = ld_nt4(W + (size_t)(k4 * 4 + 3) * NMOD);
; #pragma unroll
;     for (int r = 0; r < 9; ++r) {
;       float4 s4 = *(const float4*)(sl + r * 1024 + wave * 128 + k4 * 4);
;       acc[r].x += s4.x * w0.x + s4.y * w1.x + s4.z * w2.x + s4.w * w3.x;
;       acc[r].y += s4.x * w0.y + s4.y * w1.y + s4.z * w2.y + s4.w * w3.y;
;       acc[r].z += s4.x * w0.z + s4.y * w1.z + s4.z * w2.z + s4.w * w3.z;
;       acc[r].w += s4.x * w0.w + s4.y * w1.w + s4.z * w2.w + s4.w * w3.w;
;     }
;   }
	v_mov_b32_e32 v112, v121
	v_pk_mul_f32 v[106:107], v[180:181], v[118:119] op_sel:[0,1]
	v_pk_mul_f32 v[108:109], v[182:183], v[118:119] op_sel:[0,1]
	v_pk_fma_f32 v[106:107], v[176:177], v[118:119], v[106:107] op_sel_hi:[1,0,1]
	v_pk_fma_f32 v[108:109], v[178:179], v[118:119], v[108:109] op_sel_hi:[1,0,1]
	v_pk_fma_f32 v[106:107], v[184:185], v[120:121], v[106:107] op_sel_hi:[1,0,1]
	v_pk_fma_f32 v[108:109], v[186:187], v[120:121], v[108:109] op_sel_hi:[1,0,1]
	v_pk_fma_f32 v[106:107], v[188:189], v[112:113], v[106:107] op_sel_hi:[1,0,1]
	v_pk_fma_f32 v[108:109], v[190:191], v[112:113], v[108:109] op_sel_hi:[1,0,1]
	v_pk_add_f32 v[34:35], v[34:35], v[106:107]
	v_pk_add_f32 v[36:37], v[36:37], v[108:109]
	s_waitcnt lgkmcnt(6)
	v_mov_b32_e32 v112, v125
	v_pk_mul_f32 v[106:107], v[180:181], v[122:123] op_sel:[0,1]
	v_pk_mul_f32 v[108:109], v[182:183], v[122:123] op_sel:[0,1]
	v_pk_fma_f32 v[106:107], v[176:177], v[122:123], v[106:107] op_sel_hi:[1,0,1]
	v_pk_fma_f32 v[108:109], v[178:179], v[122:123], v[108:109] op_sel_hi:[1,0,1]
	v_pk_fma_f32 v[106:107], v[184:185], v[124:125], v[106:107] op_sel_hi:[1,0,1]
	v_pk_fma_f32 v[108:109], v[186:187], v[124:125], v[108:109] op_sel_hi:[1,0,1]
	v_pk_fma_f32 v[106:107], v[188:189], v[112:113], v[106:107] op_sel_hi:[1,0,1]
	v_pk_fma_f32 v[108:109], v[190:191], v[112:113], v[108:109] op_sel_hi:[1,0,1]
	v_pk_add_f32 v[30:31], v[30:31], v[106:107]
	v_pk_add_f32 v[32:33], v[32:33], v[108:109]
	s_waitcnt lgkmcnt(5)
	v_mov_b32_e32 v112, v129
	v_pk_mul_f32 v[106:107], v[180:181], v[126:127] op_sel:[0,1]
	v_pk_mul_f32 v[108:109], v[182:183], v[126:127] op_sel:[0,1]
	v_pk_fma_f32 v[106:107], v[176:177], v[126:127], v[106:107] op_sel_hi:[1,0,1]
	v_pk_fma_f32 v[108:109], v[178:179], v[126:127], v[108:109] op_sel_hi:[1,0,1]
	v_pk_fma_f32 v[106:107], v[184:185], v[128:129], v[106:107] op_sel_hi:[1,0,1]
	v_pk_fma_f32 v[108:109], v[186:187], v[128:129], v[108:109] op_sel_hi:[1,0,1]
	v_pk_fma_f32 v[106:107], v[188:189], v[112:113], v[106:107] op_sel_hi:[1,0,1]
	v_pk_fma_f32 v[108:109], v[190:191], v[112:113], v[108:109] op_sel_hi:[1,0,1]
	v_pk_add_f32 v[26:27], v[26:27], v[106:107]
	v_pk_add_f32 v[28:29], v[28:29], v[108:109]
	s_waitcnt lgkmcnt(4)
	v_mov_b32_e32 v112, v133
	v_pk_mul_f32 v[106:107], v[180:181], v[130:131] op_sel:[0,1]
	v_pk_mul_f32 v[108:109], v[182:183], v[130:131] op_sel:[0,1]
	v_pk_fma_f32 v[106:107], v[176:177], v[130:131], v[106:107] op_sel_hi:[1,0,1]
	v_pk_fma_f32 v[108:109], v[178:179], v[130:131], v[108:109] op_sel_hi:[1,0,1]
	v_pk_fma_f32 v[106:107], v[184:185], v[132:133], v[106:107] op_sel_hi:[1,0,1]
	v_pk_fma_f32 v[108:109], v[186:187], v[132:133], v[108:109] op_sel_hi:[1,0,1]
	v_pk_fma_f32 v[106:107], v[188:189], v[112:113], v[106:107] op_sel_hi:[1,0,1]
	v_pk_fma_f32 v[108:109], v[190:191], v[112:113], v[108:109] op_sel_hi:[1,0,1]
	v_pk_add_f32 v[18:19], v[18:19], v[106:107]
	v_pk_add_f32 v[20:21], v[20:21], v[108:109]
	s_waitcnt lgkmcnt(3)
	v_mov_b32_e32 v112, v137
	v_pk_mul_f32 v[106:107], v[180:181], v[134:135] op_sel:[0,1]
	v_pk_mul_f32 v[108:109], v[182:183], v[134:135] op_sel:[0,1]
	v_pk_fma_f32 v[106:107], v[176:177], v[134:135], v[106:107] op_sel_hi:[1,0,1]
	v_pk_fma_f32 v[108:109], v[178:179], v[134:135], v[108:109] op_sel_hi:[1,0,1]
	v_pk_fma_f32 v[106:107], v[184:185], v[136:137], v[106:107] op_sel_hi:[1,0,1]
	v_pk_fma_f32 v[108:109], v[186:187], v[136:137], v[108:109] op_sel_hi:[1,0,1]
	v_pk_fma_f32 v[106:107], v[188:189], v[112:113], v[106:107] op_sel_hi:[1,0,1]
	v_pk_fma_f32 v[108:109], v[190:191], v[112:113], v[108:109] op_sel_hi:[1,0,1]
	v_pk_add_f32 v[14:15], v[14:15], v[106:107]
	v_pk_add_f32 v[16:17], v[16:17], v[108:109]
	s_waitcnt lgkmcnt(2)
	v_mov_b32_e32 v112, v141
	v_pk_mul_f32 v[106:107], v[180:181], v[138:139] op_sel:[0,1]
	v_pk_mul_f32 v[108:109], v[182:183], v[138:139] op_sel:[0,1]
	v_pk_fma_f32 v[106:107], v[176:177], v[138:139], v[106:107] op_sel_hi:[1,0,1]
	v_pk_fma_f32 v[108:109], v[178:179], v[138:139], v[108:109] op_sel_hi:[1,0,1]
	v_pk_fma_f32 v[106:107], v[184:185], v[140:141], v[106:107] op_sel_hi:[1,0,1]
	v_pk_fma_f32 v[108:109], v[186:187], v[140:141], v[108:109] op_sel_hi:[1,0,1]
	v_pk_fma_f32 v[106:107], v[188:189], v[112:113], v[106:107] op_sel_hi:[1,0,1]
	v_pk_fma_f32 v[108:109], v[190:191], v[112:113], v[108:109] op_sel_hi:[1,0,1]
	v_pk_add_f32 v[10:11], v[10:11], v[106:107]
	v_pk_add_f32 v[12:13], v[12:13], v[108:109]
	s_waitcnt lgkmcnt(1)
	v_mov_b32_e32 v112, v145
	v_pk_mul_f32 v[106:107], v[180:181], v[142:143] op_sel:[0,1]
	v_pk_mul_f32 v[108:109], v[182:183], v[142:143] op_sel:[0,1]
	v_pk_fma_f32 v[106:107], v[176:177], v[142:143], v[106:107] op_sel_hi:[1,0,1]
	v_pk_fma_f32 v[108:109], v[178:179], v[142:143], v[108:109] op_sel_hi:[1,0,1]
	v_pk_fma_f32 v[106:107], v[184:185], v[144:145], v[106:107] op_sel_hi:[1,0,1]
	v_pk_fma_f32 v[108:109], v[186:187], v[144:145], v[108:109] op_sel_hi:[1,0,1]
	v_pk_fma_f32 v[106:107], v[188:189], v[112:113], v[106:107] op_sel_hi:[1,0,1]
	v_pk_fma_f32 v[108:109], v[190:191], v[112:113], v[108:109] op_sel_hi:[1,0,1]
	v_pk_add_f32 v[6:7], v[6:7], v[106:107]
	v_pk_add_f32 v[8:9], v[8:9], v[108:109]
	s_waitcnt lgkmcnt(0)
; __device__ __forceinline__ float4 ld_nt4(const float* p) { const f32x4v v = __builtin_nontemporal_load((const f32x4v*)p); return make_float4(v[0], v[1], v[2], v[3]); }
; DI void p0_mod_item(const Params& P, unsigned char* lds, int idx, const int tid) {
;     ...
;   for (int k4 = 0; k4 < 32; ++k4) {
;     float4 w0 = ld_nt4(W + (size_t)(k4 * 4 + 0) * NMOD);
;     float4 w1 = ld_nt4(W + (size_t)(k4 * 4 + 1) * NMOD);
;     float4 w2 = ld_nt4(W + (size_t)(k4 * 4 + 2) * NMOD);
;     float4 w3 = ld_nt4(W + (size_t)(k4 * 4 + 3) * NMOD);
; #pragma unroll
;     for (int r = 0; r < 9; ++r) {
;       float4 s4 = *(const float4*)(sl + r * 1024 + wave * 128 + k4 * 4);
;       acc[r].x += s4.x * w0.x + s4.y * w1.x + s4.z * w2.x + s4.w * w3.x;
;       acc[r].y += s4.x * w0.y + s4.y * w1.y + s4.z * w2.y + s4.w * w3.y;
;       acc[r].z += s4.x * w0.z + s4.y * w1.z + s4.z * w2.z + s4.w * w3.z;
;       acc[r].w += s4.x * w0.w + s4.y * w1.w + s4.z * w2.w + s4.w * w3.w;
;     }
;   }
	v_mov_b32_e32 v112, v149
	v_pk_mul_f32 v[106:107], v[180:181], v[146:147] op_sel:[0,1]
	v_pk_mul_f32 v[108:109], v[182:183], v[146:147] op_sel:[0,1]
	v_pk_fma_f32 v[106:107], v[176:177], v[146:147], v[106:107] op_sel_hi:[1,0,1]
	v_pk_fma_f32 v[108:109], v[178:179], v[146:147], v[108:109] op_sel_hi:[1,0,1]
	v_pk_fma_f32 v[106:107], v[184:185], v[148:149], v[106:107] op_sel_hi:[1,0,1]
	v_pk_fma_f32 v[108:109], v[186:187], v[148:149], v[108:109] op_sel_hi:[1,0,1]
	v_pk_fma_f32 v[106:107], v[188:189], v[112:113], v[106:107] op_sel_hi:[1,0,1]
	v_pk_fma_f32 v[108:109], v[190:191], v[112:113], v[108:109] op_sel_hi:[1,0,1]
	v_pk_add_f32 v[2:3], v[2:3], v[106:107]
	v_pk_add_f32 v[4:5], v[4:5], v[108:109]
	global_load_dwordx4 v[176:179], v[150:151], off nt
	v_lshl_add_u64 v[150:151], v[150:151], 0, s[0:1]
	global_load_dwordx4 v[180:183], v[150:151], off nt
	v_lshl_add_u64 v[150:151], v[150:151], 0, s[0:1]
	global_load_dwordx4 v[184:187], v[150:151], off nt
	v_lshl_add_u64 v[150:151], v[150:151], 0, s[0:1]
	global_load_dwordx4 v[188:191], v[150:151], off nt
	v_lshl_add_u64 v[150:151], v[150:151], 0, s[0:1]
	ds_read_b128 v[114:117], v152 offset:48
	ds_read_b128 v[118:121], v152 offset:4144
	ds_read_b128 v[122:125], v152 offset:8240
	ds_read_b128 v[126:129], v152 offset:12336
	ds_read_b128 v[130:133], v152 offset:16432
	ds_read_b128 v[134:137], v152 offset:20528
	ds_read_b128 v[138:141], v152 offset:24624
	ds_read_b128 v[142:145], v152 offset:28720
	ds_read_b128 v[146:149], v152 offset:32816
	s_waitcnt vmcnt(12)
	s_waitcnt lgkmcnt(8)
	v_mov_b32_e32 v112, v117
	v_pk_mul_f32 v[106:107], v[196:197], v[114:115] op_sel:[0,1]
	v_pk_mul_f32 v[108:109], v[198:199], v[114:115] op_sel:[0,1]
	v_pk_fma_f32 v[106:107], v[192:193], v[114:115], v[106:107] op_sel_hi:[1,0,1]
	v_pk_fma_f32 v[108:109], v[194:195], v[114:115], v[108:109] op_sel_hi:[1,0,1]
	v_pk_fma_f32 v[106:107], v[200:201], v[116:117], v[106:107] op_sel_hi:[1,0,1]
	v_pk_fma_f32 v[108:109], v[202:203], v[116:117], v[108:109] op_sel_hi:[1,0,1]
	v_pk_fma_f32 v[106:107], v[204:205], v[112:113], v[106:107] op_sel_hi:[1,0,1]
	v_pk_fma_f32 v[108:109], v[206:207], v[112:113], v[108:109] op_sel_hi:[1,0,1]
	v_pk_add_f32 v[22:23], v[22:23], v[106:107]
	v_pk_add_f32 v[24:25], v[24:25], v[108:109]
	s_waitcnt lgkmcnt(7)
	v_mov_b32_e32 v112, v121
	v_pk_mul_f32 v[106:107], v[196:197], v[118:119] op_sel:[0,1]
	v_pk_mul_f32 v[108:109], v[198:199], v[118:119] op_sel:[0,1]
	v_pk_fma_f32 v[106:107], v[192:193], v[118:119], v[106:107] op_sel_hi:[1,0,1]
	v_pk_fma_f32 v[108:109], v[194:195], v[118:119], v[108:109] op_sel_hi:[1,0,1]
	v_pk_fma_f32 v[106:107], v[200:201], v[120:121], v[106:107] op_sel_hi:[1,0,1]
	v_pk_fma_f32 v[108:109], v[202:203], v[120:121], v[108:109] op_sel_hi:[1,0,1]
	v_pk_fma_f32 v[106:107], v[204:205], v[112:113], v[106:107] op_sel_hi:[1,0,1]
	v_pk_fma_f32 v[108:109], v[206:207], v[112:113], v[108:109] op_sel_hi:[1,0,1]
	v_pk_add_f32 v[34:35], v[34:35], v[106:107]
	v_pk_add_f32 v[36:37], v[36:37], v[108:109]
	s_waitcnt lgkmcnt(6)
	v_mov_b32_e32 v112, v125
	v_pk_mul_f32 v[106:107], v[196:197], v[122:123] op_sel:[0,1]
	v_pk_mul_f32 v[108:109], v[198:199], v[122:123] op_sel:[0,1]
	v_pk_fma_f32 v[106:107], v[192:193], v[122:123], v[106:107] op_sel_hi:[1,0,1]
	v_pk_fma_f32 v[108:109], v[194:195], v[122:123], v[108:109] op_sel_hi:[1,0,1]
	v_pk_fma_f32 v[106:107], v[200:201], v[124:125], v[106:107] op_sel_hi:[1,0,1]
	v_pk_fma_f32 v[108:109], v[202:203], v[124:125], v[108:109] op_sel_hi:[1,0,1]
	v_pk_fma_f32 v[106:107], v[204:205], v[112:113], v[106:107] op_sel_hi:[1,0,1]
	v_pk_fma_f32 v[108:109], v[206:207], v[112:113], v[108:109] op_sel_hi:[1,0,1]
	v_pk_add_f32 v[30:31], v[30:31], v[106:107]
	v_pk_add_f32 v[32:33], v[32:33], v[108:109]
	s_waitcnt lgkmcnt(5)
	v_mov_b32_e32 v112, v129
	v_pk_mul_f32 v[106:107], v[196:197], v[126:127] op_sel:[0,1]
	v_pk_mul_f32 v[108:109], v[198:199], v[126:127] op_sel:[0,1]
	v_pk_fma_f32 v[106:107], v[192:193], v[126:127], v[106:107] op_sel_hi:[1,0,1]
	v_pk_fma_f32 v[108:109], v[194:195], v[126:127], v[108:109] op_sel_hi:[1,0,1]
	v_pk_fma_f32 v[106:107], v[200:201], v[128:129], v[106:107] op_sel_hi:[1,0,1]
	v_pk_fma_f32 v[108:109], v[202:203], v[128:129], v[108:109] op_sel_hi:[1,0,1]
	v_pk_fma_f32 v[106:107], v[204:205], v[112:113], v[106:107] op_sel_hi:[1,0,1]
	v_pk_fma_f32 v[108:109], v[206:207], v[112:113], v[108:109] op_sel_hi:[1,0,1]
	v_pk_add_f32 v[26:27], v[26:27], v[106:107]
	v_pk_add_f32 v[28:29], v[28:29], v[108:109]
	s_waitcnt lgkmcnt(4)
	v_mov_b32_e32 v112, v133
	v_pk_mul_f32 v[106:107], v[196:197], v[130:131] op_sel:[0,1]
	v_pk_mul_f32 v[108:109], v[198:199], v[130:131] op_sel:[0,1]
	v_pk_fma_f32 v[106:107], v[192:193], v[130:131], v[106:107] op_sel_hi:[1,0,1]
	v_pk_fma_f32 v[108:109], v[194:195], v[130:131], v[108:109] op_sel_hi:[1,0,1]
	v_pk_fma_f32 v[106:107], v[200:201], v[132:133], v[106:107] op_sel_hi:[1,0,1]
	v_pk_fma_f32 v[108:109], v[202:203], v[132:133], v[108:109] op_sel_hi:[1,0,1]
	v_pk_fma_f32 v[106:107], v[204:205], v[112:113], v[106:107] op_sel_hi:[1,0,1]
	v_pk_fma_f32 v[108:109], v[206:207], v[112:113], v[108:109] op_sel_hi:[1,0,1]
	v_pk_add_f32 v[18:19], v[18:19], v[106:107]
	v_pk_add_f32 v[20:21], v[20:21], v[108:109]
	s_waitcnt lgkmcnt(3)
	v_mov_b32_e32 v112, v137
	v_pk_mul_f32 v[106:107], v[196:197], v[134:135] op_sel:[0,1]
	v_pk_mul_f32 v[108:109], v[198:199], v[134:135] op_sel:[0,1]
	v_pk_fma_f32 v[106:107], v[192:193], v[134:135], v[106:107] op_sel_hi:[1,0,1]
	v_pk_fma_f32 v[108:109], v[194:195], v[134:135], v[108:109] op_sel_hi:[1,0,1]
	v_pk_fma_f32 v[106:107], v[200:201], v[136:137], v[106:107] op_sel_hi:[1,0,1]
	v_pk_fma_f32 v[108:109], v[202:203], v[136:137], v[108:109] op_sel_hi:[1,0,1]
	v_pk_fma_f32 v[106:107], v[204:205], v[112:113], v[106:107] op_sel_hi:[1,0,1]
	v_pk_fma_f32 v[108:109], v[206:207], v[112:113], v[108:109] op_sel_hi:[1,0,1]
	v_pk_add_f32 v[14:15], v[14:15], v[106:107]
	v_pk_add_f32 v[16:17], v[16:17], v[108:109]
	s_waitcnt lgkmcnt(2)
; __device__ __forceinline__ float4 ld_nt4(const float* p) { const f32x4v v = __builtin_nontemporal_load((const f32x4v*)p); return make_float4(v[0], v[1], v[2], v[3]); }
; DI void p0_mod_item(const Params& P, unsigned char* lds, int idx, const int tid) {
;     ...
;   for (int k4 = 0; k4 < 32; ++k4) {
;     float4 w0 = ld_nt4(W + (size_t)(k4 * 4 + 0) * NMOD);
;     float4 w1 = ld_nt4(W + (size_t)(k4 * 4 + 1) * NMOD);
;     float4 w2 = ld_nt4(W + (size_t)(k4 * 4 + 2) * NMOD);
;     float4 w3 = ld_nt4(W + (size_t)(k4 * 4 + 3) * NMOD);
; #pragma unroll
;     for (int r = 0; r < 9; ++r) {
;       float4 s4 = *(const float4*)(sl + r * 1024 + wave * 128 + k4 * 4);
;       acc[r].x += s4.x * w0.x + s4.y * w1.x + s4.z * w2.x + s4.w * w3.x;
;       acc[r].y += s4.x * w0.y + s4.y * w1.y + s4.z * w2.y + s4.w * w3.y;
;       acc[r].z += s4.x * w0.z + s4.y * w1.z + s4.z * w2.z + s4.w * w3.z;
;       acc[r].w += s4.x * w0.w + s4.y * w1.w + s4.z * w2.w + s4.w * w3.w;
;     }
;   }
	v_mov_b32_e32 v112, v141
	v_pk_mul_f32 v[106:107], v[196:197], v[138:139] op_sel:[0,1]
	v_pk_mul_f32 v[108:109], v[198:199], v[138:139] op_sel:[0,1]
	v_pk_fma_f32 v[106:107], v[192:193], v[138:139], v[106:107] op_sel_hi:[1,0,1]
	v_pk_fma_f32 v[108:109], v[194:195], v[138:139], v[108:109] op_sel_hi:[1,0,1]
	v_pk_fma_f32 v[106:107], v[200:201], v[140:141], v[106:107] op_sel_hi:[1,0,1]
	v_pk_fma_f32 v[108:109], v[202:203], v[140:141], v[108:109] op_sel_hi:[1,0,1]
	v_pk_fma_f32 v[106:107], v[204:205], v[112:113], v[106:107] op_sel_hi:[1,0,1]
	v_pk_fma_f32 v[108:109], v[206:207], v[112:113], v[108:109] op_sel_hi:[1,0,1]
	v_pk_add_f32 v[10:11], v[10:11], v[106:107]
	v_pk_add_f32 v[12:13], v[12:13], v[108:109]
	s_waitcnt lgkmcnt(1)
	v_mov_b32_e32 v112, v145
	v_pk_mul_f32 v[106:107], v[196:197], v[142:143] op_sel:[0,1]
	v_pk_mul_f32 v[108:109], v[198:199], v[142:143] op_sel:[0,1]
	v_pk_fma_f32 v[106:107], v[192:193], v[142:143], v[106:107] op_sel_hi:[1,0,1]
	v_pk_fma_f32 v[108:109], v[194:195], v[142:143], v[108:109] op_sel_hi:[1,0,1]
	v_pk_fma_f32 v[106:107], v[200:201], v[144:145], v[106:107] op_sel_hi:[1,0,1]
	v_pk_fma_f32 v[108:109], v[202:203], v[144:145], v[108:109] op_sel_hi:[1,0,1]
	v_pk_fma_f32 v[106:107], v[204:205], v[112:113], v[106:107] op_sel_hi:[1,0,1]
	v_pk_fma_f32 v[108:109], v[206:207], v[112:113], v[108:109] op_sel_hi:[1,0,1]
	v_pk_add_f32 v[6:7], v[6:7], v[106:107]
	v_pk_add_f32 v[8:9], v[8:9], v[108:109]
	s_waitcnt lgkmcnt(0)
	v_mov_b32_e32 v112, v149
	v_pk_mul_f32 v[106:107], v[196:197], v[146:147] op_sel:[0,1]
	v_pk_mul_f32 v[108:109], v[198:199], v[146:147] op_sel:[0,1]
	v_pk_fma_f32 v[106:107], v[192:193], v[146:147], v[106:107] op_sel_hi:[1,0,1]
	v_pk_fma_f32 v[108:109], v[194:195], v[146:147], v[108:109] op_sel_hi:[1,0,1]
	v_pk_fma_f32 v[106:107], v[200:201], v[148:149], v[106:107] op_sel_hi:[1,0,1]
	v_pk_fma_f32 v[108:109], v[202:203], v[148:149], v[108:109] op_sel_hi:[1,0,1]
	v_pk_fma_f32 v[106:107], v[204:205], v[112:113], v[106:107] op_sel_hi:[1,0,1]
	v_pk_fma_f32 v[108:109], v[206:207], v[112:113], v[108:109] op_sel_hi:[1,0,1]
	v_pk_add_f32 v[2:3], v[2:3], v[106:107]
	v_pk_add_f32 v[4:5], v[4:5], v[108:109]
	global_load_dwordx4 v[192:195], v[150:151], off nt
	v_lshl_add_u64 v[150:151], v[150:151], 0, s[0:1]
	global_load_dwordx4 v[196:199], v[150:151], off nt
	v_lshl_add_u64 v[150:151], v[150:151], 0, s[0:1]
	global_load_dwordx4 v[200:203], v[150:151], off nt
	v_lshl_add_u64 v[150:151], v[150:151], 0, s[0:1]
	global_load_dwordx4 v[204:207], v[150:151], off nt
	v_lshl_add_u64 v[150:151], v[150:151], 0, s[0:1]
	v_add_u32_e32 v152, 64, v152
	s_add_i32 s100, s100, 1
	s_cmp_lt_u32 s100, 7
	s_cbranch_scc1 .Lmod_a_trip
	ds_read_b128 v[114:117], v152
	ds_read_b128 v[118:121], v152 offset:4096
	ds_read_b128 v[122:125], v152 offset:8192
	ds_read_b128 v[126:129], v152 offset:12288
	ds_read_b128 v[130:133], v152 offset:16384
	ds_read_b128 v[134:137], v152 offset:20480
	ds_read_b128 v[138:141], v152 offset:24576
	ds_read_b128 v[142:145], v152 offset:28672
	ds_read_b128 v[146:149], v152 offset:32768
	s_waitcnt vmcnt(12)
	s_waitcnt lgkmcnt(8)
	v_mov_b32_e32 v112, v117
	v_pk_mul_f32 v[106:107], v[42:43], v[114:115] op_sel:[0,1]
	v_pk_mul_f32 v[108:109], v[44:45], v[114:115] op_sel:[0,1]
	v_pk_fma_f32 v[106:107], v[38:39], v[114:115], v[106:107] op_sel_hi:[1,0,1]
	v_pk_fma_f32 v[108:109], v[40:41], v[114:115], v[108:109] op_sel_hi:[1,0,1]
	v_pk_fma_f32 v[106:107], v[46:47], v[116:117], v[106:107] op_sel_hi:[1,0,1]
	v_pk_fma_f32 v[108:109], v[48:49], v[116:117], v[108:109] op_sel_hi:[1,0,1]
	v_pk_fma_f32 v[106:107], v[50:51], v[112:113], v[106:107] op_sel_hi:[1,0,1]
	v_pk_fma_f32 v[108:109], v[52:53], v[112:113], v[108:109] op_sel_hi:[1,0,1]
	v_pk_add_f32 v[22:23], v[22:23], v[106:107]
	v_pk_add_f32 v[24:25], v[24:25], v[108:109]
	s_waitcnt lgkmcnt(7)
	v_mov_b32_e32 v112, v121
	v_pk_mul_f32 v[106:107], v[42:43], v[118:119] op_sel:[0,1]
	v_pk_mul_f32 v[108:109], v[44:45], v[118:119] op_sel:[0,1]
	v_pk_fma_f32 v[106:107], v[38:39], v[118:119], v[106:107] op_sel_hi:[1,0,1]
	v_pk_fma_f32 v[108:109], v[40:41], v[118:119], v[108:109] op_sel_hi:[1,0,1]
	v_pk_fma_f32 v[106:107], v[46:47], v[120:121], v[106:107] op_sel_hi:[1,0,1]
	v_pk_fma_f32 v[108:109], v[48:49], v[120:121], v[108:109] op_sel_hi:[1,0,1]
	v_pk_fma_f32 v[106:107], v[50:51], v[112:113], v[106:107] op_sel_hi:[1,0,1]
	v_pk_fma_f32 v[108:109], v[52:53], v[112:113], v[108:109] op_sel_hi:[1,0,1]
	v_pk_add_f32 v[34:35], v[34:35], v[106:107]
	v_pk_add_f32 v[36:37], v[36:37], v[108:109]
	s_waitcnt lgkmcnt(6)
	v_mov_b32_e32 v112, v125
	v_pk_mul_f32 v[106:107], v[42:43], v[122:123] op_sel:[0,1]
	v_pk_mul_f32 v[108:109], v[44:45], v[122:123] op_sel:[0,1]
	v_pk_fma_f32 v[106:107], v[38:39], v[122:123], v[106:107] op_sel_hi:[1,0,1]
	v_pk_fma_f32 v[108:109], v[40:41], v[122:123], v[108:109] op_sel_hi:[1,0,1]
	v_pk_fma_f32 v[106:107], v[46:47], v[124:125], v[106:107] op_sel_hi:[1,0,1]
	v_pk_fma_f32 v[108:109], v[48:49], v[124:125], v[108:109] op_sel_hi:[1,0,1]
	v_pk_fma_f32 v[106:107], v[50:51], v[112:113], v[106:107] op_sel_hi:[1,0,1]
	v_pk_fma_f32 v[108:109], v[52:53], v[112:113], v[108:109] op_sel_hi:[1,0,1]
	v_pk_add_f32 v[30:31], v[30:31], v[106:107]
	v_pk_add_f32 v[32:33], v[32:33], v[108:109]
	s_waitcnt lgkmcnt(5)
	v_mov_b32_e32 v112, v129
	v_pk_mul_f32 v[106:107], v[42:43], v[126:127] op_sel:[0,1]
	v_pk_mul_f32 v[108:109], v[44:45], v[126:127] op_sel:[0,1]
	v_pk_fma_f32 v[106:107], v[38:39], v[126:127], v[106:107] op_sel_hi:[1,0,1]
	v_pk_fma_f32 v[108:109], v[40:41], v[126:127], v[108:109] op_sel_hi:[1,0,1]
	v_pk_fma_f32 v[106:107], v[46:47], v[128:129], v[106:107] op_sel_hi:[1,0,1]
	v_pk_fma_f32 v[108:109], v[48:49], v[128:129], v[108:109] op_sel_hi:[1,0,1]
	v_pk_fma_f32 v[106:107], v[50:51], v[112:113], v[106:107] op_sel_hi:[1,0,1]
	v_pk_fma_f32 v[108:109], v[52:53], v[112:113], v[108:109] op_sel_hi:[1,0,1]
	v_pk_add_f32 v[26:27], v[26:27], v[106:107]
	v_pk_add_f32 v[28:29], v[28:29], v[108:109]
	s_waitcnt lgkmcnt(4)
; __device__ __forceinline__ float4 ld_nt4(const float* p) { const f32x4v v = __builtin_nontemporal_load((const f32x4v*)p); return make_float4(v[0], v[1], v[2], v[3]); }
; DI void p0_mod_item(const Params& P, unsigned char* lds, int idx, const int tid) {
;     ...
;   for (int k4 = 0; k4 < 32; ++k4) {
;     float4 w0 = ld_nt4(W + (size_t)(k4 * 4 + 0) * NMOD);
;     float4 w1 = ld_nt4(W + (size_t)(k4 * 4 + 1) * NMOD);
;     float4 w2 = ld_nt4(W + (size_t)(k4 * 4 + 2) * NMOD);
;     float4 w3 = ld_nt4(W + (size_t)(k4 * 4 + 3) * NMOD);
; #pragma unroll
;     for (int r = 0; r < 9; ++r) {
;       float4 s4 = *(const float4*)(sl + r * 1024 + wave * 128 + k4 * 4);
;       acc[r].x += s4.x * w0.x + s4.y * w1.x + s4.z * w2.x + s4.w * w3.x;
;       acc[r].y += s4.x * w0.y + s4.y * w1.y + s4.z * w2.y + s4.w * w3.y;
;       acc[r].z += s4.x * w0.z + s4.y * w1.z + s4.z * w2.z + s4.w * w3.z;
;       acc[r].w += s4.x * w0.w + s4.y * w1.w + s4.z * w2.w + s4.w * w3.w;
;     }
;   }
	v_mov_b32_e32 v112, v133
	v_pk_mul_f32 v[106:107], v[42:43], v[130:131] op_sel:[0,1]
	v_pk_mul_f32 v[108:109], v[44:45], v[130:131] op_sel:[0,1]
	v_pk_fma_f32 v[106:107], v[38:39], v[130:131], v[106:107] op_sel_hi:[1,0,1]
	v_pk_fma_f32 v[108:109], v[40:41], v[130:131], v[108:109] op_sel_hi:[1,0,1]
	v_pk_fma_f32 v[106:107], v[46:47], v[132:133], v[106:107] op_sel_hi:[1,0,1]
	v_pk_fma_f32 v[108:109], v[48:49], v[132:133], v[108:109] op_sel_hi:[1,0,1]
	v_pk_fma_f32 v[106:107], v[50:51], v[112:113], v[106:107] op_sel_hi:[1,0,1]
	v_pk_fma_f32 v[108:109], v[52:53], v[112:113], v[108:109] op_sel_hi:[1,0,1]
	v_pk_add_f32 v[18:19], v[18:19], v[106:107]
	v_pk_add_f32 v[20:21], v[20:21], v[108:109]
	s_waitcnt lgkmcnt(3)
	v_mov_b32_e32 v112, v137
	v_pk_mul_f32 v[106:107], v[42:43], v[134:135] op_sel:[0,1]
	v_pk_mul_f32 v[108:109], v[44:45], v[134:135] op_sel:[0,1]
	v_pk_fma_f32 v[106:107], v[38:39], v[134:135], v[106:107] op_sel_hi:[1,0,1]
	v_pk_fma_f32 v[108:109], v[40:41], v[134:135], v[108:109] op_sel_hi:[1,0,1]
	v_pk_fma_f32 v[106:107], v[46:47], v[136:137], v[106:107] op_sel_hi:[1,0,1]
	v_pk_fma_f32 v[108:109], v[48:49], v[136:137], v[108:109] op_sel_hi:[1,0,1]
	v_pk_fma_f32 v[106:107], v[50:51], v[112:113], v[106:107] op_sel_hi:[1,0,1]
	v_pk_fma_f32 v[108:109], v[52:53], v[112:113], v[108:109] op_sel_hi:[1,0,1]
	v_pk_add_f32 v[14:15], v[14:15], v[106:107]
	v_pk_add_f32 v[16:17], v[16:17], v[108:109]
	s_waitcnt lgkmcnt(2)
	v_mov_b32_e32 v112, v141
	v_pk_mul_f32 v[106:107], v[42:43], v[138:139] op_sel:[0,1]
	v_pk_mul_f32 v[108:109], v[44:45], v[138:139] op_sel:[0,1]
	v_pk_fma_f32 v[106:107], v[38:39], v[138:139], v[106:107] op_sel_hi:[1,0,1]
	v_pk_fma_f32 v[108:109], v[40:41], v[138:139], v[108:109] op_sel_hi:[1,0,1]
	v_pk_fma_f32 v[106:107], v[46:47], v[140:141], v[106:107] op_sel_hi:[1,0,1]
	v_pk_fma_f32 v[108:109], v[48:49], v[140:141], v[108:109] op_sel_hi:[1,0,1]
	v_pk_fma_f32 v[106:107], v[50:51], v[112:113], v[106:107] op_sel_hi:[1,0,1]
	v_pk_fma_f32 v[108:109], v[52:53], v[112:113], v[108:109] op_sel_hi:[1,0,1]
	v_pk_add_f32 v[10:11], v[10:11], v[106:107]
	v_pk_add_f32 v[12:13], v[12:13], v[108:109]
	s_waitcnt lgkmcnt(1)
	v_mov_b32_e32 v112, v145
	v_pk_mul_f32 v[106:107], v[42:43], v[142:143] op_sel:[0,1]
	v_pk_mul_f32 v[108:109], v[44:45], v[142:143] op_sel:[0,1]
	v_pk_fma_f32 v[106:107], v[38:39], v[142:143], v[106:107] op_sel_hi:[1,0,1]
	v_pk_fma_f32 v[108:109], v[40:41], v[142:143], v[108:109] op_sel_hi:[1,0,1]
	v_pk_fma_f32 v[106:107], v[46:47], v[144:145], v[106:107] op_sel_hi:[1,0,1]
	v_pk_fma_f32 v[108:109], v[48:49], v[144:145], v[108:109] op_sel_hi:[1,0,1]
	v_pk_fma_f32 v[106:107], v[50:51], v[112:113], v[106:107] op_sel_hi:[1,0,1]
	v_pk_fma_f32 v[108:109], v[52:53], v[112:113], v[108:109] op_sel_hi:[1,0,1]
	v_pk_add_f32 v[6:7], v[6:7], v[106:107]
	v_pk_add_f32 v[8:9], v[8:9], v[108:109]
	s_waitcnt lgkmcnt(0)
	v_mov_b32_e32 v112, v149
	v_pk_mul_f32 v[106:107], v[42:43], v[146:147] op_sel:[0,1]
	v_pk_mul_f32 v[108:109], v[44:45], v[146:147] op_sel:[0,1]
	v_pk_fma_f32 v[106:107], v[38:39], v[146:147], v[106:107] op_sel_hi:[1,0,1]
	v_pk_fma_f32 v[108:109], v[40:41], v[146:147], v[108:109] op_sel_hi:[1,0,1]
	v_pk_fma_f32 v[106:107], v[46:47], v[148:149], v[106:107] op_sel_hi:[1,0,1]
	v_pk_fma_f32 v[108:109], v[48:49], v[148:149], v[108:109] op_sel_hi:[1,0,1]
	v_pk_fma_f32 v[106:107], v[50:51], v[112:113], v[106:107] op_sel_hi:[1,0,1]
	v_pk_fma_f32 v[108:109], v[52:53], v[112:113], v[108:109] op_sel_hi:[1,0,1]
	v_pk_add_f32 v[2:3], v[2:3], v[106:107]
	v_pk_add_f32 v[4:5], v[4:5], v[108:109]
	ds_read_b128 v[114:117], v152 offset:16
	ds_read_b128 v[118:121], v152 offset:4112
	ds_read_b128 v[122:125], v152 offset:8208
	ds_read_b128 v[126:129], v152 offset:12304
	ds_read_b128 v[130:133], v152 offset:16400
	ds_read_b128 v[134:137], v152 offset:20496
	ds_read_b128 v[138:141], v152 offset:24592
	ds_read_b128 v[142:145], v152 offset:28688
	ds_read_b128 v[146:149], v152 offset:32784
	s_waitcnt vmcnt(8)
	s_waitcnt lgkmcnt(8)
	v_mov_b32_e32 v112, v117
	v_pk_mul_f32 v[106:107], v[164:165], v[114:115] op_sel:[0,1]
	v_pk_mul_f32 v[108:109], v[166:167], v[114:115] op_sel:[0,1]
	v_pk_fma_f32 v[106:107], v[160:161], v[114:115], v[106:107] op_sel_hi:[1,0,1]
	v_pk_fma_f32 v[108:109], v[162:163], v[114:115], v[108:109] op_sel_hi:[1,0,1]
	v_pk_fma_f32 v[106:107], v[168:169], v[116:117], v[106:107] op_sel_hi:[1,0,1]
	v_pk_fma_f32 v[108:109], v[170:171], v[116:117], v[108:109] op_sel_hi:[1,0,1]
	v_pk_fma_f32 v[106:107], v[172:173], v[112:113], v[106:107] op_sel_hi:[1,0,1]
	v_pk_fma_f32 v[108:109], v[174:175], v[112:113], v[108:109] op_sel_hi:[1,0,1]
	v_pk_add_f32 v[22:23], v[22:23], v[106:107]
	v_pk_add_f32 v[24:25], v[24:25], v[108:109]
	s_waitcnt lgkmcnt(7)
	v_mov_b32_e32 v112, v121
	v_pk_mul_f32 v[106:107], v[164:165], v[118:119] op_sel:[0,1]
	v_pk_mul_f32 v[108:109], v[166:167], v[118:119] op_sel:[0,1]
	v_pk_fma_f32 v[106:107], v[160:161], v[118:119], v[106:107] op_sel_hi:[1,0,1]
	v_pk_fma_f32 v[108:109], v[162:163], v[118:119], v[108:109] op_sel_hi:[1,0,1]
	v_pk_fma_f32 v[106:107], v[168:169], v[120:121], v[106:107] op_sel_hi:[1,0,1]
	v_pk_fma_f32 v[108:109], v[170:171], v[120:121], v[108:109] op_sel_hi:[1,0,1]
	v_pk_fma_f32 v[106:107], v[172:173], v[112:113], v[106:107] op_sel_hi:[1,0,1]
	v_pk_fma_f32 v[108:109], v[174:175], v[112:113], v[108:109] op_sel_hi:[1,0,1]
	v_pk_add_f32 v[34:35], v[34:35], v[106:107]
	v_pk_add_f32 v[36:37], v[36:37], v[108:109]
	s_waitcnt lgkmcnt(6)
; __device__ __forceinline__ float4 ld_nt4(const float* p) { const f32x4v v = __builtin_nontemporal_load((const f32x4v*)p); return make_float4(v[0], v[1], v[2], v[3]); }
; DI void p0_mod_item(const Params& P, unsigned char* lds, int idx, const int tid) {
;     ...
;   for (int k4 = 0; k4 < 32; ++k4) {
;     float4 w0 = ld_nt4(W + (size_t)(k4 * 4 + 0) * NMOD);
;     float4 w1 = ld_nt4(W + (size_t)(k4 * 4 + 1) * NMOD);
;     float4 w2 = ld_nt4(W + (size_t)(k4 * 4 + 2) * NMOD);
;     float4 w3 = ld_nt4(W + (size_t)(k4 * 4 + 3) * NMOD);
; #pragma unroll
;     for (int r = 0; r < 9; ++r) {
;       float4 s4 = *(const float4*)(sl + r * 1024 + wave * 128 + k4 * 4);
;       acc[r].x += s4.x * w0.x + s4.y * w1.x + s4.z * w2.x + s4.w * w3.x;
;       acc[r].y += s4.x * w0.y + s4.y * w1.y + s4.z * w2.y + s4.w * w3.y;
;       acc[r].z += s4.x * w0.z + s4.y * w1.z + s4.z * w2.z + s4.w * w3.z;
;       acc[r].w += s4.x * w0.w + s4.y * w1.w + s4.z * w2.w + s4.w * w3.w;
;     }
;   }
	v_mov_b32_e32 v112, v125
	v_pk_mul_f32 v[106:107], v[164:165], v[122:123] op_sel:[0,1]
	v_pk_mul_f32 v[108:109], v[166:167], v[122:123] op_sel:[0,1]
	v_pk_fma_f32 v[106:107], v[160:161], v[122:123], v[106:107] op_sel_hi:[1,0,1]
	v_pk_fma_f32 v[108:109], v[162:163], v[122:123], v[108:109] op_sel_hi:[1,0,1]
	v_pk_fma_f32 v[106:107], v[168:169], v[124:125], v[106:107] op_sel_hi:[1,0,1]
	v_pk_fma_f32 v[108:109], v[170:171], v[124:125], v[108:109] op_sel_hi:[1,0,1]
	v_pk_fma_f32 v[106:107], v[172:173], v[112:113], v[106:107] op_sel_hi:[1,0,1]
	v_pk_fma_f32 v[108:109], v[174:175], v[112:113], v[108:109] op_sel_hi:[1,0,1]
	v_pk_add_f32 v[30:31], v[30:31], v[106:107]
	v_pk_add_f32 v[32:33], v[32:33], v[108:109]
	s_waitcnt lgkmcnt(5)
	v_mov_b32_e32 v112, v129
	v_pk_mul_f32 v[106:107], v[164:165], v[126:127] op_sel:[0,1]
	v_pk_mul_f32 v[108:109], v[166:167], v[126:127] op_sel:[0,1]
	v_pk_fma_f32 v[106:107], v[160:161], v[126:127], v[106:107] op_sel_hi:[1,0,1]
	v_pk_fma_f32 v[108:109], v[162:163], v[126:127], v[108:109] op_sel_hi:[1,0,1]
	v_pk_fma_f32 v[106:107], v[168:169], v[128:129], v[106:107] op_sel_hi:[1,0,1]
	v_pk_fma_f32 v[108:109], v[170:171], v[128:129], v[108:109] op_sel_hi:[1,0,1]
	v_pk_fma_f32 v[106:107], v[172:173], v[112:113], v[106:107] op_sel_hi:[1,0,1]
	v_pk_fma_f32 v[108:109], v[174:175], v[112:113], v[108:109] op_sel_hi:[1,0,1]
	v_pk_add_f32 v[26:27], v[26:27], v[106:107]
	v_pk_add_f32 v[28:29], v[28:29], v[108:109]
	s_waitcnt lgkmcnt(4)
	v_mov_b32_e32 v112, v133
	v_pk_mul_f32 v[106:107], v[164:165], v[130:131] op_sel:[0,1]
	v_pk_mul_f32 v[108:109], v[166:167], v[130:131] op_sel:[0,1]
	v_pk_fma_f32 v[106:107], v[160:161], v[130:131], v[106:107] op_sel_hi:[1,0,1]
	v_pk_fma_f32 v[108:109], v[162:163], v[130:131], v[108:109] op_sel_hi:[1,0,1]
	v_pk_fma_f32 v[106:107], v[168:169], v[132:133], v[106:107] op_sel_hi:[1,0,1]
	v_pk_fma_f32 v[108:109], v[170:171], v[132:133], v[108:109] op_sel_hi:[1,0,1]
	v_pk_fma_f32 v[106:107], v[172:173], v[112:113], v[106:107] op_sel_hi:[1,0,1]
	v_pk_fma_f32 v[108:109], v[174:175], v[112:113], v[108:109] op_sel_hi:[1,0,1]
	v_pk_add_f32 v[18:19], v[18:19], v[106:107]
	v_pk_add_f32 v[20:21], v[20:21], v[108:109]
	s_waitcnt lgkmcnt(3)
	v_mov_b32_e32 v112, v137
	v_pk_mul_f32 v[106:107], v[164:165], v[134:135] op_sel:[0,1]
	v_pk_mul_f32 v[108:109], v[166:167], v[134:135] op_sel:[0,1]
	v_pk_fma_f32 v[106:107], v[160:161], v[134:135], v[106:107] op_sel_hi:[1,0,1]
	v_pk_fma_f32 v[108:109], v[162:163], v[134:135], v[108:109] op_sel_hi:[1,0,1]
	v_pk_fma_f32 v[106:107], v[168:169], v[136:137], v[106:107] op_sel_hi:[1,0,1]
	v_pk_fma_f32 v[108:109], v[170:171], v[136:137], v[108:109] op_sel_hi:[1,0,1]
	v_pk_fma_f32 v[106:107], v[172:173], v[112:113], v[106:107] op_sel_hi:[1,0,1]
	v_pk_fma_f32 v[108:109], v[174:175], v[112:113], v[108:109] op_sel_hi:[1,0,1]
	v_pk_add_f32 v[14:15], v[14:15], v[106:107]
	v_pk_add_f32 v[16:17], v[16:17], v[108:109]
	s_waitcnt lgkmcnt(2)
	v_mov_b32_e32 v112, v141
	v_pk_mul_f32 v[106:107], v[164:165], v[138:139] op_sel:[0,1]
	v_pk_mul_f32 v[108:109], v[166:167], v[138:139] op_sel:[0,1]
	v_pk_fma_f32 v[106:107], v[160:161], v[138:139], v[106:107] op_sel_hi:[1,0,1]
	v_pk_fma_f32 v[108:109], v[162:163], v[138:139], v[108:109] op_sel_hi:[1,0,1]
	v_pk_fma_f32 v[106:107], v[168:169], v[140:141], v[106:107] op_sel_hi:[1,0,1]
	v_pk_fma_f32 v[108:109], v[170:171], v[140:141], v[108:109] op_sel_hi:[1,0,1]
	v_pk_fma_f32 v[106:107], v[172:173], v[112:113], v[106:107] op_sel_hi:[1,0,1]
	v_pk_fma_f32 v[108:109], v[174:175], v[112:113], v[108:109] op_sel_hi:[1,0,1]
	v_pk_add_f32 v[10:11], v[10:11], v[106:107]
	v_pk_add_f32 v[12:13], v[12:13], v[108:109]
	s_waitcnt lgkmcnt(1)
	v_mov_b32_e32 v112, v145
	v_pk_mul_f32 v[106:107], v[164:165], v[142:143] op_sel:[0,1]
	v_pk_mul_f32 v[108:109], v[166:167], v[142:143] op_sel:[0,1]
	v_pk_fma_f32 v[106:107], v[160:161], v[142:143], v[106:107] op_sel_hi:[1,0,1]
	v_pk_fma_f32 v[108:109], v[162:163], v[142:143], v[108:109] op_sel_hi:[1,0,1]
	v_pk_fma_f32 v[106:107], v[168:169], v[144:145], v[106:107] op_sel_hi:[1,0,1]
	v_pk_fma_f32 v[108:109], v[170:171], v[144:145], v[108:109] op_sel_hi:[1,0,1]
	v_pk_fma_f32 v[106:107], v[172:173], v[112:113], v[106:107] op_sel_hi:[1,0,1]
	v_pk_fma_f32 v[108:109], v[174:175], v[112:113], v[108:109] op_sel_hi:[1,0,1]
	v_pk_add_f32 v[6:7], v[6:7], v[106:107]
	v_pk_add_f32 v[8:9], v[8:9], v[108:109]
	s_waitcnt lgkmcnt(0)
	v_mov_b32_e32 v112, v149
	v_pk_mul_f32 v[106:107], v[164:165], v[146:147] op_sel:[0,1]
	v_pk_mul_f32 v[108:109], v[166:167], v[146:147] op_sel:[0,1]
	v_pk_fma_f32 v[106:107], v[160:161], v[146:147], v[106:107] op_sel_hi:[1,0,1]
	v_pk_fma_f32 v[108:109], v[162:163], v[146:147], v[108:109] op_sel_hi:[1,0,1]
	v_pk_fma_f32 v[106:107], v[168:169], v[148:149], v[106:107] op_sel_hi:[1,0,1]
	v_pk_fma_f32 v[108:109], v[170:171], v[148:149], v[108:109] op_sel_hi:[1,0,1]
	v_pk_fma_f32 v[106:107], v[172:173], v[112:113], v[106:107] op_sel_hi:[1,0,1]
	v_pk_fma_f32 v[108:109], v[174:175], v[112:113], v[108:109] op_sel_hi:[1,0,1]
	v_pk_add_f32 v[2:3], v[2:3], v[106:107]
	v_pk_add_f32 v[4:5], v[4:5], v[108:109]
	ds_read_b128 v[114:117], v152 offset:32
	ds_read_b128 v[118:121], v152 offset:4128
	ds_read_b128 v[122:125], v152 offset:8224
	ds_read_b128 v[126:129], v152 offset:12320
	ds_read_b128 v[130:133], v152 offset:16416
	ds_read_b128 v[134:137], v152 offset:20512
	ds_read_b128 v[138:141], v152 offset:24608
	ds_read_b128 v[142:145], v152 offset:28704
	ds_read_b128 v[146:149], v152 offset:32800
	s_waitcnt vmcnt(4)
	s_waitcnt lgkmcnt(8)
; __device__ __forceinline__ float4 ld_nt4(const float* p) { const f32x4v v = __builtin_nontemporal_load((const f32x4v*)p); return make_float4(v[0], v[1], v[2], v[3]); }
; DI void p0_mod_item(const Params& P, unsigned char* lds, int idx, const int tid) {
;     ...
;   for (int k4 = 0; k4 < 32; ++k4) {
;     float4 w0 = ld_nt4(W + (size_t)(k4 * 4 + 0) * NMOD);
;     float4 w1 = ld_nt4(W + (size_t)(k4 * 4 + 1) * NMOD);
;     float4 w2 = ld_nt4(W + (size_t)(k4 * 4 + 2) * NMOD);
;     float4 w3 = ld_nt4(W + (size_t)(k4 * 4 + 3) * NMOD);
; #pragma unroll
;     for (int r = 0; r < 9; ++r) {
;       float4 s4 = *(const float4*)(sl + r * 1024 + wave * 128 + k4 * 4);
;       acc[r].x += s4.x * w0.x + s4.y * w1.x + s4.z * w2.x + s4.w * w3.x;
;       acc[r].y += s4.x * w0.y + s4.y * w1.y + s4.z * w2.y + s4.w * w3.y;
;       acc[r].z += s4.x * w0.z + s4.y * w1.z + s4.z * w2.z + s4.w * w3.z;
;       acc[r].w += s4.x * w0.w + s4.y * w1.w + s4.z * w2.w + s4.w * w3.w;
;     }
;   }
	v_mov_b32_e32 v112, v117
	v_pk_mul_f32 v[106:107], v[180:181], v[114:115] op_sel:[0,1]
	v_pk_mul_f32 v[108:109], v[182:183], v[114:115] op_sel:[0,1]
	v_pk_fma_f32 v[106:107], v[176:177], v[114:115], v[106:107] op_sel_hi:[1,0,1]
	v_pk_fma_f32 v[108:109], v[178:179], v[114:115], v[108:109] op_sel_hi:[1,0,1]
	v_pk_fma_f32 v[106:107], v[184:185], v[116:117], v[106:107] op_sel_hi:[1,0,1]
	v_pk_fma_f32 v[108:109], v[186:187], v[116:117], v[108:109] op_sel_hi:[1,0,1]
	v_pk_fma_f32 v[106:107], v[188:189], v[112:113], v[106:107] op_sel_hi:[1,0,1]
	v_pk_fma_f32 v[108:109], v[190:191], v[112:113], v[108:109] op_sel_hi:[1,0,1]
	v_pk_add_f32 v[22:23], v[22:23], v[106:107]
	v_pk_add_f32 v[24:25], v[24:25], v[108:109]
	s_waitcnt lgkmcnt(7)
	v_mov_b32_e32 v112, v121
	v_pk_mul_f32 v[106:107], v[180:181], v[118:119] op_sel:[0,1]
	v_pk_mul_f32 v[108:109], v[182:183], v[118:119] op_sel:[0,1]
	v_pk_fma_f32 v[106:107], v[176:177], v[118:119], v[106:107] op_sel_hi:[1,0,1]
	v_pk_fma_f32 v[108:109], v[178:179], v[118:119], v[108:109] op_sel_hi:[1,0,1]
	v_pk_fma_f32 v[106:107], v[184:185], v[120:121], v[106:107] op_sel_hi:[1,0,1]
	v_pk_fma_f32 v[108:109], v[186:187], v[120:121], v[108:109] op_sel_hi:[1,0,1]
	v_pk_fma_f32 v[106:107], v[188:189], v[112:113], v[106:107] op_sel_hi:[1,0,1]
	v_pk_fma_f32 v[108:109], v[190:191], v[112:113], v[108:109] op_sel_hi:[1,0,1]
	v_pk_add_f32 v[34:35], v[34:35], v[106:107]
	v_pk_add_f32 v[36:37], v[36:37], v[108:109]
	s_waitcnt lgkmcnt(6)
	v_mov_b32_e32 v112, v125
	v_pk_mul_f32 v[106:107], v[180:181], v[122:123] op_sel:[0,1]
	v_pk_mul_f32 v[108:109], v[182:183], v[122:123] op_sel:[0,1]
	v_pk_fma_f32 v[106:107], v[176:177], v[122:123], v[106:107] op_sel_hi:[1,0,1]
	v_pk_fma_f32 v[108:109], v[178:179], v[122:123], v[108:109] op_sel_hi:[1,0,1]
	v_pk_fma_f32 v[106:107], v[184:185], v[124:125], v[106:107] op_sel_hi:[1,0,1]
	v_pk_fma_f32 v[108:109], v[186:187], v[124:125], v[108:109] op_sel_hi:[1,0,1]
	v_pk_fma_f32 v[106:107], v[188:189], v[112:113], v[106:107] op_sel_hi:[1,0,1]
	v_pk_fma_f32 v[108:109], v[190:191], v[112:113], v[108:109] op_sel_hi:[1,0,1]
	v_pk_add_f32 v[30:31], v[30:31], v[106:107]
	v_pk_add_f32 v[32:33], v[32:33], v[108:109]
	s_waitcnt lgkmcnt(5)
	v_mov_b32_e32 v112, v129
	v_pk_mul_f32 v[106:107], v[180:181], v[126:127] op_sel:[0,1]
	v_pk_mul_f32 v[108:109], v[182:183], v[126:127] op_sel:[0,1]
	v_pk_fma_f32 v[106:107], v[176:177], v[126:127], v[106:107] op_sel_hi:[1,0,1]
	v_pk_fma_f32 v[108:109], v[178:179], v[126:127], v[108:109] op_sel_hi:[1,0,1]
	v_pk_fma_f32 v[106:107], v[184:185], v[128:129], v[106:107] op_sel_hi:[1,0,1]
	v_pk_fma_f32 v[108:109], v[186:187], v[128:129], v[108:109] op_sel_hi:[1,0,1]
	v_pk_fma_f32 v[106:107], v[188:189], v[112:113], v[106:107] op_sel_hi:[1,0,1]
	v_pk_fma_f32 v[108:109], v[190:191], v[112:113], v[108:109] op_sel_hi:[1,0,1]
	v_pk_add_f32 v[26:27], v[26:27], v[106:107]
	v_pk_add_f32 v[28:29], v[28:29], v[108:109]
	s_waitcnt lgkmcnt(4)
	v_mov_b32_e32 v112, v133
	v_pk_mul_f32 v[106:107], v[180:181], v[130:131] op_sel:[0,1]
	v_pk_mul_f32 v[108:109], v[182:183], v[130:131] op_sel:[0,1]
	v_pk_fma_f32 v[106:107], v[176:177], v[130:131], v[106:107] op_sel_hi:[1,0,1]
	v_pk_fma_f32 v[108:109], v[178:179], v[130:131], v[108:109] op_sel_hi:[1,0,1]
	v_pk_fma_f32 v[106:107], v[184:185], v[132:133], v[106:107] op_sel_hi:[1,0,1]
	v_pk_fma_f32 v[108:109], v[186:187], v[132:133], v[108:109] op_sel_hi:[1,0,1]
	v_pk_fma_f32 v[106:107], v[188:189], v[112:113], v[106:107] op_sel_hi:[1,0,1]
	v_pk_fma_f32 v[108:109], v[190:191], v[112:113], v[108:109] op_sel_hi:[1,0,1]
	v_pk_add_f32 v[18:19], v[18:19], v[106:107]
	v_pk_add_f32 v[20:21], v[20:21], v[108:109]
	s_waitcnt lgkmcnt(3)
	v_mov_b32_e32 v112, v137
	v_pk_mul_f32 v[106:107], v[180:181], v[134:135] op_sel:[0,1]
	v_pk_mul_f32 v[108:109], v[182:183], v[134:135] op_sel:[0,1]
	v_pk_fma_f32 v[106:107], v[176:177], v[134:135], v[106:107] op_sel_hi:[1,0,1]
	v_pk_fma_f32 v[108:109], v[178:179], v[134:135], v[108:109] op_sel_hi:[1,0,1]
	v_pk_fma_f32 v[106:107], v[184:185], v[136:137], v[106:107] op_sel_hi:[1,0,1]
	v_pk_fma_f32 v[108:109], v[186:187], v[136:137], v[108:109] op_sel_hi:[1,0,1]
	v_pk_fma_f32 v[106:107], v[188:189], v[112:113], v[106:107] op_sel_hi:[1,0,1]
	v_pk_fma_f32 v[108:109], v[190:191], v[112:113], v[108:109] op_sel_hi:[1,0,1]
	v_pk_add_f32 v[14:15], v[14:15], v[106:107]
	v_pk_add_f32 v[16:17], v[16:17], v[108:109]
	s_waitcnt lgkmcnt(2)
	v_mov_b32_e32 v112, v141
	v_pk_mul_f32 v[106:107], v[180:181], v[138:139] op_sel:[0,1]
	v_pk_mul_f32 v[108:109], v[182:183], v[138:139] op_sel:[0,1]
	v_pk_fma_f32 v[106:107], v[176:177], v[138:139], v[106:107] op_sel_hi:[1,0,1]
	v_pk_fma_f32 v[108:109], v[178:179], v[138:139], v[108:109] op_sel_hi:[1,0,1]
	v_pk_fma_f32 v[106:107], v[184:185], v[140:141], v[106:107] op_sel_hi:[1,0,1]
	v_pk_fma_f32 v[108:109], v[186:187], v[140:141], v[108:109] op_sel_hi:[1,0,1]
	v_pk_fma_f32 v[106:107], v[188:189], v[112:113], v[106:107] op_sel_hi:[1,0,1]
	v_pk_fma_f32 v[108:109], v[190:191], v[112:113], v[108:109] op_sel_hi:[1,0,1]
	v_pk_add_f32 v[10:11], v[10:11], v[106:107]
	v_pk_add_f32 v[12:13], v[12:13], v[108:109]
	s_waitcnt lgkmcnt(1)
	v_mov_b32_e32 v112, v145
	v_pk_mul_f32 v[106:107], v[180:181], v[142:143] op_sel:[0,1]
	v_pk_mul_f32 v[108:109], v[182:183], v[142:143] op_sel:[0,1]
	v_pk_fma_f32 v[106:107], v[176:177], v[142:143], v[106:107] op_sel_hi:[1,0,1]
	v_pk_fma_f32 v[108:109], v[178:179], v[142:143], v[108:109] op_sel_hi:[1,0,1]
	v_pk_fma_f32 v[106:107], v[184:185], v[144:145], v[106:107] op_sel_hi:[1,0,1]
	v_pk_fma_f32 v[108:109], v[186:187], v[144:145], v[108:109] op_sel_hi:[1,0,1]
	v_pk_fma_f32 v[106:107], v[188:189], v[112:113], v[106:107] op_sel_hi:[1,0,1]
	v_pk_fma_f32 v[108:109], v[190:191], v[112:113], v[108:109] op_sel_hi:[1,0,1]
	v_pk_add_f32 v[6:7], v[6:7], v[106:107]
	v_pk_add_f32 v[8:9], v[8:9], v[108:109]
	s_waitcnt lgkmcnt(0)
; __device__ __forceinline__ float4 ld_nt4(const float* p) { const f32x4v v = __builtin_nontemporal_load((const f32x4v*)p); return make_float4(v[0], v[1], v[2], v[3]); }
; DI void p0_mod_item(const Params& P, unsigned char* lds, int idx, const int tid) {
;     ...
;   for (int k4 = 0; k4 < 32; ++k4) {
;     float4 w0 = ld_nt4(W + (size_t)(k4 * 4 + 0) * NMOD);
;     float4 w1 = ld_nt4(W + (size_t)(k4 * 4 + 1) * NMOD);
;     float4 w2 = ld_nt4(W + (size_t)(k4 * 4 + 2) * NMOD);
;     float4 w3 = ld_nt4(W + (size_t)(k4 * 4 + 3) * NMOD);
; #pragma unroll
;     for (int r = 0; r < 9; ++r) {
;       float4 s4 = *(const float4*)(sl + r * 1024 + wave * 128 + k4 * 4);
;       acc[r].x += s4.x * w0.x + s4.y * w1.x + s4.z * w2.x + s4.w * w3.x;
;       acc[r].y += s4.x * w0.y + s4.y * w1.y + s4.z * w2.y + s4.w * w3.y;
;       acc[r].z += s4.x * w0.z + s4.y * w1.z + s4.z * w2.z + s4.w * w3.z;
;       acc[r].w += s4.x * w0.w + s4.y * w1.w + s4.z * w2.w + s4.w * w3.w;
;     }
;   }
	v_mov_b32_e32 v112, v149
	v_pk_mul_f32 v[106:107], v[180:181], v[146:147] op_sel:[0,1]
	v_pk_mul_f32 v[108:109], v[182:183], v[146:147] op_sel:[0,1]
	v_pk_fma_f32 v[106:107], v[176:177], v[146:147], v[106:107] op_sel_hi:[1,0,1]
	v_pk_fma_f32 v[108:109], v[178:179], v[146:147], v[108:109] op_sel_hi:[1,0,1]
	v_pk_fma_f32 v[106:107], v[184:185], v[148:149], v[106:107] op_sel_hi:[1,0,1]
	v_pk_fma_f32 v[108:109], v[186:187], v[148:149], v[108:109] op_sel_hi:[1,0,1]
	v_pk_fma_f32 v[106:107], v[188:189], v[112:113], v[106:107] op_sel_hi:[1,0,1]
	v_pk_fma_f32 v[108:109], v[190:191], v[112:113], v[108:109] op_sel_hi:[1,0,1]
	v_pk_add_f32 v[2:3], v[2:3], v[106:107]
	v_pk_add_f32 v[4:5], v[4:5], v[108:109]
	ds_read_b128 v[114:117], v152 offset:48
	ds_read_b128 v[118:121], v152 offset:4144
	ds_read_b128 v[122:125], v152 offset:8240
	ds_read_b128 v[126:129], v152 offset:12336
	ds_read_b128 v[130:133], v152 offset:16432
	ds_read_b128 v[134:137], v152 offset:20528
	ds_read_b128 v[138:141], v152 offset:24624
	ds_read_b128 v[142:145], v152 offset:28720
	ds_read_b128 v[146:149], v152 offset:32816
	s_waitcnt vmcnt(0)
	s_waitcnt lgkmcnt(8)
	v_mov_b32_e32 v112, v117
	v_pk_mul_f32 v[106:107], v[196:197], v[114:115] op_sel:[0,1]
	v_pk_mul_f32 v[108:109], v[198:199], v[114:115] op_sel:[0,1]
	v_pk_fma_f32 v[106:107], v[192:193], v[114:115], v[106:107] op_sel_hi:[1,0,1]
	v_pk_fma_f32 v[108:109], v[194:195], v[114:115], v[108:109] op_sel_hi:[1,0,1]
	v_pk_fma_f32 v[106:107], v[200:201], v[116:117], v[106:107] op_sel_hi:[1,0,1]
	v_pk_fma_f32 v[108:109], v[202:203], v[116:117], v[108:109] op_sel_hi:[1,0,1]
	v_pk_fma_f32 v[106:107], v[204:205], v[112:113], v[106:107] op_sel_hi:[1,0,1]
	v_pk_fma_f32 v[108:109], v[206:207], v[112:113], v[108:109] op_sel_hi:[1,0,1]
	v_pk_add_f32 v[22:23], v[22:23], v[106:107]
	v_pk_add_f32 v[24:25], v[24:25], v[108:109]
	s_waitcnt lgkmcnt(7)
	v_mov_b32_e32 v112, v121
	v_pk_mul_f32 v[106:107], v[196:197], v[118:119] op_sel:[0,1]
	v_pk_mul_f32 v[108:109], v[198:199], v[118:119] op_sel:[0,1]
	v_pk_fma_f32 v[106:107], v[192:193], v[118:119], v[106:107] op_sel_hi:[1,0,1]
	v_pk_fma_f32 v[108:109], v[194:195], v[118:119], v[108:109] op_sel_hi:[1,0,1]
	v_pk_fma_f32 v[106:107], v[200:201], v[120:121], v[106:107] op_sel_hi:[1,0,1]
	v_pk_fma_f32 v[108:109], v[202:203], v[120:121], v[108:109] op_sel_hi:[1,0,1]
	v_pk_fma_f32 v[106:107], v[204:205], v[112:113], v[106:107] op_sel_hi:[1,0,1]
	v_pk_fma_f32 v[108:109], v[206:207], v[112:113], v[108:109] op_sel_hi:[1,0,1]
	v_pk_add_f32 v[34:35], v[34:35], v[106:107]
	v_pk_add_f32 v[36:37], v[36:37], v[108:109]
	s_waitcnt lgkmcnt(6)
	v_mov_b32_e32 v112, v125
	v_pk_mul_f32 v[106:107], v[196:197], v[122:123] op_sel:[0,1]
	v_pk_mul_f32 v[108:109], v[198:199], v[122:123] op_sel:[0,1]
	v_pk_fma_f32 v[106:107], v[192:193], v[122:123], v[106:107] op_sel_hi:[1,0,1]
	v_pk_fma_f32 v[108:109], v[194:195], v[122:123], v[108:109] op_sel_hi:[1,0,1]
	v_pk_fma_f32 v[106:107], v[200:201], v[124:125], v[106:107] op_sel_hi:[1,0,1]
	v_pk_fma_f32 v[108:109], v[202:203], v[124:125], v[108:109] op_sel_hi:[1,0,1]
	v_pk_fma_f32 v[106:107], v[204:205], v[112:113], v[106:107] op_sel_hi:[1,0,1]
	v_pk_fma_f32 v[108:109], v[206:207], v[112:113], v[108:109] op_sel_hi:[1,0,1]
	v_pk_add_f32 v[30:31], v[30:31], v[106:107]
	v_pk_add_f32 v[32:33], v[32:33], v[108:109]
	s_waitcnt lgkmcnt(5)
	v_mov_b32_e32 v112, v129
	v_pk_mul_f32 v[106:107], v[196:197], v[126:127] op_sel:[0,1]
	v_pk_mul_f32 v[108:109], v[198:199], v[126:127] op_sel:[0,1]
	v_pk_fma_f32 v[106:107], v[192:193], v[126:127], v[106:107] op_sel_hi:[1,0,1]
	v_pk_fma_f32 v[108:109], v[194:195], v[126:127], v[108:109] op_sel_hi:[1,0,1]
	v_pk_fma_f32 v[106:107], v[200:201], v[128:129], v[106:107] op_sel_hi:[1,0,1]
	v_pk_fma_f32 v[108:109], v[202:203], v[128:129], v[108:109] op_sel_hi:[1,0,1]
	v_pk_fma_f32 v[106:107], v[204:205], v[112:113], v[106:107] op_sel_hi:[1,0,1]
	v_pk_fma_f32 v[108:109], v[206:207], v[112:113], v[108:109] op_sel_hi:[1,0,1]
	v_pk_add_f32 v[26:27], v[26:27], v[106:107]
	v_pk_add_f32 v[28:29], v[28:29], v[108:109]
	s_waitcnt lgkmcnt(4)
; DI void p0_mod_item(const Params& P, unsigned char* lds, int idx, const int tid) {
;     ...
;     for (int r = 0; r < 9; ++r) {
;       float4 s4 = *(const float4*)(sl + r * 1024 + wave * 128 + k4 * 4);
;       acc[r].x += s4.x * w0.x + s4.y * w1.x + s4.z * w2.x + s4.w * w3.x;
;       acc[r].y += s4.x * w0.y + s4.y * w1.y + s4.z * w2.y + s4.w * w3.y;
;       acc[r].z += s4.x * w0.z + s4.y * w1.z + s4.z * w2.z + s4.w * w3.z;
;       acc[r].w += s4.x * w0.w + s4.y * w1.w + s4.z * w2.w + s4.w * w3.w;
;     }
;   }
; #pragma unroll
;   for (int r = 0; r < 9; ++r) *(float4*)(red + (wave * 9 + r) * 256 + lane * 4) = acc[r];
;   __syncthreads();
;   float* mod = (float*)(P.ws + WS_MOD);
;   for (int o = tid; o < 2304; o += 512) {
;     int r = o >> 8, cc = o & 255;
;     float sacc = P.b_ada[l * NMOD + cch * 256 + cc];
; #pragma unroll
;     for (int w = 0; w < 8; ++w) sacc += red[(w * 9 + r) * 256 + cc];
;     mod[((size_t)l * 9 + r) * NMOD + cch * 256 + cc] = sacc;
	v_mov_b32_e32 v112, v133
	v_pk_mul_f32 v[106:107], v[196:197], v[130:131] op_sel:[0,1]
	v_pk_mul_f32 v[108:109], v[198:199], v[130:131] op_sel:[0,1]
	v_pk_fma_f32 v[106:107], v[192:193], v[130:131], v[106:107] op_sel_hi:[1,0,1]
	v_pk_fma_f32 v[108:109], v[194:195], v[130:131], v[108:109] op_sel_hi:[1,0,1]
	v_pk_fma_f32 v[106:107], v[200:201], v[132:133], v[106:107] op_sel_hi:[1,0,1]
	v_pk_fma_f32 v[108:109], v[202:203], v[132:133], v[108:109] op_sel_hi:[1,0,1]
	v_pk_fma_f32 v[106:107], v[204:205], v[112:113], v[106:107] op_sel_hi:[1,0,1]
	v_pk_fma_f32 v[108:109], v[206:207], v[112:113], v[108:109] op_sel_hi:[1,0,1]
	v_pk_add_f32 v[18:19], v[18:19], v[106:107]
	v_pk_add_f32 v[20:21], v[20:21], v[108:109]
	s_waitcnt lgkmcnt(3)
	v_mov_b32_e32 v112, v137
	v_pk_mul_f32 v[106:107], v[196:197], v[134:135] op_sel:[0,1]
	v_pk_mul_f32 v[108:109], v[198:199], v[134:135] op_sel:[0,1]
	v_pk_fma_f32 v[106:107], v[192:193], v[134:135], v[106:107] op_sel_hi:[1,0,1]
	v_pk_fma_f32 v[108:109], v[194:195], v[134:135], v[108:109] op_sel_hi:[1,0,1]
	v_pk_fma_f32 v[106:107], v[200:201], v[136:137], v[106:107] op_sel_hi:[1,0,1]
	v_pk_fma_f32 v[108:109], v[202:203], v[136:137], v[108:109] op_sel_hi:[1,0,1]
	v_pk_fma_f32 v[106:107], v[204:205], v[112:113], v[106:107] op_sel_hi:[1,0,1]
	v_pk_fma_f32 v[108:109], v[206:207], v[112:113], v[108:109] op_sel_hi:[1,0,1]
	v_pk_add_f32 v[14:15], v[14:15], v[106:107]
	v_pk_add_f32 v[16:17], v[16:17], v[108:109]
	s_waitcnt lgkmcnt(2)
	v_mov_b32_e32 v112, v141
	v_pk_mul_f32 v[106:107], v[196:197], v[138:139] op_sel:[0,1]
	v_pk_mul_f32 v[108:109], v[198:199], v[138:139] op_sel:[0,1]
	v_pk_fma_f32 v[106:107], v[192:193], v[138:139], v[106:107] op_sel_hi:[1,0,1]
	v_pk_fma_f32 v[108:109], v[194:195], v[138:139], v[108:109] op_sel_hi:[1,0,1]
	v_pk_fma_f32 v[106:107], v[200:201], v[140:141], v[106:107] op_sel_hi:[1,0,1]
	v_pk_fma_f32 v[108:109], v[202:203], v[140:141], v[108:109] op_sel_hi:[1,0,1]
	v_pk_fma_f32 v[106:107], v[204:205], v[112:113], v[106:107] op_sel_hi:[1,0,1]
	v_pk_fma_f32 v[108:109], v[206:207], v[112:113], v[108:109] op_sel_hi:[1,0,1]
	v_pk_add_f32 v[10:11], v[10:11], v[106:107]
	v_pk_add_f32 v[12:13], v[12:13], v[108:109]
	s_waitcnt lgkmcnt(1)
	v_mov_b32_e32 v112, v145
	v_pk_mul_f32 v[106:107], v[196:197], v[142:143] op_sel:[0,1]
	v_pk_mul_f32 v[108:109], v[198:199], v[142:143] op_sel:[0,1]
	v_pk_fma_f32 v[106:107], v[192:193], v[142:143], v[106:107] op_sel_hi:[1,0,1]
	v_pk_fma_f32 v[108:109], v[194:195], v[142:143], v[108:109] op_sel_hi:[1,0,1]
	v_pk_fma_f32 v[106:107], v[200:201], v[144:145], v[106:107] op_sel_hi:[1,0,1]
	v_pk_fma_f32 v[108:109], v[202:203], v[144:145], v[108:109] op_sel_hi:[1,0,1]
	v_pk_fma_f32 v[106:107], v[204:205], v[112:113], v[106:107] op_sel_hi:[1,0,1]
	v_pk_fma_f32 v[108:109], v[206:207], v[112:113], v[108:109] op_sel_hi:[1,0,1]
	v_pk_add_f32 v[6:7], v[6:7], v[106:107]
	v_pk_add_f32 v[8:9], v[8:9], v[108:109]
	s_waitcnt lgkmcnt(0)
	v_mov_b32_e32 v112, v149
	v_pk_mul_f32 v[106:107], v[196:197], v[146:147] op_sel:[0,1]
	v_pk_mul_f32 v[108:109], v[198:199], v[146:147] op_sel:[0,1]
	v_pk_fma_f32 v[106:107], v[192:193], v[146:147], v[106:107] op_sel_hi:[1,0,1]
	v_pk_fma_f32 v[108:109], v[194:195], v[146:147], v[108:109] op_sel_hi:[1,0,1]
	v_pk_fma_f32 v[106:107], v[200:201], v[148:149], v[106:107] op_sel_hi:[1,0,1]
	v_pk_fma_f32 v[108:109], v[202:203], v[148:149], v[108:109] op_sel_hi:[1,0,1]
	v_pk_fma_f32 v[106:107], v[204:205], v[112:113], v[106:107] op_sel_hi:[1,0,1]
	v_pk_fma_f32 v[108:109], v[206:207], v[112:113], v[108:109] op_sel_hi:[1,0,1]
	v_pk_add_f32 v[2:3], v[2:3], v[106:107]
	v_pk_add_f32 v[4:5], v[4:5], v[108:109]
	ds_write_b128 v105, v[22:25] offset:36864
	ds_write_b128 v105, v[34:37] offset:37888
	ds_write_b128 v105, v[30:33] offset:38912
	ds_write_b128 v105, v[26:29] offset:39936
	ds_write_b128 v105, v[18:21] offset:40960
	ds_write_b128 v105, v[14:17] offset:41984
	ds_write_b128 v105, v[10:13] offset:43008
	ds_write_b128 v105, v[6:9] offset:44032
	ds_write_b128 v105, v[2:5] offset:45056
	s_waitcnt lgkmcnt(0)
	s_barrier
	s_and_saveexec_b64 s[0:1], s[40:41]
	s_cbranch_execz .LBB0_1242
	s_mul_i32 s4, s2, 0xffffffdc
	s_add_i32 s4, s4, s12
	s_lshl_b32 s4, s4, 8
	s_add_i32 s6, s4, s3
	v_or_b32_sdwa v2, s6, v54 dst_sel:DWORD dst_unused:UNUSED_PAD src0_sel:DWORD src1_sel:BYTE_0
	s_ashr_i32 s5, s4, 31
	v_ashrrev_i32_e32 v3, 31, v2
	s_mul_hi_i32 s3, s2, 9
	s_mul_i32 s2, s2, 9
	v_lshl_add_u64 v[2:3], v[2:3], 2, s[82:83]
	v_lshl_add_u64 v[4:5], s[4:5], 2, v[56:57]
	s_mov_b64 s[4:5], 0
	v_mov_b32_e32 v0, v54

; #define LAS __attribute__((address_space(3)))
; __global__ void __launch_bounds__(512) mega(Params P0) {
;   extern __shared__ __attribute__((aligned(16))) unsigned char lds[];
;   cg::grid_group grid = cg::this_grid();
;   const int wv = __builtin_amdgcn_readfirstlane((int)(threadIdx.x >> 6));
;   volatile LAS unsigned* xb_st = (volatile LAS unsigned*)(lds + LDS_MAIN);
	.amdhsa_kernel _Z4mega6Params
		.amdhsa_group_segment_fixed_size 0
		.amdhsa_private_segment_fixed_size 0
		.amdhsa_kernarg_size 432
		.amdhsa_user_sgpr_count 2
		.amdhsa_user_sgpr_dispatch_ptr 0
		.amdhsa_user_sgpr_queue_ptr 0
		.amdhsa_user_sgpr_kernarg_segment_ptr 1
		.amdhsa_user_sgpr_dispatch_id 0
		.amdhsa_user_sgpr_kernarg_preload_length 0
		.amdhsa_user_sgpr_kernarg_preload_offset 0
		.amdhsa_user_sgpr_private_segment_size 0
		.amdhsa_uses_dynamic_stack 0
		.amdhsa_enable_private_segment 0
		.amdhsa_system_sgpr_workgroup_id_x 1
		.amdhsa_system_sgpr_workgroup_id_y 0
		.amdhsa_system_sgpr_workgroup_id_z 0
		.amdhsa_system_sgpr_workgroup_info 0
		.amdhsa_system_vgpr_workitem_id 2
		.amdhsa_next_free_vgpr 256
		.amdhsa_next_free_sgpr 102
		.amdhsa_accum_offset 256
		.amdhsa_reserve_vcc 1
		.amdhsa_float_round_mode_32 0
		.amdhsa_float_round_mode_16_64 0
		.amdhsa_float_denorm_mode_32 3
		.amdhsa_float_denorm_mode_16_64 3
		.amdhsa_dx10_clamp 1
		.amdhsa_ieee_mode 1
		.amdhsa_fp16_overflow 0
		.amdhsa_tg_split 0
		.amdhsa_exception_fp_ieee_invalid_op 0
		.amdhsa_exception_fp_denorm_src 0
		.amdhsa_exception_fp_ieee_div_zero 0
		.amdhsa_exception_fp_ieee_overflow 0
		.amdhsa_exception_fp_ieee_underflow 0
		.amdhsa_exception_fp_ieee_inexact 0
		.amdhsa_exception_int_div_zero 0
	.end_amdhsa_kernel

; #define LAS __attribute__((address_space(3)))
; __global__ void __launch_bounds__(512) mega(Params P0) {
;   extern __shared__ __attribute__((aligned(16))) unsigned char lds[];
;   cg::grid_group grid = cg::this_grid();
;   const int wv = __builtin_amdgcn_readfirstlane((int)(threadIdx.x >> 6));
;   volatile LAS unsigned* xb_st = (volatile LAS unsigned*)(lds + LDS_MAIN);
amdhsa.kernels:
  - .agpr_count:     0
    .args:
      - .offset:         0
        .size:           176
        .value_kind:     by_value
      - .offset:         176
        .size:           4
        .value_kind:     hidden_block_count_x
      - .offset:         180
        .size:           4
        .value_kind:     hidden_block_count_y
      - .offset:         184
        .size:           4
        .value_kind:     hidden_block_count_z
      - .offset:         188
        .size:           2
        .value_kind:     hidden_group_size_x
      - .offset:         190
        .size:           2
        .value_kind:     hidden_group_size_y
      - .offset:         192
        .size:           2
        .value_kind:     hidden_group_size_z
      - .offset:         194
        .size:           2
        .value_kind:     hidden_remainder_x
      - .offset:         196
        .size:           2
        .value_kind:     hidden_remainder_y
      - .offset:         198
        .size:           2
        .value_kind:     hidden_remainder_z
      - .offset:         216
        .size:           8
        .value_kind:     hidden_global_offset_x
      - .offset:         224
        .size:           8
        .value_kind:     hidden_global_offset_y
      - .offset:         232
        .size:           8
        .value_kind:     hidden_global_offset_z
      - .offset:         240
        .size:           2
        .value_kind:     hidden_grid_dims
      - .offset:         264
        .size:           8
        .value_kind:     hidden_multigrid_sync_arg
      - .offset:         296
        .size:           4
        .value_kind:     hidden_dynamic_lds_size
    .group_segment_fixed_size: 0
    .kernarg_segment_align: 8
    .kernarg_segment_size: 432
    .language:       OpenCL C
    .language_version:
      - 2
      - 0
    .max_flat_workgroup_size: 512
    .name:           _Z4mega6Params
    .private_segment_fixed_size: 0
    .sgpr_count:     108
    .sgpr_spill_count: 235
    .symbol:         _Z4mega6Params.kd
    .uniform_work_group_size: 1
    .uses_dynamic_stack: false
    .vgpr_count:     256
    .vgpr_spill_count: 0
    .wavefront_size: 64
